# sample-row units: conv-context loads merged (one 16B load per half, c0 via DPP from the t>=2 lanes) and issued one row group ahead; row-group-1 sample blocks out of line too
# speedup vs baseline: 1.0169x; 1.0047x over previous
; template <int N> __device__ __forceinline__ float dpp_ror(float v) { const int i = __builtin_bit_cast(int, v); return __builtin_bit_cast(float, __builtin_amdgcn_update_dpp(i, i, 0x120 + N, 0xF, 0xF, false)); }
;     __device__ __forceinline__ void operator()(const f32x4 (&acc)[2][2][4][2], const pg8::Unit& u, int wr, int wc, int fr, int fq, PG8_LAS unsigned char* xl) const {
;     ...
;                         const f32x4 cur = acc[ai][bj][m][n]; f32x4 p1, p2;
;                         if (!sample) { const f32x4 prv = (m == 0) ? hb[bj] : acc[ai][bj][m == 0 ? 0 : m - 1][n];
; #pragma unroll
;                             for (int j = 0; j < 4; ++j) { const float s1 = fr == 15 ? prv[j] : cur[j], s2 = fr >= 14 ? prv[j] : cur[j]; p1[j] = dpp_ror<1>(s1); p2[j] = dpp_ror<2>(s2); }
;                         } else { const int t = fr & 3, b = (row - MP) >> 2;
; #pragma unroll
;                             for (int j = 0; j < 4; ++j) { p1[j] = dpp_ror<1>(cur[j]); p2[j] = dpp_ror<2>(cur[j]); }
;                             const f32x4 c1 = *(const f32x4*)(ctx_s + (size_t)(b * 2 + 1) * FF2 + bj * FF + jc0 + 4 * n), c0 = *(const f32x4*)(ctx_s + (size_t)(b * 2) * FF2 + bj * FF + jc0 + 4 * n);
; #pragma unroll
;                             for (int j = 0; j < 4; ++j) { p2[j] = t == 0 ? c0[j] : (t == 1 ? c1[j] : p2[j]); p1[j] = t == 0 ? c1[j] : p1[j]; }
;                         }
.LBB0_557:
	s_or_b64 exec, exec, s[6:7]
	v_lshl_add_u32 v225, s42, 8, v212
	v_add_u32_e32 v164, 0xffffc000, v225
	v_ashrrev_i32_e32 v164, 1, v164
	v_and_b32_e32 v224, 0xffffffe6, v164
	s_mov_b64 s[6:7], -1
	s_and_b64 vcc, exec, s[34:35]
	s_cbranch_vccnz .Lsmp1_0_0
	s_waitcnt lgkmcnt(0)
	v_cndmask_b32_e64 v164, v156, v172, s[16:17]
	v_cndmask_b32_e64 v168, v156, v172, s[8:9]
	v_cndmask_b32_e64 v165, v157, v173, s[16:17]
	v_cndmask_b32_e64 v169, v157, v173, s[8:9]
	v_cndmask_b32_e64 v166, v158, v174, s[16:17]
	v_cndmask_b32_e64 v170, v158, v174, s[8:9]
	v_cndmask_b32_e64 v167, v159, v175, s[16:17]
	v_cndmask_b32_e64 v171, v159, v175, s[8:9]
	v_mov_b32_dpp v164, v164 row_ror:1 row_mask:0xf bank_mask:0xf
	v_mov_b32_dpp v168, v168 row_ror:2 row_mask:0xf bank_mask:0xf
	v_mov_b32_dpp v165, v165 row_ror:1 row_mask:0xf bank_mask:0xf
	v_mov_b32_dpp v169, v169 row_ror:2 row_mask:0xf bank_mask:0xf
	v_mov_b32_dpp v166, v166 row_ror:1 row_mask:0xf bank_mask:0xf
	v_mov_b32_dpp v170, v170 row_ror:2 row_mask:0xf bank_mask:0xf
	v_mov_b32_dpp v167, v167 row_ror:1 row_mask:0xf bank_mask:0xf
	v_mov_b32_dpp v171, v171 row_ror:2 row_mask:0xf bank_mask:0xf
.LBB0_561:
	s_waitcnt lgkmcnt(0)
	v_cndmask_b32_e64 v172, 0, 1, s[34:35]
	v_cmp_ne_u32_e64 s[22:23], 1, v172
	s_andn2_b64 vcc, exec, s[34:35]
	s_mov_b64 s[6:7], -1
	s_cbranch_vccz .Lsmp1_0_1
	v_cndmask_b32_e64 v172, v152, v160, s[16:17]
	v_cndmask_b32_e64 v176, v152, v160, s[8:9]
	v_cndmask_b32_e64 v173, v153, v161, s[16:17]
	v_cndmask_b32_e64 v177, v153, v161, s[8:9]
	v_cndmask_b32_e64 v174, v154, v162, s[16:17]
	v_cndmask_b32_e64 v178, v154, v162, s[8:9]
	v_cndmask_b32_e64 v175, v155, v163, s[16:17]
	v_cndmask_b32_e64 v179, v155, v163, s[8:9]
	v_mov_b32_dpp v172, v172 row_ror:1 row_mask:0xf bank_mask:0xf
	v_mov_b32_dpp v176, v176 row_ror:2 row_mask:0xf bank_mask:0xf
	v_mov_b32_dpp v173, v173 row_ror:1 row_mask:0xf bank_mask:0xf
	v_mov_b32_dpp v177, v177 row_ror:2 row_mask:0xf bank_mask:0xf
	v_mov_b32_dpp v174, v174 row_ror:1 row_mask:0xf bank_mask:0xf
	v_mov_b32_dpp v178, v178 row_ror:2 row_mask:0xf bank_mask:0xf
	v_mov_b32_dpp v175, v175 row_ror:1 row_mask:0xf bank_mask:0xf
	v_mov_b32_dpp v179, v179 row_ror:2 row_mask:0xf bank_mask:0xf

; template <int N> __device__ __forceinline__ float dpp_ror(float v) { const int i = __builtin_bit_cast(int, v); return __builtin_bit_cast(float, __builtin_amdgcn_update_dpp(i, i, 0x120 + N, 0xF, 0xF, false)); }
;     __device__ __forceinline__ void operator()(const f32x4 (&acc)[2][2][4][2], const pg8::Unit& u, int wr, int wc, int fr, int fq, PG8_LAS unsigned char* xl) const {
;     ...
;                         } else { const int t = fr & 3, b = (row - MP) >> 2;
; #pragma unroll
;                             for (int j = 0; j < 4; ++j) { p1[j] = dpp_ror<1>(cur[j]); p2[j] = dpp_ror<2>(cur[j]); }
;                             const f32x4 c1 = *(const f32x4*)(ctx_s + (size_t)(b * 2 + 1) * FF2 + bj * FF + jc0 + 4 * n), c0 = *(const f32x4*)(ctx_s + (size_t)(b * 2) * FF2 + bj * FF + jc0 + 4 * n);
; #pragma unroll
;                             for (int j = 0; j < 4; ++j) { p2[j] = t == 0 ? c0[j] : (t == 1 ? c1[j] : p2[j]); p1[j] = t == 0 ? c1[j] : p1[j]; }
;                         }
.Lsmp_0_0:
	v_mov_b32_e32 v168, v148
	v_mov_b32_e32 v169, v148
	v_mov_b32_e32 v170, v149
	v_mov_b32_e32 v171, v149
	v_mov_b32_e32 v228, v150
	v_mov_b32_e32 v230, v151
	v_mov_b32_e32 v227, v150
	v_mov_b32_e32 v229, v151
	v_mov_b32_dpp v168, v168 row_ror:1 row_mask:0xf bank_mask:0xf
	v_mov_b32_dpp v169, v169 row_ror:2 row_mask:0xf bank_mask:0xf
	v_mov_b32_dpp v170, v170 row_ror:1 row_mask:0xf bank_mask:0xf
	v_mov_b32_dpp v171, v171 row_ror:2 row_mask:0xf bank_mask:0xf
	v_mov_b32_dpp v228, v228 row_ror:2 row_mask:0xf bank_mask:0xf
	v_mov_b32_dpp v230, v230 row_ror:2 row_mask:0xf bank_mask:0xf
	v_mov_b32_dpp v227, v227 row_ror:1 row_mask:0xf bank_mask:0xf
	v_mov_b32_dpp v229, v229 row_ror:1 row_mask:0xf bank_mask:0xf
	s_waitcnt vmcnt(4)
	v_cndmask_b32_e64 v169, v169, v240, s[14:15]
	v_cndmask_b32_e64 v160, v168, v240, s[12:13]
	v_cndmask_b32_e64 v168, v171, v241, s[14:15]
	v_cndmask_b32_e64 v161, v170, v241, s[12:13]
	v_cndmask_b32_e64 v170, v228, v242, s[14:15]
	v_cndmask_b32_e64 v171, v230, v243, s[14:15]
	v_cndmask_b32_e64 v162, v227, v242, s[12:13]
	v_cndmask_b32_e64 v163, v229, v243, s[12:13]
	v_mov_b32_dpp v164, v240 row_ror:14 row_mask:0xf bank_mask:0xf
	v_mov_b32_dpp v165, v241 row_ror:14 row_mask:0xf bank_mask:0xf
	v_mov_b32_dpp v166, v242 row_ror:14 row_mask:0xf bank_mask:0xf
	v_mov_b32_dpp v167, v243 row_ror:14 row_mask:0xf bank_mask:0xf
	v_cndmask_b32_e64 v164, v169, v164, s[12:13]
	v_cndmask_b32_e64 v165, v168, v165, s[12:13]
	v_cndmask_b32_e64 v166, v170, v166, s[12:13]
	v_cndmask_b32_e64 v167, v171, v167, s[12:13]
	s_branch .LBB0_573
.Lsmp_0_1:
	v_mov_b32_e32 v227, v144
	v_mov_b32_e32 v228, v144
	v_mov_b32_e32 v229, v145
	v_mov_b32_e32 v230, v145
	v_mov_b32_e32 v232, v146
	v_mov_b32_e32 v234, v147
	v_mov_b32_e32 v231, v146
	v_mov_b32_e32 v233, v147
	v_mov_b32_dpp v227, v227 row_ror:1 row_mask:0xf bank_mask:0xf
	v_mov_b32_dpp v228, v228 row_ror:2 row_mask:0xf bank_mask:0xf
	v_mov_b32_dpp v229, v229 row_ror:1 row_mask:0xf bank_mask:0xf
	v_mov_b32_dpp v230, v230 row_ror:2 row_mask:0xf bank_mask:0xf
	v_mov_b32_dpp v232, v232 row_ror:2 row_mask:0xf bank_mask:0xf
	v_mov_b32_dpp v234, v234 row_ror:2 row_mask:0xf bank_mask:0xf
	v_mov_b32_dpp v231, v231 row_ror:1 row_mask:0xf bank_mask:0xf
	v_mov_b32_dpp v233, v233 row_ror:1 row_mask:0xf bank_mask:0xf
	s_waitcnt vmcnt(3)
	v_cndmask_b32_e64 v228, v228, v248, s[14:15]
	v_cndmask_b32_e64 v156, v227, v248, s[12:13]
	v_cndmask_b32_e64 v227, v230, v249, s[14:15]
	v_cndmask_b32_e64 v157, v229, v249, s[12:13]
	v_cndmask_b32_e64 v229, v232, v250, s[14:15]
	v_cndmask_b32_e64 v230, v234, v251, s[14:15]
	v_cndmask_b32_e64 v158, v231, v250, s[12:13]
	v_cndmask_b32_e64 v159, v233, v251, s[12:13]
	v_mov_b32_dpp v168, v248 row_ror:14 row_mask:0xf bank_mask:0xf
	v_mov_b32_dpp v169, v249 row_ror:14 row_mask:0xf bank_mask:0xf
	v_mov_b32_dpp v170, v250 row_ror:14 row_mask:0xf bank_mask:0xf
	v_mov_b32_dpp v171, v251 row_ror:14 row_mask:0xf bank_mask:0xf
	v_cndmask_b32_e64 v168, v228, v168, s[12:13]
	v_cndmask_b32_e64 v169, v227, v169, s[12:13]
	v_cndmask_b32_e64 v170, v229, v170, s[12:13]
	v_cndmask_b32_e64 v171, v230, v171, s[12:13]
	s_mul_i32 s100, s36, 16
	v_lshl_add_u64 v[240:241], v[252:253], 0, s[100:101]
	global_load_dwordx4 v[240:243], v[240:241], off
	v_lshl_add_u64 v[248:249], v[254:255], 0, s[100:101]
	global_load_dwordx4 v[248:251], v[248:249], off offset:3072
	s_branch .LBB0_577

; template <int N> __device__ __forceinline__ float dpp_ror(float v) { const int i = __builtin_bit_cast(int, v); return __builtin_bit_cast(float, __builtin_amdgcn_update_dpp(i, i, 0x120 + N, 0xF, 0xF, false)); }
;     __device__ __forceinline__ void operator()(const f32x4 (&acc)[2][2][4][2], const pg8::Unit& u, int wr, int wc, int fr, int fq, PG8_LAS unsigned char* xl) const {
;     ...
;                         } else { const int t = fr & 3, b = (row - MP) >> 2;
; #pragma unroll
;                             for (int j = 0; j < 4; ++j) { p1[j] = dpp_ror<1>(cur[j]); p2[j] = dpp_ror<2>(cur[j]); }
;                             const f32x4 c1 = *(const f32x4*)(ctx_s + (size_t)(b * 2 + 1) * FF2 + bj * FF + jc0 + 4 * n), c0 = *(const f32x4*)(ctx_s + (size_t)(b * 2) * FF2 + bj * FF + jc0 + 4 * n);
; #pragma unroll
;                             for (int j = 0; j < 4; ++j) { p2[j] = t == 0 ? c0[j] : (t == 1 ? c1[j] : p2[j]); p1[j] = t == 0 ? c1[j] : p1[j]; }
;                         }
.Lsmp_0_2:
	v_mov_b32_e32 v160, v140
	v_mov_b32_e32 v161, v140
	v_mov_b32_e32 v162, v141
	v_mov_b32_e32 v163, v141
	v_mov_b32_e32 v227, v142
	v_mov_b32_e32 v229, v143
	v_mov_b32_e32 v226, v142
	v_mov_b32_e32 v228, v143
	v_mov_b32_dpp v160, v160 row_ror:1 row_mask:0xf bank_mask:0xf
	v_mov_b32_dpp v161, v161 row_ror:2 row_mask:0xf bank_mask:0xf
	v_mov_b32_dpp v162, v162 row_ror:1 row_mask:0xf bank_mask:0xf
	v_mov_b32_dpp v163, v163 row_ror:2 row_mask:0xf bank_mask:0xf
	v_mov_b32_dpp v227, v227 row_ror:2 row_mask:0xf bank_mask:0xf
	v_mov_b32_dpp v229, v229 row_ror:2 row_mask:0xf bank_mask:0xf
	v_mov_b32_dpp v226, v226 row_ror:1 row_mask:0xf bank_mask:0xf
	v_mov_b32_dpp v228, v228 row_ror:1 row_mask:0xf bank_mask:0xf
	s_waitcnt vmcnt(4)
	v_cndmask_b32_e64 v161, v161, v240, s[14:15]
	v_cndmask_b32_e64 v152, v160, v240, s[12:13]
	v_cndmask_b32_e64 v160, v163, v241, s[14:15]
	v_cndmask_b32_e64 v153, v162, v241, s[12:13]
	v_cndmask_b32_e64 v162, v227, v242, s[14:15]
	v_cndmask_b32_e64 v163, v229, v243, s[14:15]
	v_cndmask_b32_e64 v154, v226, v242, s[12:13]
	v_cndmask_b32_e64 v155, v228, v243, s[12:13]
	v_mov_b32_dpp v156, v240 row_ror:14 row_mask:0xf bank_mask:0xf
	v_mov_b32_dpp v157, v241 row_ror:14 row_mask:0xf bank_mask:0xf
	v_mov_b32_dpp v158, v242 row_ror:14 row_mask:0xf bank_mask:0xf
	v_mov_b32_dpp v159, v243 row_ror:14 row_mask:0xf bank_mask:0xf
	v_cndmask_b32_e64 v156, v161, v156, s[12:13]
	v_cndmask_b32_e64 v157, v160, v157, s[12:13]
	v_cndmask_b32_e64 v158, v162, v158, s[12:13]
	v_cndmask_b32_e64 v159, v163, v159, s[12:13]
	s_branch .LBB0_583
.Lsmp_0_3:
	v_mov_b32_e32 v226, v136
	v_mov_b32_e32 v227, v136
	v_mov_b32_e32 v228, v137
	v_mov_b32_e32 v229, v137
	v_mov_b32_e32 v231, v138
	v_mov_b32_e32 v233, v139
	v_mov_b32_e32 v230, v138
	v_mov_b32_e32 v232, v139
	v_mov_b32_dpp v226, v226 row_ror:1 row_mask:0xf bank_mask:0xf
	v_mov_b32_dpp v227, v227 row_ror:2 row_mask:0xf bank_mask:0xf
	v_mov_b32_dpp v228, v228 row_ror:1 row_mask:0xf bank_mask:0xf
	v_mov_b32_dpp v229, v229 row_ror:2 row_mask:0xf bank_mask:0xf
	v_mov_b32_dpp v231, v231 row_ror:2 row_mask:0xf bank_mask:0xf
	v_mov_b32_dpp v233, v233 row_ror:2 row_mask:0xf bank_mask:0xf
	v_mov_b32_dpp v230, v230 row_ror:1 row_mask:0xf bank_mask:0xf
	v_mov_b32_dpp v232, v232 row_ror:1 row_mask:0xf bank_mask:0xf
	s_waitcnt vmcnt(3)
	v_cndmask_b32_e64 v227, v227, v248, s[14:15]
	v_cndmask_b32_e64 v148, v226, v248, s[12:13]
	v_cndmask_b32_e64 v226, v229, v249, s[14:15]
	v_cndmask_b32_e64 v149, v228, v249, s[12:13]
	v_cndmask_b32_e64 v228, v231, v250, s[14:15]
	v_cndmask_b32_e64 v229, v233, v251, s[14:15]
	v_cndmask_b32_e64 v150, v230, v250, s[12:13]
	v_cndmask_b32_e64 v151, v232, v251, s[12:13]
	v_mov_b32_dpp v160, v248 row_ror:14 row_mask:0xf bank_mask:0xf
	v_mov_b32_dpp v161, v249 row_ror:14 row_mask:0xf bank_mask:0xf
	v_mov_b32_dpp v162, v250 row_ror:14 row_mask:0xf bank_mask:0xf
	v_mov_b32_dpp v163, v251 row_ror:14 row_mask:0xf bank_mask:0xf
	v_cndmask_b32_e64 v160, v227, v160, s[12:13]
	v_cndmask_b32_e64 v161, v226, v161, s[12:13]
	v_cndmask_b32_e64 v162, v228, v162, s[12:13]
	v_cndmask_b32_e64 v163, v229, v163, s[12:13]
	s_mul_i32 s100, s36, 24
	v_lshl_add_u64 v[240:241], v[252:253], 0, s[100:101]
	global_load_dwordx4 v[240:243], v[240:241], off
	v_lshl_add_u64 v[248:249], v[254:255], 0, s[100:101]
	global_load_dwordx4 v[248:251], v[248:249], off offset:3072
	s_branch .LBB0_587

; template <int N> __device__ __forceinline__ float dpp_ror(float v) { const int i = __builtin_bit_cast(int, v); return __builtin_bit_cast(float, __builtin_amdgcn_update_dpp(i, i, 0x120 + N, 0xF, 0xF, false)); }
;     __device__ __forceinline__ void operator()(const f32x4 (&acc)[2][2][4][2], const pg8::Unit& u, int wr, int wc, int fr, int fq, PG8_LAS unsigned char* xl) const {
;     ...
;                         } else { const int t = fr & 3, b = (row - MP) >> 2;
; #pragma unroll
;                             for (int j = 0; j < 4; ++j) { p1[j] = dpp_ror<1>(cur[j]); p2[j] = dpp_ror<2>(cur[j]); }
;                             const f32x4 c1 = *(const f32x4*)(ctx_s + (size_t)(b * 2 + 1) * FF2 + bj * FF + jc0 + 4 * n), c0 = *(const f32x4*)(ctx_s + (size_t)(b * 2) * FF2 + bj * FF + jc0 + 4 * n);
; #pragma unroll
;                             for (int j = 0; j < 4; ++j) { p2[j] = t == 0 ? c0[j] : (t == 1 ? c1[j] : p2[j]); p1[j] = t == 0 ? c1[j] : p1[j]; }
;                         }
.Lsmp_0_4:
	v_mov_b32_e32 v152, v132
	v_mov_b32_e32 v153, v132
	v_mov_b32_e32 v154, v133
	v_mov_b32_e32 v155, v133
	v_mov_b32_e32 v226, v134
	v_mov_b32_e32 v228, v135
	v_mov_b32_e32 v171, v134
	v_mov_b32_e32 v227, v135
	v_mov_b32_dpp v152, v152 row_ror:1 row_mask:0xf bank_mask:0xf
	v_mov_b32_dpp v153, v153 row_ror:2 row_mask:0xf bank_mask:0xf
	v_mov_b32_dpp v154, v154 row_ror:1 row_mask:0xf bank_mask:0xf
	v_mov_b32_dpp v155, v155 row_ror:2 row_mask:0xf bank_mask:0xf
	v_mov_b32_dpp v226, v226 row_ror:2 row_mask:0xf bank_mask:0xf
	v_mov_b32_dpp v228, v228 row_ror:2 row_mask:0xf bank_mask:0xf
	v_mov_b32_dpp v171, v171 row_ror:1 row_mask:0xf bank_mask:0xf
	v_mov_b32_dpp v227, v227 row_ror:1 row_mask:0xf bank_mask:0xf
	s_waitcnt vmcnt(4)
	v_cndmask_b32_e64 v153, v153, v240, s[14:15]
	v_cndmask_b32_e64 v144, v152, v240, s[12:13]
	v_cndmask_b32_e64 v152, v155, v241, s[14:15]
	v_cndmask_b32_e64 v145, v154, v241, s[12:13]
	v_cndmask_b32_e64 v154, v226, v242, s[14:15]
	v_cndmask_b32_e64 v155, v228, v243, s[14:15]
	v_cndmask_b32_e64 v146, v171, v242, s[12:13]
	v_cndmask_b32_e64 v147, v227, v243, s[12:13]
	v_mov_b32_dpp v148, v240 row_ror:14 row_mask:0xf bank_mask:0xf
	v_mov_b32_dpp v149, v241 row_ror:14 row_mask:0xf bank_mask:0xf
	v_mov_b32_dpp v150, v242 row_ror:14 row_mask:0xf bank_mask:0xf
	v_mov_b32_dpp v151, v243 row_ror:14 row_mask:0xf bank_mask:0xf
	v_cndmask_b32_e64 v148, v153, v148, s[12:13]
	v_cndmask_b32_e64 v149, v152, v149, s[12:13]
	v_cndmask_b32_e64 v150, v154, v150, s[12:13]
	v_cndmask_b32_e64 v151, v155, v151, s[12:13]
	s_branch .LBB0_593
.Lsmp_0_5:
	v_mov_b32_e32 v171, v128
	v_mov_b32_e32 v226, v128
	v_mov_b32_e32 v227, v129
	v_mov_b32_e32 v228, v129
	v_mov_b32_e32 v230, v130
	v_mov_b32_e32 v232, v131
	v_mov_b32_e32 v229, v130
	v_mov_b32_e32 v231, v131
	v_mov_b32_dpp v171, v171 row_ror:1 row_mask:0xf bank_mask:0xf
	v_mov_b32_dpp v226, v226 row_ror:2 row_mask:0xf bank_mask:0xf
	v_mov_b32_dpp v227, v227 row_ror:1 row_mask:0xf bank_mask:0xf
	v_mov_b32_dpp v228, v228 row_ror:2 row_mask:0xf bank_mask:0xf
	v_mov_b32_dpp v230, v230 row_ror:2 row_mask:0xf bank_mask:0xf
	v_mov_b32_dpp v232, v232 row_ror:2 row_mask:0xf bank_mask:0xf
	v_mov_b32_dpp v229, v229 row_ror:1 row_mask:0xf bank_mask:0xf
	v_mov_b32_dpp v231, v231 row_ror:1 row_mask:0xf bank_mask:0xf
	s_waitcnt vmcnt(3)
	v_cndmask_b32_e64 v226, v226, v248, s[14:15]
	v_cndmask_b32_e64 v140, v171, v248, s[12:13]
	v_cndmask_b32_e64 v171, v228, v249, s[14:15]
	v_cndmask_b32_e64 v141, v227, v249, s[12:13]
	v_cndmask_b32_e64 v227, v230, v250, s[14:15]
	v_cndmask_b32_e64 v228, v232, v251, s[14:15]
	v_cndmask_b32_e64 v142, v229, v250, s[12:13]
	v_cndmask_b32_e64 v143, v231, v251, s[12:13]
	v_mov_b32_dpp v152, v248 row_ror:14 row_mask:0xf bank_mask:0xf
	v_mov_b32_dpp v153, v249 row_ror:14 row_mask:0xf bank_mask:0xf
	v_mov_b32_dpp v154, v250 row_ror:14 row_mask:0xf bank_mask:0xf
	v_mov_b32_dpp v155, v251 row_ror:14 row_mask:0xf bank_mask:0xf
	v_cndmask_b32_e64 v152, v226, v152, s[12:13]
	v_cndmask_b32_e64 v153, v171, v153, s[12:13]
	v_cndmask_b32_e64 v154, v227, v154, s[12:13]
	v_cndmask_b32_e64 v155, v228, v155, s[12:13]
	s_mul_i32 s100, s36, 64
	v_lshl_add_u64 v[240:241], v[252:253], 0, s[100:101]
	global_load_dwordx4 v[240:243], v[240:241], off
	v_lshl_add_u64 v[248:249], v[254:255], 0, s[100:101]
	global_load_dwordx4 v[248:251], v[248:249], off offset:3072
	s_branch .LBB0_597

; template <int N> __device__ __forceinline__ float dpp_ror(float v) { const int i = __builtin_bit_cast(int, v); return __builtin_bit_cast(float, __builtin_amdgcn_update_dpp(i, i, 0x120 + N, 0xF, 0xF, false)); }
;     __device__ __forceinline__ void operator()(const f32x4 (&acc)[2][2][4][2], const pg8::Unit& u, int wr, int wc, int fr, int fq, PG8_LAS unsigned char* xl) const {
;     ...
;                         } else { const int t = fr & 3, b = (row - MP) >> 2;
; #pragma unroll
;                             for (int j = 0; j < 4; ++j) { p1[j] = dpp_ror<1>(cur[j]); p2[j] = dpp_ror<2>(cur[j]); }
;                             const f32x4 c1 = *(const f32x4*)(ctx_s + (size_t)(b * 2 + 1) * FF2 + bj * FF + jc0 + 4 * n), c0 = *(const f32x4*)(ctx_s + (size_t)(b * 2) * FF2 + bj * FF + jc0 + 4 * n);
; #pragma unroll
;                             for (int j = 0; j < 4; ++j) { p2[j] = t == 0 ? c0[j] : (t == 1 ? c1[j] : p2[j]); p1[j] = t == 0 ? c1[j] : p1[j]; }
;                         }
.Lsmp_0_6:
	v_mov_b32_e32 v144, v124
	v_mov_b32_e32 v145, v124
	v_mov_b32_e32 v146, v125
	v_mov_b32_e32 v147, v125
	v_mov_b32_e32 v171, v126
	v_mov_b32_e32 v227, v127
	v_mov_b32_e32 v163, v126
	v_mov_b32_e32 v226, v127
	v_mov_b32_dpp v144, v144 row_ror:1 row_mask:0xf bank_mask:0xf
	v_mov_b32_dpp v145, v145 row_ror:2 row_mask:0xf bank_mask:0xf
	v_mov_b32_dpp v146, v146 row_ror:1 row_mask:0xf bank_mask:0xf
	v_mov_b32_dpp v147, v147 row_ror:2 row_mask:0xf bank_mask:0xf
	v_mov_b32_dpp v171, v171 row_ror:2 row_mask:0xf bank_mask:0xf
	v_mov_b32_dpp v227, v227 row_ror:2 row_mask:0xf bank_mask:0xf
	v_mov_b32_dpp v163, v163 row_ror:1 row_mask:0xf bank_mask:0xf
	v_mov_b32_dpp v226, v226 row_ror:1 row_mask:0xf bank_mask:0xf
	s_waitcnt vmcnt(4)
	v_cndmask_b32_e64 v145, v145, v240, s[14:15]
	v_cndmask_b32_e64 v132, v144, v240, s[12:13]
	v_cndmask_b32_e64 v144, v147, v241, s[14:15]
	v_cndmask_b32_e64 v133, v146, v241, s[12:13]
	v_cndmask_b32_e64 v146, v171, v242, s[14:15]
	v_cndmask_b32_e64 v147, v227, v243, s[14:15]
	v_cndmask_b32_e64 v134, v163, v242, s[12:13]
	v_cndmask_b32_e64 v135, v226, v243, s[12:13]
	v_mov_b32_dpp v136, v240 row_ror:14 row_mask:0xf bank_mask:0xf
	v_mov_b32_dpp v137, v241 row_ror:14 row_mask:0xf bank_mask:0xf
	v_mov_b32_dpp v138, v242 row_ror:14 row_mask:0xf bank_mask:0xf
	v_mov_b32_dpp v139, v243 row_ror:14 row_mask:0xf bank_mask:0xf
	v_cndmask_b32_e64 v136, v145, v136, s[12:13]
	v_cndmask_b32_e64 v137, v144, v137, s[12:13]
	v_cndmask_b32_e64 v138, v146, v138, s[12:13]
	v_cndmask_b32_e64 v139, v147, v139, s[12:13]
	s_branch .LBB0_605
.Lsmp_0_7:
	s_waitcnt lgkmcnt(1)
	v_mov_b32_e32 v163, v88
	v_mov_b32_e32 v171, v88
	v_mov_b32_e32 v226, v89
	v_mov_b32_e32 v227, v89
	v_mov_b32_e32 v229, v90
	v_mov_b32_e32 v231, v91
	v_mov_b32_e32 v228, v90
	v_mov_b32_e32 v230, v91
	v_mov_b32_dpp v163, v163 row_ror:1 row_mask:0xf bank_mask:0xf
	v_mov_b32_dpp v171, v171 row_ror:2 row_mask:0xf bank_mask:0xf
	v_mov_b32_dpp v226, v226 row_ror:1 row_mask:0xf bank_mask:0xf
	v_mov_b32_dpp v227, v227 row_ror:2 row_mask:0xf bank_mask:0xf
	v_mov_b32_dpp v229, v229 row_ror:2 row_mask:0xf bank_mask:0xf
	v_mov_b32_dpp v231, v231 row_ror:2 row_mask:0xf bank_mask:0xf
	v_mov_b32_dpp v228, v228 row_ror:1 row_mask:0xf bank_mask:0xf
	v_mov_b32_dpp v230, v230 row_ror:1 row_mask:0xf bank_mask:0xf
	s_waitcnt vmcnt(3)
	v_cndmask_b32_e64 v171, v171, v248, s[14:15]
	v_cndmask_b32_e64 v140, v163, v248, s[12:13]
	v_cndmask_b32_e64 v163, v227, v249, s[14:15]
	v_cndmask_b32_e64 v141, v226, v249, s[12:13]
	v_cndmask_b32_e64 v226, v229, v250, s[14:15]
	v_cndmask_b32_e64 v227, v231, v251, s[14:15]
	v_cndmask_b32_e64 v142, v228, v250, s[12:13]
	v_cndmask_b32_e64 v143, v230, v251, s[12:13]
	v_mov_b32_dpp v144, v248 row_ror:14 row_mask:0xf bank_mask:0xf
	v_mov_b32_dpp v145, v249 row_ror:14 row_mask:0xf bank_mask:0xf
	v_mov_b32_dpp v146, v250 row_ror:14 row_mask:0xf bank_mask:0xf
	v_mov_b32_dpp v147, v251 row_ror:14 row_mask:0xf bank_mask:0xf
	v_cndmask_b32_e64 v144, v171, v144, s[12:13]
	v_cndmask_b32_e64 v145, v163, v145, s[12:13]
	v_cndmask_b32_e64 v146, v226, v146, s[12:13]
	v_cndmask_b32_e64 v147, v227, v147, s[12:13]
	s_mul_i32 s100, s36, 72
	v_lshl_add_u64 v[240:241], v[252:253], 0, s[100:101]
	global_load_dwordx4 v[240:243], v[240:241], off
	v_lshl_add_u64 v[248:249], v[254:255], 0, s[100:101]
	global_load_dwordx4 v[248:251], v[248:249], off offset:3072
	s_branch .LBB0_609

; template <int N> __device__ __forceinline__ float dpp_ror(float v) { const int i = __builtin_bit_cast(int, v); return __builtin_bit_cast(float, __builtin_amdgcn_update_dpp(i, i, 0x120 + N, 0xF, 0xF, false)); }
;     __device__ __forceinline__ void operator()(const f32x4 (&acc)[2][2][4][2], const pg8::Unit& u, int wr, int wc, int fr, int fq, PG8_LAS unsigned char* xl) const {
;     ...
;                         } else { const int t = fr & 3, b = (row - MP) >> 2;
; #pragma unroll
;                             for (int j = 0; j < 4; ++j) { p1[j] = dpp_ror<1>(cur[j]); p2[j] = dpp_ror<2>(cur[j]); }
;                             const f32x4 c1 = *(const f32x4*)(ctx_s + (size_t)(b * 2 + 1) * FF2 + bj * FF + jc0 + 4 * n), c0 = *(const f32x4*)(ctx_s + (size_t)(b * 2) * FF2 + bj * FF + jc0 + 4 * n);
; #pragma unroll
;                             for (int j = 0; j < 4; ++j) { p2[j] = t == 0 ? c0[j] : (t == 1 ? c1[j] : p2[j]); p1[j] = t == 0 ? c1[j] : p1[j]; }
;                         }
.Lsmp_0_8:
	v_mov_b32_e32 v136, v84
	v_mov_b32_e32 v137, v84
	v_mov_b32_e32 v138, v85
	v_mov_b32_e32 v139, v85
	v_mov_b32_e32 v163, v86
	v_mov_b32_e32 v226, v87
	v_mov_b32_e32 v155, v86
	v_mov_b32_e32 v171, v87
	v_mov_b32_dpp v136, v136 row_ror:1 row_mask:0xf bank_mask:0xf
	v_mov_b32_dpp v137, v137 row_ror:2 row_mask:0xf bank_mask:0xf
	v_mov_b32_dpp v138, v138 row_ror:1 row_mask:0xf bank_mask:0xf
	v_mov_b32_dpp v139, v139 row_ror:2 row_mask:0xf bank_mask:0xf
	v_mov_b32_dpp v163, v163 row_ror:2 row_mask:0xf bank_mask:0xf
	v_mov_b32_dpp v226, v226 row_ror:2 row_mask:0xf bank_mask:0xf
	v_mov_b32_dpp v155, v155 row_ror:1 row_mask:0xf bank_mask:0xf
	v_mov_b32_dpp v171, v171 row_ror:1 row_mask:0xf bank_mask:0xf
	s_waitcnt vmcnt(4)
	v_cndmask_b32_e64 v137, v137, v240, s[14:15]
	v_cndmask_b32_e64 v128, v136, v240, s[12:13]
	v_cndmask_b32_e64 v136, v139, v241, s[14:15]
	v_cndmask_b32_e64 v129, v138, v241, s[12:13]
	v_cndmask_b32_e64 v138, v163, v242, s[14:15]
	v_cndmask_b32_e64 v139, v226, v243, s[14:15]
	v_cndmask_b32_e64 v130, v155, v242, s[12:13]
	v_cndmask_b32_e64 v131, v171, v243, s[12:13]
	v_mov_b32_dpp v132, v240 row_ror:14 row_mask:0xf bank_mask:0xf
	v_mov_b32_dpp v133, v241 row_ror:14 row_mask:0xf bank_mask:0xf
	v_mov_b32_dpp v134, v242 row_ror:14 row_mask:0xf bank_mask:0xf
	v_mov_b32_dpp v135, v243 row_ror:14 row_mask:0xf bank_mask:0xf
	v_cndmask_b32_e64 v132, v137, v132, s[12:13]
	v_cndmask_b32_e64 v133, v136, v133, s[12:13]
	v_cndmask_b32_e64 v134, v138, v134, s[12:13]
	v_cndmask_b32_e64 v135, v139, v135, s[12:13]
	s_branch .LBB0_615
.Lsmp_0_9:
	v_mov_b32_e32 v155, v80
	v_mov_b32_e32 v163, v80
	v_mov_b32_e32 v171, v81
	v_mov_b32_e32 v226, v81
	v_mov_b32_e32 v228, v82
	v_mov_b32_e32 v230, v83
	v_mov_b32_e32 v227, v82
	v_mov_b32_e32 v229, v83
	v_mov_b32_dpp v155, v155 row_ror:1 row_mask:0xf bank_mask:0xf
	v_mov_b32_dpp v163, v163 row_ror:2 row_mask:0xf bank_mask:0xf
	v_mov_b32_dpp v171, v171 row_ror:1 row_mask:0xf bank_mask:0xf
	v_mov_b32_dpp v226, v226 row_ror:2 row_mask:0xf bank_mask:0xf
	v_mov_b32_dpp v228, v228 row_ror:2 row_mask:0xf bank_mask:0xf
	v_mov_b32_dpp v230, v230 row_ror:2 row_mask:0xf bank_mask:0xf
	v_mov_b32_dpp v227, v227 row_ror:1 row_mask:0xf bank_mask:0xf
	v_mov_b32_dpp v229, v229 row_ror:1 row_mask:0xf bank_mask:0xf
	s_waitcnt vmcnt(3)
	v_cndmask_b32_e64 v163, v163, v248, s[14:15]
	v_cndmask_b32_e64 v124, v155, v248, s[12:13]
	v_cndmask_b32_e64 v155, v226, v249, s[14:15]
	v_cndmask_b32_e64 v125, v171, v249, s[12:13]
	v_cndmask_b32_e64 v171, v228, v250, s[14:15]
	v_cndmask_b32_e64 v226, v230, v251, s[14:15]
	v_cndmask_b32_e64 v126, v227, v250, s[12:13]
	v_cndmask_b32_e64 v127, v229, v251, s[12:13]
	v_mov_b32_dpp v136, v248 row_ror:14 row_mask:0xf bank_mask:0xf
	v_mov_b32_dpp v137, v249 row_ror:14 row_mask:0xf bank_mask:0xf
	v_mov_b32_dpp v138, v250 row_ror:14 row_mask:0xf bank_mask:0xf
	v_mov_b32_dpp v139, v251 row_ror:14 row_mask:0xf bank_mask:0xf
	v_cndmask_b32_e64 v136, v163, v136, s[12:13]
	v_cndmask_b32_e64 v137, v155, v137, s[12:13]
	v_cndmask_b32_e64 v138, v171, v138, s[12:13]
	v_cndmask_b32_e64 v139, v226, v139, s[12:13]
	s_mul_i32 s100, s36, 80
	v_lshl_add_u64 v[240:241], v[252:253], 0, s[100:101]
	global_load_dwordx4 v[240:243], v[240:241], off
	v_lshl_add_u64 v[248:249], v[254:255], 0, s[100:101]
	global_load_dwordx4 v[248:251], v[248:249], off offset:3072
	s_branch .LBB0_619

; template <int N> __device__ __forceinline__ float dpp_ror(float v) { const int i = __builtin_bit_cast(int, v); return __builtin_bit_cast(float, __builtin_amdgcn_update_dpp(i, i, 0x120 + N, 0xF, 0xF, false)); }
;     __device__ __forceinline__ void operator()(const f32x4 (&acc)[2][2][4][2], const pg8::Unit& u, int wr, int wc, int fr, int fq, PG8_LAS unsigned char* xl) const {
;     ...
;                         } else { const int t = fr & 3, b = (row - MP) >> 2;
; #pragma unroll
;                             for (int j = 0; j < 4; ++j) { p1[j] = dpp_ror<1>(cur[j]); p2[j] = dpp_ror<2>(cur[j]); }
;                             const f32x4 c1 = *(const f32x4*)(ctx_s + (size_t)(b * 2 + 1) * FF2 + bj * FF + jc0 + 4 * n), c0 = *(const f32x4*)(ctx_s + (size_t)(b * 2) * FF2 + bj * FF + jc0 + 4 * n);
; #pragma unroll
;                             for (int j = 0; j < 4; ++j) { p2[j] = t == 0 ? c0[j] : (t == 1 ? c1[j] : p2[j]); p1[j] = t == 0 ? c1[j] : p1[j]; }
;                         }
.Lsmp_0_10:
	v_mov_b32_e32 v128, v76
	v_mov_b32_e32 v129, v76
	v_mov_b32_e32 v130, v77
	v_mov_b32_e32 v131, v77
	v_mov_b32_e32 v155, v78
	v_mov_b32_e32 v171, v79
	v_mov_b32_e32 v147, v78
	v_mov_b32_e32 v163, v79
	v_mov_b32_dpp v128, v128 row_ror:1 row_mask:0xf bank_mask:0xf
	v_mov_b32_dpp v129, v129 row_ror:2 row_mask:0xf bank_mask:0xf
	v_mov_b32_dpp v130, v130 row_ror:1 row_mask:0xf bank_mask:0xf
	v_mov_b32_dpp v131, v131 row_ror:2 row_mask:0xf bank_mask:0xf
	v_mov_b32_dpp v155, v155 row_ror:2 row_mask:0xf bank_mask:0xf
	v_mov_b32_dpp v171, v171 row_ror:2 row_mask:0xf bank_mask:0xf
	v_mov_b32_dpp v147, v147 row_ror:1 row_mask:0xf bank_mask:0xf
	v_mov_b32_dpp v163, v163 row_ror:1 row_mask:0xf bank_mask:0xf
	s_waitcnt vmcnt(4)
	v_cndmask_b32_e64 v129, v129, v240, s[14:15]
	v_cndmask_b32_e64 v88, v128, v240, s[12:13]
	v_cndmask_b32_e64 v128, v131, v241, s[14:15]
	v_cndmask_b32_e64 v89, v130, v241, s[12:13]
	v_cndmask_b32_e64 v130, v155, v242, s[14:15]
	v_cndmask_b32_e64 v131, v171, v243, s[14:15]
	v_cndmask_b32_e64 v90, v147, v242, s[12:13]
	v_cndmask_b32_e64 v91, v163, v243, s[12:13]
	v_mov_b32_dpp v124, v240 row_ror:14 row_mask:0xf bank_mask:0xf
	v_mov_b32_dpp v125, v241 row_ror:14 row_mask:0xf bank_mask:0xf
	v_mov_b32_dpp v126, v242 row_ror:14 row_mask:0xf bank_mask:0xf
	v_mov_b32_dpp v127, v243 row_ror:14 row_mask:0xf bank_mask:0xf
	v_cndmask_b32_e64 v124, v129, v124, s[12:13]
	v_cndmask_b32_e64 v125, v128, v125, s[12:13]
	v_cndmask_b32_e64 v126, v130, v126, s[12:13]
	v_cndmask_b32_e64 v127, v131, v127, s[12:13]
	s_branch .LBB0_625
.Lsmp_0_11:
	v_mov_b32_e32 v147, v72
	v_mov_b32_e32 v155, v72
	v_mov_b32_e32 v163, v73
	v_mov_b32_e32 v171, v73
	v_mov_b32_e32 v227, v74
	v_mov_b32_e32 v229, v75
	v_mov_b32_e32 v226, v74
	v_mov_b32_e32 v228, v75
	v_mov_b32_dpp v147, v147 row_ror:1 row_mask:0xf bank_mask:0xf
	v_mov_b32_dpp v155, v155 row_ror:2 row_mask:0xf bank_mask:0xf
	v_mov_b32_dpp v163, v163 row_ror:1 row_mask:0xf bank_mask:0xf
	v_mov_b32_dpp v171, v171 row_ror:2 row_mask:0xf bank_mask:0xf
	v_mov_b32_dpp v227, v227 row_ror:2 row_mask:0xf bank_mask:0xf
	v_mov_b32_dpp v229, v229 row_ror:2 row_mask:0xf bank_mask:0xf
	v_mov_b32_dpp v226, v226 row_ror:1 row_mask:0xf bank_mask:0xf
	v_mov_b32_dpp v228, v228 row_ror:1 row_mask:0xf bank_mask:0xf
	s_waitcnt vmcnt(3)
	v_cndmask_b32_e64 v155, v155, v248, s[14:15]
	v_cndmask_b32_e64 v84, v147, v248, s[12:13]
	v_cndmask_b32_e64 v147, v171, v249, s[14:15]
	v_cndmask_b32_e64 v85, v163, v249, s[12:13]
	v_cndmask_b32_e64 v163, v227, v250, s[14:15]
	v_cndmask_b32_e64 v171, v229, v251, s[14:15]
	v_cndmask_b32_e64 v86, v226, v250, s[12:13]
	v_cndmask_b32_e64 v87, v228, v251, s[12:13]
	v_mov_b32_dpp v128, v248 row_ror:14 row_mask:0xf bank_mask:0xf
	v_mov_b32_dpp v129, v249 row_ror:14 row_mask:0xf bank_mask:0xf
	v_mov_b32_dpp v130, v250 row_ror:14 row_mask:0xf bank_mask:0xf
	v_mov_b32_dpp v131, v251 row_ror:14 row_mask:0xf bank_mask:0xf
	v_cndmask_b32_e64 v128, v155, v128, s[12:13]
	v_cndmask_b32_e64 v129, v147, v129, s[12:13]
	v_cndmask_b32_e64 v130, v163, v130, s[12:13]
	v_cndmask_b32_e64 v131, v171, v131, s[12:13]
	s_mul_i32 s100, s36, 88
	v_lshl_add_u64 v[240:241], v[252:253], 0, s[100:101]
	global_load_dwordx4 v[240:243], v[240:241], off
	v_lshl_add_u64 v[248:249], v[254:255], 0, s[100:101]
	global_load_dwordx4 v[248:251], v[248:249], off offset:3072
	s_branch .LBB0_629

; template <int N> __device__ __forceinline__ float dpp_ror(float v) { const int i = __builtin_bit_cast(int, v); return __builtin_bit_cast(float, __builtin_amdgcn_update_dpp(i, i, 0x120 + N, 0xF, 0xF, false)); }
;     __device__ __forceinline__ void operator()(const f32x4 (&acc)[2][2][4][2], const pg8::Unit& u, int wr, int wc, int fr, int fq, PG8_LAS unsigned char* xl) const {
;     ...
;                         } else { const int t = fr & 3, b = (row - MP) >> 2;
; #pragma unroll
;                             for (int j = 0; j < 4; ++j) { p1[j] = dpp_ror<1>(cur[j]); p2[j] = dpp_ror<2>(cur[j]); }
;                             const f32x4 c1 = *(const f32x4*)(ctx_s + (size_t)(b * 2 + 1) * FF2 + bj * FF + jc0 + 4 * n), c0 = *(const f32x4*)(ctx_s + (size_t)(b * 2) * FF2 + bj * FF + jc0 + 4 * n);
; #pragma unroll
;                             for (int j = 0; j < 4; ++j) { p2[j] = t == 0 ? c0[j] : (t == 1 ? c1[j] : p2[j]); p1[j] = t == 0 ? c1[j] : p1[j]; }
;                         }
.Lsmp_0_12:
	v_mov_b32_e32 v88, v12
	v_mov_b32_e32 v89, v12
	v_mov_b32_e32 v90, v13
	v_mov_b32_e32 v91, v13
	v_mov_b32_e32 v131, v14
	v_mov_b32_e32 v163, v15
	v_mov_b32_e32 v130, v14
	v_mov_b32_e32 v155, v15
	v_mov_b32_dpp v88, v88 row_ror:1 row_mask:0xf bank_mask:0xf
	v_mov_b32_dpp v89, v89 row_ror:2 row_mask:0xf bank_mask:0xf
	v_mov_b32_dpp v90, v90 row_ror:1 row_mask:0xf bank_mask:0xf
	v_mov_b32_dpp v91, v91 row_ror:2 row_mask:0xf bank_mask:0xf
	v_mov_b32_dpp v131, v131 row_ror:2 row_mask:0xf bank_mask:0xf
	v_mov_b32_dpp v163, v163 row_ror:2 row_mask:0xf bank_mask:0xf
	v_mov_b32_dpp v130, v130 row_ror:1 row_mask:0xf bank_mask:0xf
	v_mov_b32_dpp v155, v155 row_ror:1 row_mask:0xf bank_mask:0xf
	s_waitcnt vmcnt(4)
	v_cndmask_b32_e64 v89, v89, v240, s[14:15]
	v_cndmask_b32_e64 v80, v88, v240, s[12:13]
	v_cndmask_b32_e64 v88, v91, v241, s[14:15]
	v_cndmask_b32_e64 v81, v90, v241, s[12:13]
	v_cndmask_b32_e64 v90, v131, v242, s[14:15]
	v_cndmask_b32_e64 v91, v163, v243, s[14:15]
	v_cndmask_b32_e64 v82, v130, v242, s[12:13]
	v_cndmask_b32_e64 v83, v155, v243, s[12:13]
	v_mov_b32_dpp v84, v240 row_ror:14 row_mask:0xf bank_mask:0xf
	v_mov_b32_dpp v85, v241 row_ror:14 row_mask:0xf bank_mask:0xf
	v_mov_b32_dpp v86, v242 row_ror:14 row_mask:0xf bank_mask:0xf
	v_mov_b32_dpp v87, v243 row_ror:14 row_mask:0xf bank_mask:0xf
	v_cndmask_b32_e64 v84, v89, v84, s[12:13]
	v_cndmask_b32_e64 v85, v88, v85, s[12:13]
	v_cndmask_b32_e64 v86, v90, v86, s[12:13]
	v_cndmask_b32_e64 v87, v91, v87, s[12:13]
	s_branch .LBB0_635
.Lsmp_0_13:
	v_mov_b32_e32 v130, v4
	v_mov_b32_e32 v131, v4
	v_mov_b32_e32 v155, v5
	v_mov_b32_e32 v163, v5
	v_mov_b32_e32 v226, v6
	v_mov_b32_e32 v228, v7
	v_mov_b32_e32 v171, v6
	v_mov_b32_e32 v227, v7
	v_mov_b32_dpp v130, v130 row_ror:1 row_mask:0xf bank_mask:0xf
	v_mov_b32_dpp v131, v131 row_ror:2 row_mask:0xf bank_mask:0xf
	v_mov_b32_dpp v155, v155 row_ror:1 row_mask:0xf bank_mask:0xf
	v_mov_b32_dpp v163, v163 row_ror:2 row_mask:0xf bank_mask:0xf
	v_mov_b32_dpp v226, v226 row_ror:2 row_mask:0xf bank_mask:0xf
	v_mov_b32_dpp v228, v228 row_ror:2 row_mask:0xf bank_mask:0xf
	v_mov_b32_dpp v171, v171 row_ror:1 row_mask:0xf bank_mask:0xf
	v_mov_b32_dpp v227, v227 row_ror:1 row_mask:0xf bank_mask:0xf
	s_waitcnt vmcnt(3)
	v_cndmask_b32_e64 v131, v131, v248, s[14:15]
	v_cndmask_b32_e64 v76, v130, v248, s[12:13]
	v_cndmask_b32_e64 v130, v163, v249, s[14:15]
	v_cndmask_b32_e64 v77, v155, v249, s[12:13]
	v_cndmask_b32_e64 v155, v226, v250, s[14:15]
	v_cndmask_b32_e64 v163, v228, v251, s[14:15]
	v_cndmask_b32_e64 v78, v171, v250, s[12:13]
	v_cndmask_b32_e64 v79, v227, v251, s[12:13]
	v_mov_b32_dpp v88, v248 row_ror:14 row_mask:0xf bank_mask:0xf
	v_mov_b32_dpp v89, v249 row_ror:14 row_mask:0xf bank_mask:0xf
	v_mov_b32_dpp v90, v250 row_ror:14 row_mask:0xf bank_mask:0xf
	v_mov_b32_dpp v91, v251 row_ror:14 row_mask:0xf bank_mask:0xf
	v_cndmask_b32_e64 v88, v131, v88, s[12:13]
	v_cndmask_b32_e64 v89, v130, v89, s[12:13]
	v_cndmask_b32_e64 v90, v155, v90, s[12:13]
	v_cndmask_b32_e64 v91, v163, v91, s[12:13]
	s_mov_b32 s100, 0
	v_lshl_add_u64 v[240:241], v[252:253], 0, s[100:101]
	global_load_dwordx4 v[240:243], v[240:241], off offset:16
	v_lshl_add_u64 v[248:249], v[254:255], 0, s[100:101]
	global_load_dwordx4 v[248:251], v[248:249], off offset:3088
	s_branch .LBB0_639

; template <int N> __device__ __forceinline__ float dpp_ror(float v) { const int i = __builtin_bit_cast(int, v); return __builtin_bit_cast(float, __builtin_amdgcn_update_dpp(i, i, 0x120 + N, 0xF, 0xF, false)); }
;     __device__ __forceinline__ void operator()(const f32x4 (&acc)[2][2][4][2], const pg8::Unit& u, int wr, int wc, int fr, int fq, PG8_LAS unsigned char* xl) const {
;     ...
;                         } else { const int t = fr & 3, b = (row - MP) >> 2;
; #pragma unroll
;                             for (int j = 0; j < 4; ++j) { p1[j] = dpp_ror<1>(cur[j]); p2[j] = dpp_ror<2>(cur[j]); }
;                             const f32x4 c1 = *(const f32x4*)(ctx_s + (size_t)(b * 2 + 1) * FF2 + bj * FF + jc0 + 4 * n), c0 = *(const f32x4*)(ctx_s + (size_t)(b * 2) * FF2 + bj * FF + jc0 + 4 * n);
; #pragma unroll
;                             for (int j = 0; j < 4; ++j) { p2[j] = t == 0 ? c0[j] : (t == 1 ? c1[j] : p2[j]); p1[j] = t == 0 ? c1[j] : p1[j]; }
;                         }
.Lsmp_0_14:
	v_mov_b32_e32 v120, v68
	v_mov_b32_e32 v121, v68
	v_mov_b32_e32 v122, v69
	v_mov_b32_e32 v123, v69
	v_mov_b32_e32 v163, v70
	v_mov_b32_e32 v204, v71
	v_mov_b32_e32 v155, v70
	v_mov_b32_e32 v171, v71
	v_mov_b32_dpp v120, v120 row_ror:1 row_mask:0xf bank_mask:0xf
	v_mov_b32_dpp v121, v121 row_ror:2 row_mask:0xf bank_mask:0xf
	v_mov_b32_dpp v122, v122 row_ror:1 row_mask:0xf bank_mask:0xf
	v_mov_b32_dpp v123, v123 row_ror:2 row_mask:0xf bank_mask:0xf
	v_mov_b32_dpp v163, v163 row_ror:2 row_mask:0xf bank_mask:0xf
	v_mov_b32_dpp v204, v204 row_ror:2 row_mask:0xf bank_mask:0xf
	v_mov_b32_dpp v155, v155 row_ror:1 row_mask:0xf bank_mask:0xf
	v_mov_b32_dpp v171, v171 row_ror:1 row_mask:0xf bank_mask:0xf
	s_waitcnt vmcnt(12)
	v_cndmask_b32_e64 v121, v121, v240, s[14:15]
	v_cndmask_b32_e64 v108, v120, v240, s[12:13]
	v_cndmask_b32_e64 v120, v123, v241, s[14:15]
	v_cndmask_b32_e64 v109, v122, v241, s[12:13]
	v_cndmask_b32_e64 v122, v163, v242, s[14:15]
	v_cndmask_b32_e64 v123, v204, v243, s[14:15]
	v_cndmask_b32_e64 v110, v155, v242, s[12:13]
	v_cndmask_b32_e64 v111, v171, v243, s[12:13]
	v_mov_b32_dpp v112, v240 row_ror:14 row_mask:0xf bank_mask:0xf
	v_mov_b32_dpp v113, v241 row_ror:14 row_mask:0xf bank_mask:0xf
	v_mov_b32_dpp v114, v242 row_ror:14 row_mask:0xf bank_mask:0xf
	v_mov_b32_dpp v115, v243 row_ror:14 row_mask:0xf bank_mask:0xf
	v_cndmask_b32_e64 v112, v121, v112, s[12:13]
	v_cndmask_b32_e64 v113, v120, v113, s[12:13]
	v_cndmask_b32_e64 v114, v122, v114, s[12:13]
	v_cndmask_b32_e64 v115, v123, v115, s[12:13]
	s_branch .LBB0_647
.Lsmp_0_15:
	s_waitcnt lgkmcnt(1)
	v_mov_b32_e32 v155, v64
	v_mov_b32_e32 v163, v64
	v_mov_b32_e32 v171, v65
	v_mov_b32_e32 v200, v65
	v_mov_b32_e32 v202, v66
	v_mov_b32_e32 v204, v67
	v_mov_b32_e32 v201, v66
	v_mov_b32_e32 v203, v67
	v_mov_b32_dpp v155, v155 row_ror:1 row_mask:0xf bank_mask:0xf
	v_mov_b32_dpp v163, v163 row_ror:2 row_mask:0xf bank_mask:0xf
	v_mov_b32_dpp v171, v171 row_ror:1 row_mask:0xf bank_mask:0xf
	v_mov_b32_dpp v200, v200 row_ror:2 row_mask:0xf bank_mask:0xf
	v_mov_b32_dpp v202, v202 row_ror:2 row_mask:0xf bank_mask:0xf
	v_mov_b32_dpp v204, v204 row_ror:2 row_mask:0xf bank_mask:0xf
	v_mov_b32_dpp v201, v201 row_ror:1 row_mask:0xf bank_mask:0xf
	v_mov_b32_dpp v203, v203 row_ror:1 row_mask:0xf bank_mask:0xf
	s_waitcnt vmcnt(11)
	v_cndmask_b32_e64 v163, v163, v248, s[14:15]
	v_cndmask_b32_e64 v116, v155, v248, s[12:13]
	v_cndmask_b32_e64 v155, v200, v249, s[14:15]
	v_cndmask_b32_e64 v117, v171, v249, s[12:13]
	v_cndmask_b32_e64 v171, v202, v250, s[14:15]
	v_cndmask_b32_e64 v200, v204, v251, s[14:15]
	v_cndmask_b32_e64 v118, v201, v250, s[12:13]
	v_cndmask_b32_e64 v119, v203, v251, s[12:13]
	v_mov_b32_dpp v120, v248 row_ror:14 row_mask:0xf bank_mask:0xf
	v_mov_b32_dpp v121, v249 row_ror:14 row_mask:0xf bank_mask:0xf
	v_mov_b32_dpp v122, v250 row_ror:14 row_mask:0xf bank_mask:0xf
	v_mov_b32_dpp v123, v251 row_ror:14 row_mask:0xf bank_mask:0xf
	v_cndmask_b32_e64 v120, v163, v120, s[12:13]
	v_cndmask_b32_e64 v121, v155, v121, s[12:13]
	v_cndmask_b32_e64 v122, v171, v122, s[12:13]
	v_cndmask_b32_e64 v123, v200, v123, s[12:13]
	s_mul_i32 s100, s36, 8
	v_lshl_add_u64 v[240:241], v[252:253], 0, s[100:101]
	global_load_dwordx4 v[240:243], v[240:241], off offset:16
	v_lshl_add_u64 v[248:249], v[254:255], 0, s[100:101]
	global_load_dwordx4 v[248:251], v[248:249], off offset:3088
	s_branch .LBB0_651
.Lsmp_0_16:
	v_mov_b32_e32 v112, v60
	v_mov_b32_e32 v113, v60
	v_mov_b32_e32 v114, v61
	v_mov_b32_e32 v115, v61
	v_mov_b32_e32 v117, v62
	v_mov_b32_e32 v119, v63
	v_mov_b32_e32 v116, v62
	v_mov_b32_e32 v118, v63
	v_mov_b32_dpp v112, v112 row_ror:1 row_mask:0xf bank_mask:0xf
	v_mov_b32_dpp v113, v113 row_ror:2 row_mask:0xf bank_mask:0xf
	v_mov_b32_dpp v114, v114 row_ror:1 row_mask:0xf bank_mask:0xf
	v_mov_b32_dpp v115, v115 row_ror:2 row_mask:0xf bank_mask:0xf
	v_mov_b32_dpp v117, v117 row_ror:2 row_mask:0xf bank_mask:0xf
	v_mov_b32_dpp v119, v119 row_ror:2 row_mask:0xf bank_mask:0xf
	v_mov_b32_dpp v116, v116 row_ror:1 row_mask:0xf bank_mask:0xf
	v_mov_b32_dpp v118, v118 row_ror:1 row_mask:0xf bank_mask:0xf
	s_waitcnt vmcnt(4)
	v_cndmask_b32_e64 v113, v113, v240, s[14:15]
	v_cndmask_b32_e64 v104, v112, v240, s[12:13]
	v_cndmask_b32_e64 v112, v115, v241, s[14:15]
	v_cndmask_b32_e64 v105, v114, v241, s[12:13]
	v_cndmask_b32_e64 v114, v117, v242, s[14:15]
	v_cndmask_b32_e64 v115, v119, v243, s[14:15]
	v_cndmask_b32_e64 v106, v116, v242, s[12:13]
	v_cndmask_b32_e64 v107, v118, v243, s[12:13]
	v_mov_b32_dpp v108, v240 row_ror:14 row_mask:0xf bank_mask:0xf
	v_mov_b32_dpp v109, v241 row_ror:14 row_mask:0xf bank_mask:0xf
	v_mov_b32_dpp v110, v242 row_ror:14 row_mask:0xf bank_mask:0xf
	v_mov_b32_dpp v111, v243 row_ror:14 row_mask:0xf bank_mask:0xf
	v_cndmask_b32_e64 v108, v113, v108, s[12:13]
	v_cndmask_b32_e64 v109, v112, v109, s[12:13]
	v_cndmask_b32_e64 v110, v114, v110, s[12:13]
	v_cndmask_b32_e64 v111, v115, v111, s[12:13]
	s_branch .LBB0_659
.Lsmp_0_17:
	v_mov_b32_e32 v116, v56
	v_mov_b32_e32 v117, v56
	v_mov_b32_e32 v118, v57
	v_mov_b32_e32 v119, v57
	v_mov_b32_e32 v121, v58
	v_mov_b32_e32 v123, v59
	v_mov_b32_e32 v120, v58
	v_mov_b32_e32 v122, v59
	v_mov_b32_dpp v116, v116 row_ror:1 row_mask:0xf bank_mask:0xf
	v_mov_b32_dpp v117, v117 row_ror:2 row_mask:0xf bank_mask:0xf
	v_mov_b32_dpp v118, v118 row_ror:1 row_mask:0xf bank_mask:0xf
	v_mov_b32_dpp v119, v119 row_ror:2 row_mask:0xf bank_mask:0xf
	v_mov_b32_dpp v121, v121 row_ror:2 row_mask:0xf bank_mask:0xf
	v_mov_b32_dpp v123, v123 row_ror:2 row_mask:0xf bank_mask:0xf
	v_mov_b32_dpp v120, v120 row_ror:1 row_mask:0xf bank_mask:0xf
	v_mov_b32_dpp v122, v122 row_ror:1 row_mask:0xf bank_mask:0xf
	s_waitcnt vmcnt(3)
	v_cndmask_b32_e64 v117, v117, v248, s[14:15]
	v_cndmask_b32_e64 v68, v116, v248, s[12:13]
	v_cndmask_b32_e64 v116, v119, v249, s[14:15]
	v_cndmask_b32_e64 v69, v118, v249, s[12:13]
	v_cndmask_b32_e64 v118, v121, v250, s[14:15]
	v_cndmask_b32_e64 v119, v123, v251, s[14:15]
	v_cndmask_b32_e64 v70, v120, v250, s[12:13]
	v_cndmask_b32_e64 v71, v122, v251, s[12:13]
	v_mov_b32_dpp v112, v248 row_ror:14 row_mask:0xf bank_mask:0xf
	v_mov_b32_dpp v113, v249 row_ror:14 row_mask:0xf bank_mask:0xf
	v_mov_b32_dpp v114, v250 row_ror:14 row_mask:0xf bank_mask:0xf
	v_mov_b32_dpp v115, v251 row_ror:14 row_mask:0xf bank_mask:0xf
	v_cndmask_b32_e64 v112, v117, v112, s[12:13]
	v_cndmask_b32_e64 v113, v116, v113, s[12:13]
	v_cndmask_b32_e64 v114, v118, v114, s[12:13]
	v_cndmask_b32_e64 v115, v119, v115, s[12:13]
	s_mul_i32 s100, s36, 16
	v_lshl_add_u64 v[240:241], v[252:253], 0, s[100:101]
	global_load_dwordx4 v[240:243], v[240:241], off offset:16
	v_lshl_add_u64 v[248:249], v[254:255], 0, s[100:101]
	global_load_dwordx4 v[248:251], v[248:249], off offset:3088
	s_branch .LBB0_663

; template <int N> __device__ __forceinline__ float dpp_ror(float v) { const int i = __builtin_bit_cast(int, v); return __builtin_bit_cast(float, __builtin_amdgcn_update_dpp(i, i, 0x120 + N, 0xF, 0xF, false)); }
;     __device__ __forceinline__ void operator()(const f32x4 (&acc)[2][2][4][2], const pg8::Unit& u, int wr, int wc, int fr, int fq, PG8_LAS unsigned char* xl) const {
;     ...
;                         } else { const int t = fr & 3, b = (row - MP) >> 2;
; #pragma unroll
;                             for (int j = 0; j < 4; ++j) { p1[j] = dpp_ror<1>(cur[j]); p2[j] = dpp_ror<2>(cur[j]); }
;                             const f32x4 c1 = *(const f32x4*)(ctx_s + (size_t)(b * 2 + 1) * FF2 + bj * FF + jc0 + 4 * n), c0 = *(const f32x4*)(ctx_s + (size_t)(b * 2) * FF2 + bj * FF + jc0 + 4 * n);
; #pragma unroll
;                             for (int j = 0; j < 4; ++j) { p2[j] = t == 0 ? c0[j] : (t == 1 ? c1[j] : p2[j]); p1[j] = t == 0 ? c1[j] : p1[j]; }
;                         }
.Lsmp_0_18:
	v_mov_b32_e32 v104, v52
	v_mov_b32_e32 v105, v52
	v_mov_b32_e32 v106, v53
	v_mov_b32_e32 v107, v53
	v_mov_b32_e32 v109, v54
	v_mov_b32_e32 v111, v55
	v_mov_b32_e32 v108, v54
	v_mov_b32_e32 v110, v55
	v_mov_b32_dpp v104, v104 row_ror:1 row_mask:0xf bank_mask:0xf
	v_mov_b32_dpp v105, v105 row_ror:2 row_mask:0xf bank_mask:0xf
	v_mov_b32_dpp v106, v106 row_ror:1 row_mask:0xf bank_mask:0xf
	v_mov_b32_dpp v107, v107 row_ror:2 row_mask:0xf bank_mask:0xf
	v_mov_b32_dpp v109, v109 row_ror:2 row_mask:0xf bank_mask:0xf
	v_mov_b32_dpp v111, v111 row_ror:2 row_mask:0xf bank_mask:0xf
	v_mov_b32_dpp v108, v108 row_ror:1 row_mask:0xf bank_mask:0xf
	v_mov_b32_dpp v110, v110 row_ror:1 row_mask:0xf bank_mask:0xf
	s_waitcnt vmcnt(4)
	v_cndmask_b32_e64 v105, v105, v240, s[14:15]
	v_cndmask_b32_e64 v64, v104, v240, s[12:13]
	v_cndmask_b32_e64 v104, v107, v241, s[14:15]
	v_cndmask_b32_e64 v65, v106, v241, s[12:13]
	v_cndmask_b32_e64 v106, v109, v242, s[14:15]
	v_cndmask_b32_e64 v107, v111, v243, s[14:15]
	v_cndmask_b32_e64 v66, v108, v242, s[12:13]
	v_cndmask_b32_e64 v67, v110, v243, s[12:13]
	v_mov_b32_dpp v68, v240 row_ror:14 row_mask:0xf bank_mask:0xf
	v_mov_b32_dpp v69, v241 row_ror:14 row_mask:0xf bank_mask:0xf
	v_mov_b32_dpp v70, v242 row_ror:14 row_mask:0xf bank_mask:0xf
	v_mov_b32_dpp v71, v243 row_ror:14 row_mask:0xf bank_mask:0xf
	v_cndmask_b32_e64 v68, v105, v68, s[12:13]
	v_cndmask_b32_e64 v69, v104, v69, s[12:13]
	v_cndmask_b32_e64 v70, v106, v70, s[12:13]
	v_cndmask_b32_e64 v71, v107, v71, s[12:13]
	s_branch .LBB0_669
.Lsmp_0_19:
	v_mov_b32_e32 v108, v48
	v_mov_b32_e32 v109, v48
	v_mov_b32_e32 v110, v49
	v_mov_b32_e32 v111, v49
	v_mov_b32_e32 v113, v50
	v_mov_b32_e32 v115, v51
	v_mov_b32_e32 v112, v50
	v_mov_b32_e32 v114, v51
	v_mov_b32_dpp v108, v108 row_ror:1 row_mask:0xf bank_mask:0xf
	v_mov_b32_dpp v109, v109 row_ror:2 row_mask:0xf bank_mask:0xf
	v_mov_b32_dpp v110, v110 row_ror:1 row_mask:0xf bank_mask:0xf
	v_mov_b32_dpp v111, v111 row_ror:2 row_mask:0xf bank_mask:0xf
	v_mov_b32_dpp v113, v113 row_ror:2 row_mask:0xf bank_mask:0xf
	v_mov_b32_dpp v115, v115 row_ror:2 row_mask:0xf bank_mask:0xf
	v_mov_b32_dpp v112, v112 row_ror:1 row_mask:0xf bank_mask:0xf
	v_mov_b32_dpp v114, v114 row_ror:1 row_mask:0xf bank_mask:0xf
	s_waitcnt vmcnt(3)
	v_cndmask_b32_e64 v109, v109, v248, s[14:15]
	v_cndmask_b32_e64 v60, v108, v248, s[12:13]
	v_cndmask_b32_e64 v108, v111, v249, s[14:15]
	v_cndmask_b32_e64 v61, v110, v249, s[12:13]
	v_cndmask_b32_e64 v110, v113, v250, s[14:15]
	v_cndmask_b32_e64 v111, v115, v251, s[14:15]
	v_cndmask_b32_e64 v62, v112, v250, s[12:13]
	v_cndmask_b32_e64 v63, v114, v251, s[12:13]
	v_mov_b32_dpp v104, v248 row_ror:14 row_mask:0xf bank_mask:0xf
	v_mov_b32_dpp v105, v249 row_ror:14 row_mask:0xf bank_mask:0xf
	v_mov_b32_dpp v106, v250 row_ror:14 row_mask:0xf bank_mask:0xf
	v_mov_b32_dpp v107, v251 row_ror:14 row_mask:0xf bank_mask:0xf
	v_cndmask_b32_e64 v104, v109, v104, s[12:13]
	v_cndmask_b32_e64 v105, v108, v105, s[12:13]
	v_cndmask_b32_e64 v106, v110, v106, s[12:13]
	v_cndmask_b32_e64 v107, v111, v107, s[12:13]
	s_mul_i32 s100, s36, 24
	v_lshl_add_u64 v[240:241], v[252:253], 0, s[100:101]
	global_load_dwordx4 v[240:243], v[240:241], off offset:16
	v_lshl_add_u64 v[248:249], v[254:255], 0, s[100:101]
	global_load_dwordx4 v[248:251], v[248:249], off offset:3088
	s_branch .LBB0_673

; template <int N> __device__ __forceinline__ float dpp_ror(float v) { const int i = __builtin_bit_cast(int, v); return __builtin_bit_cast(float, __builtin_amdgcn_update_dpp(i, i, 0x120 + N, 0xF, 0xF, false)); }
;     __device__ __forceinline__ void operator()(const f32x4 (&acc)[2][2][4][2], const pg8::Unit& u, int wr, int wc, int fr, int fq, PG8_LAS unsigned char* xl) const {
;     ...
;                         } else { const int t = fr & 3, b = (row - MP) >> 2;
; #pragma unroll
;                             for (int j = 0; j < 4; ++j) { p1[j] = dpp_ror<1>(cur[j]); p2[j] = dpp_ror<2>(cur[j]); }
;                             const f32x4 c1 = *(const f32x4*)(ctx_s + (size_t)(b * 2 + 1) * FF2 + bj * FF + jc0 + 4 * n), c0 = *(const f32x4*)(ctx_s + (size_t)(b * 2) * FF2 + bj * FF + jc0 + 4 * n);
; #pragma unroll
;                             for (int j = 0; j < 4; ++j) { p2[j] = t == 0 ? c0[j] : (t == 1 ? c1[j] : p2[j]); p1[j] = t == 0 ? c1[j] : p1[j]; }
;                         }
.Lsmp_0_20:
	v_mov_b32_e32 v64, v44
	v_mov_b32_e32 v65, v44
	v_mov_b32_e32 v66, v45
	v_mov_b32_e32 v67, v45
	v_mov_b32_e32 v69, v46
	v_mov_b32_e32 v71, v47
	v_mov_b32_e32 v68, v46
	v_mov_b32_e32 v70, v47
	v_mov_b32_dpp v64, v64 row_ror:1 row_mask:0xf bank_mask:0xf
	v_mov_b32_dpp v65, v65 row_ror:2 row_mask:0xf bank_mask:0xf
	v_mov_b32_dpp v66, v66 row_ror:1 row_mask:0xf bank_mask:0xf
	v_mov_b32_dpp v67, v67 row_ror:2 row_mask:0xf bank_mask:0xf
	v_mov_b32_dpp v69, v69 row_ror:2 row_mask:0xf bank_mask:0xf
	v_mov_b32_dpp v71, v71 row_ror:2 row_mask:0xf bank_mask:0xf
	v_mov_b32_dpp v68, v68 row_ror:1 row_mask:0xf bank_mask:0xf
	v_mov_b32_dpp v70, v70 row_ror:1 row_mask:0xf bank_mask:0xf
	s_waitcnt vmcnt(4)
	v_cndmask_b32_e64 v65, v65, v240, s[14:15]
	v_cndmask_b32_e64 v56, v64, v240, s[12:13]
	v_cndmask_b32_e64 v64, v67, v241, s[14:15]
	v_cndmask_b32_e64 v57, v66, v241, s[12:13]
	v_cndmask_b32_e64 v66, v69, v242, s[14:15]
	v_cndmask_b32_e64 v67, v71, v243, s[14:15]
	v_cndmask_b32_e64 v58, v68, v242, s[12:13]
	v_cndmask_b32_e64 v59, v70, v243, s[12:13]
	v_mov_b32_dpp v60, v240 row_ror:14 row_mask:0xf bank_mask:0xf
	v_mov_b32_dpp v61, v241 row_ror:14 row_mask:0xf bank_mask:0xf
	v_mov_b32_dpp v62, v242 row_ror:14 row_mask:0xf bank_mask:0xf
	v_mov_b32_dpp v63, v243 row_ror:14 row_mask:0xf bank_mask:0xf
	v_cndmask_b32_e64 v60, v65, v60, s[12:13]
	v_cndmask_b32_e64 v61, v64, v61, s[12:13]
	v_cndmask_b32_e64 v62, v66, v62, s[12:13]
	v_cndmask_b32_e64 v63, v67, v63, s[12:13]
	s_branch .LBB0_679
.Lsmp_0_21:
	v_mov_b32_e32 v68, v40
	v_mov_b32_e32 v69, v40
	v_mov_b32_e32 v70, v41
	v_mov_b32_e32 v71, v41
	v_mov_b32_e32 v105, v42
	v_mov_b32_e32 v107, v43
	v_mov_b32_e32 v104, v42
	v_mov_b32_e32 v106, v43
	v_mov_b32_dpp v68, v68 row_ror:1 row_mask:0xf bank_mask:0xf
	v_mov_b32_dpp v69, v69 row_ror:2 row_mask:0xf bank_mask:0xf
	v_mov_b32_dpp v70, v70 row_ror:1 row_mask:0xf bank_mask:0xf
	v_mov_b32_dpp v71, v71 row_ror:2 row_mask:0xf bank_mask:0xf
	v_mov_b32_dpp v105, v105 row_ror:2 row_mask:0xf bank_mask:0xf
	v_mov_b32_dpp v107, v107 row_ror:2 row_mask:0xf bank_mask:0xf
	v_mov_b32_dpp v104, v104 row_ror:1 row_mask:0xf bank_mask:0xf
	v_mov_b32_dpp v106, v106 row_ror:1 row_mask:0xf bank_mask:0xf
	s_waitcnt vmcnt(3)
	v_cndmask_b32_e64 v69, v69, v248, s[14:15]
	v_cndmask_b32_e64 v52, v68, v248, s[12:13]
	v_cndmask_b32_e64 v68, v71, v249, s[14:15]
	v_cndmask_b32_e64 v53, v70, v249, s[12:13]
	v_cndmask_b32_e64 v70, v105, v250, s[14:15]
	v_cndmask_b32_e64 v71, v107, v251, s[14:15]
	v_cndmask_b32_e64 v54, v104, v250, s[12:13]
	v_cndmask_b32_e64 v55, v106, v251, s[12:13]
	v_mov_b32_dpp v64, v248 row_ror:14 row_mask:0xf bank_mask:0xf
	v_mov_b32_dpp v65, v249 row_ror:14 row_mask:0xf bank_mask:0xf
	v_mov_b32_dpp v66, v250 row_ror:14 row_mask:0xf bank_mask:0xf
	v_mov_b32_dpp v67, v251 row_ror:14 row_mask:0xf bank_mask:0xf
	v_cndmask_b32_e64 v64, v69, v64, s[12:13]
	v_cndmask_b32_e64 v65, v68, v65, s[12:13]
	v_cndmask_b32_e64 v66, v70, v66, s[12:13]
	v_cndmask_b32_e64 v67, v71, v67, s[12:13]
	s_mul_i32 s100, s36, 64
	v_lshl_add_u64 v[240:241], v[252:253], 0, s[100:101]
	global_load_dwordx4 v[240:243], v[240:241], off offset:16
	v_lshl_add_u64 v[248:249], v[254:255], 0, s[100:101]
	global_load_dwordx4 v[248:251], v[248:249], off offset:3088
	s_branch .LBB0_683

; template <int N> __device__ __forceinline__ float dpp_ror(float v) { const int i = __builtin_bit_cast(int, v); return __builtin_bit_cast(float, __builtin_amdgcn_update_dpp(i, i, 0x120 + N, 0xF, 0xF, false)); }
;     __device__ __forceinline__ void operator()(const f32x4 (&acc)[2][2][4][2], const pg8::Unit& u, int wr, int wc, int fr, int fq, PG8_LAS unsigned char* xl) const {
;     ...
;                         } else { const int t = fr & 3, b = (row - MP) >> 2;
; #pragma unroll
;                             for (int j = 0; j < 4; ++j) { p1[j] = dpp_ror<1>(cur[j]); p2[j] = dpp_ror<2>(cur[j]); }
;                             const f32x4 c1 = *(const f32x4*)(ctx_s + (size_t)(b * 2 + 1) * FF2 + bj * FF + jc0 + 4 * n), c0 = *(const f32x4*)(ctx_s + (size_t)(b * 2) * FF2 + bj * FF + jc0 + 4 * n);
; #pragma unroll
;                             for (int j = 0; j < 4; ++j) { p2[j] = t == 0 ? c0[j] : (t == 1 ? c1[j] : p2[j]); p1[j] = t == 0 ? c1[j] : p1[j]; }
;                         }
.Lsmp_0_22:
	v_mov_b32_e32 v56, v36
	v_mov_b32_e32 v57, v36
	v_mov_b32_e32 v58, v37
	v_mov_b32_e32 v59, v37
	v_mov_b32_e32 v61, v38
	v_mov_b32_e32 v63, v39
	v_mov_b32_e32 v60, v38
	v_mov_b32_e32 v62, v39
	v_mov_b32_dpp v56, v56 row_ror:1 row_mask:0xf bank_mask:0xf
	v_mov_b32_dpp v57, v57 row_ror:2 row_mask:0xf bank_mask:0xf
	v_mov_b32_dpp v58, v58 row_ror:1 row_mask:0xf bank_mask:0xf
	v_mov_b32_dpp v59, v59 row_ror:2 row_mask:0xf bank_mask:0xf
	v_mov_b32_dpp v61, v61 row_ror:2 row_mask:0xf bank_mask:0xf
	v_mov_b32_dpp v63, v63 row_ror:2 row_mask:0xf bank_mask:0xf
	v_mov_b32_dpp v60, v60 row_ror:1 row_mask:0xf bank_mask:0xf
	v_mov_b32_dpp v62, v62 row_ror:1 row_mask:0xf bank_mask:0xf
	s_waitcnt vmcnt(4)
	v_cndmask_b32_e64 v57, v57, v240, s[14:15]
	v_cndmask_b32_e64 v44, v56, v240, s[12:13]
	v_cndmask_b32_e64 v56, v59, v241, s[14:15]
	v_cndmask_b32_e64 v45, v58, v241, s[12:13]
	v_cndmask_b32_e64 v58, v61, v242, s[14:15]
	v_cndmask_b32_e64 v59, v63, v243, s[14:15]
	v_cndmask_b32_e64 v46, v60, v242, s[12:13]
	v_cndmask_b32_e64 v47, v62, v243, s[12:13]
	v_mov_b32_dpp v48, v240 row_ror:14 row_mask:0xf bank_mask:0xf
	v_mov_b32_dpp v49, v241 row_ror:14 row_mask:0xf bank_mask:0xf
	v_mov_b32_dpp v50, v242 row_ror:14 row_mask:0xf bank_mask:0xf
	v_mov_b32_dpp v51, v243 row_ror:14 row_mask:0xf bank_mask:0xf
	v_cndmask_b32_e64 v48, v57, v48, s[12:13]
	v_cndmask_b32_e64 v49, v56, v49, s[12:13]
	v_cndmask_b32_e64 v50, v58, v50, s[12:13]
	v_cndmask_b32_e64 v51, v59, v51, s[12:13]
	s_branch .LBB0_691
.Lsmp_0_23:
	s_waitcnt lgkmcnt(1)
	v_mov_b32_e32 v60, v32
	v_mov_b32_e32 v61, v32
	v_mov_b32_e32 v62, v33
	v_mov_b32_e32 v63, v33
	v_mov_b32_e32 v65, v34
	v_mov_b32_e32 v67, v35
	v_mov_b32_e32 v64, v34
	v_mov_b32_e32 v66, v35
	v_mov_b32_dpp v60, v60 row_ror:1 row_mask:0xf bank_mask:0xf
	v_mov_b32_dpp v61, v61 row_ror:2 row_mask:0xf bank_mask:0xf
	v_mov_b32_dpp v62, v62 row_ror:1 row_mask:0xf bank_mask:0xf
	v_mov_b32_dpp v63, v63 row_ror:2 row_mask:0xf bank_mask:0xf
	v_mov_b32_dpp v65, v65 row_ror:2 row_mask:0xf bank_mask:0xf
	v_mov_b32_dpp v67, v67 row_ror:2 row_mask:0xf bank_mask:0xf
	v_mov_b32_dpp v64, v64 row_ror:1 row_mask:0xf bank_mask:0xf
	v_mov_b32_dpp v66, v66 row_ror:1 row_mask:0xf bank_mask:0xf
	s_waitcnt vmcnt(3)
	v_cndmask_b32_e64 v61, v61, v248, s[14:15]
	v_cndmask_b32_e64 v52, v60, v248, s[12:13]
	v_cndmask_b32_e64 v60, v63, v249, s[14:15]
	v_cndmask_b32_e64 v53, v62, v249, s[12:13]
	v_cndmask_b32_e64 v62, v65, v250, s[14:15]
	v_cndmask_b32_e64 v63, v67, v251, s[14:15]
	v_cndmask_b32_e64 v54, v64, v250, s[12:13]
	v_cndmask_b32_e64 v55, v66, v251, s[12:13]
	v_mov_b32_dpp v56, v248 row_ror:14 row_mask:0xf bank_mask:0xf
	v_mov_b32_dpp v57, v249 row_ror:14 row_mask:0xf bank_mask:0xf
	v_mov_b32_dpp v58, v250 row_ror:14 row_mask:0xf bank_mask:0xf
	v_mov_b32_dpp v59, v251 row_ror:14 row_mask:0xf bank_mask:0xf
	v_cndmask_b32_e64 v56, v61, v56, s[12:13]
	v_cndmask_b32_e64 v57, v60, v57, s[12:13]
	v_cndmask_b32_e64 v58, v62, v58, s[12:13]
	v_cndmask_b32_e64 v59, v63, v59, s[12:13]
	s_mul_i32 s100, s36, 72
	v_lshl_add_u64 v[240:241], v[252:253], 0, s[100:101]
	global_load_dwordx4 v[240:243], v[240:241], off offset:16
	v_lshl_add_u64 v[248:249], v[254:255], 0, s[100:101]
	global_load_dwordx4 v[248:251], v[248:249], off offset:3088
	s_branch .LBB0_695

; template <int N> __device__ __forceinline__ float dpp_ror(float v) { const int i = __builtin_bit_cast(int, v); return __builtin_bit_cast(float, __builtin_amdgcn_update_dpp(i, i, 0x120 + N, 0xF, 0xF, false)); }
;     __device__ __forceinline__ void operator()(const f32x4 (&acc)[2][2][4][2], const pg8::Unit& u, int wr, int wc, int fr, int fq, PG8_LAS unsigned char* xl) const {
;     ...
;                         } else { const int t = fr & 3, b = (row - MP) >> 2;
; #pragma unroll
;                             for (int j = 0; j < 4; ++j) { p1[j] = dpp_ror<1>(cur[j]); p2[j] = dpp_ror<2>(cur[j]); }
;                             const f32x4 c1 = *(const f32x4*)(ctx_s + (size_t)(b * 2 + 1) * FF2 + bj * FF + jc0 + 4 * n), c0 = *(const f32x4*)(ctx_s + (size_t)(b * 2) * FF2 + bj * FF + jc0 + 4 * n);
; #pragma unroll
;                             for (int j = 0; j < 4; ++j) { p2[j] = t == 0 ? c0[j] : (t == 1 ? c1[j] : p2[j]); p1[j] = t == 0 ? c1[j] : p1[j]; }
;                         }
.Lsmp_0_24:
	v_mov_b32_e32 v48, v28
	v_mov_b32_e32 v49, v28
	v_mov_b32_e32 v50, v29
	v_mov_b32_e32 v51, v29
	v_mov_b32_e32 v53, v30
	v_mov_b32_e32 v55, v31
	v_mov_b32_e32 v52, v30
	v_mov_b32_e32 v54, v31
	v_mov_b32_dpp v48, v48 row_ror:1 row_mask:0xf bank_mask:0xf
	v_mov_b32_dpp v49, v49 row_ror:2 row_mask:0xf bank_mask:0xf
	v_mov_b32_dpp v50, v50 row_ror:1 row_mask:0xf bank_mask:0xf
	v_mov_b32_dpp v51, v51 row_ror:2 row_mask:0xf bank_mask:0xf
	v_mov_b32_dpp v53, v53 row_ror:2 row_mask:0xf bank_mask:0xf
	v_mov_b32_dpp v55, v55 row_ror:2 row_mask:0xf bank_mask:0xf
	v_mov_b32_dpp v52, v52 row_ror:1 row_mask:0xf bank_mask:0xf
	v_mov_b32_dpp v54, v54 row_ror:1 row_mask:0xf bank_mask:0xf
	s_waitcnt vmcnt(4)
	v_cndmask_b32_e64 v49, v49, v240, s[14:15]
	v_cndmask_b32_e64 v40, v48, v240, s[12:13]
	v_cndmask_b32_e64 v48, v51, v241, s[14:15]
	v_cndmask_b32_e64 v41, v50, v241, s[12:13]
	v_cndmask_b32_e64 v50, v53, v242, s[14:15]
	v_cndmask_b32_e64 v51, v55, v243, s[14:15]
	v_cndmask_b32_e64 v42, v52, v242, s[12:13]
	v_cndmask_b32_e64 v43, v54, v243, s[12:13]
	v_mov_b32_dpp v44, v240 row_ror:14 row_mask:0xf bank_mask:0xf
	v_mov_b32_dpp v45, v241 row_ror:14 row_mask:0xf bank_mask:0xf
	v_mov_b32_dpp v46, v242 row_ror:14 row_mask:0xf bank_mask:0xf
	v_mov_b32_dpp v47, v243 row_ror:14 row_mask:0xf bank_mask:0xf
	v_cndmask_b32_e64 v44, v49, v44, s[12:13]
	v_cndmask_b32_e64 v45, v48, v45, s[12:13]
	v_cndmask_b32_e64 v46, v50, v46, s[12:13]
	v_cndmask_b32_e64 v47, v51, v47, s[12:13]
	s_branch .LBB0_701
.Lsmp_0_25:
	v_mov_b32_e32 v52, v24
	v_mov_b32_e32 v53, v24
	v_mov_b32_e32 v54, v25
	v_mov_b32_e32 v55, v25
	v_mov_b32_e32 v57, v26
	v_mov_b32_e32 v59, v27
	v_mov_b32_e32 v56, v26
	v_mov_b32_e32 v58, v27
	v_mov_b32_dpp v52, v52 row_ror:1 row_mask:0xf bank_mask:0xf
	v_mov_b32_dpp v53, v53 row_ror:2 row_mask:0xf bank_mask:0xf
	v_mov_b32_dpp v54, v54 row_ror:1 row_mask:0xf bank_mask:0xf
	v_mov_b32_dpp v55, v55 row_ror:2 row_mask:0xf bank_mask:0xf
	v_mov_b32_dpp v57, v57 row_ror:2 row_mask:0xf bank_mask:0xf
	v_mov_b32_dpp v59, v59 row_ror:2 row_mask:0xf bank_mask:0xf
	v_mov_b32_dpp v56, v56 row_ror:1 row_mask:0xf bank_mask:0xf
	v_mov_b32_dpp v58, v58 row_ror:1 row_mask:0xf bank_mask:0xf
	s_waitcnt vmcnt(3)
	v_cndmask_b32_e64 v53, v53, v248, s[14:15]
	v_cndmask_b32_e64 v36, v52, v248, s[12:13]
	v_cndmask_b32_e64 v52, v55, v249, s[14:15]
	v_cndmask_b32_e64 v37, v54, v249, s[12:13]
	v_cndmask_b32_e64 v54, v57, v250, s[14:15]
	v_cndmask_b32_e64 v55, v59, v251, s[14:15]
	v_cndmask_b32_e64 v38, v56, v250, s[12:13]
	v_cndmask_b32_e64 v39, v58, v251, s[12:13]
	v_mov_b32_dpp v48, v248 row_ror:14 row_mask:0xf bank_mask:0xf
	v_mov_b32_dpp v49, v249 row_ror:14 row_mask:0xf bank_mask:0xf
	v_mov_b32_dpp v50, v250 row_ror:14 row_mask:0xf bank_mask:0xf
	v_mov_b32_dpp v51, v251 row_ror:14 row_mask:0xf bank_mask:0xf
	v_cndmask_b32_e64 v48, v53, v48, s[12:13]
	v_cndmask_b32_e64 v49, v52, v49, s[12:13]
	v_cndmask_b32_e64 v50, v54, v50, s[12:13]
	v_cndmask_b32_e64 v51, v55, v51, s[12:13]
	s_mul_i32 s100, s36, 80
	v_lshl_add_u64 v[240:241], v[252:253], 0, s[100:101]
	global_load_dwordx4 v[240:243], v[240:241], off offset:16
	v_lshl_add_u64 v[248:249], v[254:255], 0, s[100:101]
	global_load_dwordx4 v[248:251], v[248:249], off offset:3088
	s_branch .LBB0_705

; template <int N> __device__ __forceinline__ float dpp_ror(float v) { const int i = __builtin_bit_cast(int, v); return __builtin_bit_cast(float, __builtin_amdgcn_update_dpp(i, i, 0x120 + N, 0xF, 0xF, false)); }
;     __device__ __forceinline__ void operator()(const f32x4 (&acc)[2][2][4][2], const pg8::Unit& u, int wr, int wc, int fr, int fq, PG8_LAS unsigned char* xl) const {
;     ...
;                         } else { const int t = fr & 3, b = (row - MP) >> 2;
; #pragma unroll
;                             for (int j = 0; j < 4; ++j) { p1[j] = dpp_ror<1>(cur[j]); p2[j] = dpp_ror<2>(cur[j]); }
;                             const f32x4 c1 = *(const f32x4*)(ctx_s + (size_t)(b * 2 + 1) * FF2 + bj * FF + jc0 + 4 * n), c0 = *(const f32x4*)(ctx_s + (size_t)(b * 2) * FF2 + bj * FF + jc0 + 4 * n);
; #pragma unroll
;                             for (int j = 0; j < 4; ++j) { p2[j] = t == 0 ? c0[j] : (t == 1 ? c1[j] : p2[j]); p1[j] = t == 0 ? c1[j] : p1[j]; }
;                         }
.Lsmp_0_26:
	v_mov_b32_e32 v40, v20
	v_mov_b32_e32 v41, v20
	v_mov_b32_e32 v42, v21
	v_mov_b32_e32 v43, v21
	v_mov_b32_e32 v45, v22
	v_mov_b32_e32 v47, v23
	v_mov_b32_e32 v44, v22
	v_mov_b32_e32 v46, v23
	v_mov_b32_dpp v40, v40 row_ror:1 row_mask:0xf bank_mask:0xf
	v_mov_b32_dpp v41, v41 row_ror:2 row_mask:0xf bank_mask:0xf
	v_mov_b32_dpp v42, v42 row_ror:1 row_mask:0xf bank_mask:0xf
	v_mov_b32_dpp v43, v43 row_ror:2 row_mask:0xf bank_mask:0xf
	v_mov_b32_dpp v45, v45 row_ror:2 row_mask:0xf bank_mask:0xf
	v_mov_b32_dpp v47, v47 row_ror:2 row_mask:0xf bank_mask:0xf
	v_mov_b32_dpp v44, v44 row_ror:1 row_mask:0xf bank_mask:0xf
	v_mov_b32_dpp v46, v46 row_ror:1 row_mask:0xf bank_mask:0xf
	s_waitcnt vmcnt(4)
	v_cndmask_b32_e64 v41, v41, v240, s[14:15]
	v_cndmask_b32_e64 v32, v40, v240, s[12:13]
	v_cndmask_b32_e64 v40, v43, v241, s[14:15]
	v_cndmask_b32_e64 v33, v42, v241, s[12:13]
	v_cndmask_b32_e64 v42, v45, v242, s[14:15]
	v_cndmask_b32_e64 v43, v47, v243, s[14:15]
	v_cndmask_b32_e64 v34, v44, v242, s[12:13]
	v_cndmask_b32_e64 v35, v46, v243, s[12:13]
	v_mov_b32_dpp v36, v240 row_ror:14 row_mask:0xf bank_mask:0xf
	v_mov_b32_dpp v37, v241 row_ror:14 row_mask:0xf bank_mask:0xf
	v_mov_b32_dpp v38, v242 row_ror:14 row_mask:0xf bank_mask:0xf
	v_mov_b32_dpp v39, v243 row_ror:14 row_mask:0xf bank_mask:0xf
	v_cndmask_b32_e64 v36, v41, v36, s[12:13]
	v_cndmask_b32_e64 v37, v40, v37, s[12:13]
	v_cndmask_b32_e64 v38, v42, v38, s[12:13]
	v_cndmask_b32_e64 v39, v43, v39, s[12:13]
	s_branch .LBB0_711
.Lsmp_0_27:
	v_mov_b32_e32 v44, v16
	v_mov_b32_e32 v45, v16
	v_mov_b32_e32 v46, v17
	v_mov_b32_e32 v47, v17
	v_mov_b32_e32 v49, v18
	v_mov_b32_e32 v51, v19
	v_mov_b32_e32 v48, v18
	v_mov_b32_e32 v50, v19
	v_mov_b32_dpp v44, v44 row_ror:1 row_mask:0xf bank_mask:0xf
	v_mov_b32_dpp v45, v45 row_ror:2 row_mask:0xf bank_mask:0xf
	v_mov_b32_dpp v46, v46 row_ror:1 row_mask:0xf bank_mask:0xf
	v_mov_b32_dpp v47, v47 row_ror:2 row_mask:0xf bank_mask:0xf
	v_mov_b32_dpp v49, v49 row_ror:2 row_mask:0xf bank_mask:0xf
	v_mov_b32_dpp v51, v51 row_ror:2 row_mask:0xf bank_mask:0xf
	v_mov_b32_dpp v48, v48 row_ror:1 row_mask:0xf bank_mask:0xf
	v_mov_b32_dpp v50, v50 row_ror:1 row_mask:0xf bank_mask:0xf
	s_waitcnt vmcnt(3)
	v_cndmask_b32_e64 v45, v45, v248, s[14:15]
	v_cndmask_b32_e64 v28, v44, v248, s[12:13]
	v_cndmask_b32_e64 v44, v47, v249, s[14:15]
	v_cndmask_b32_e64 v29, v46, v249, s[12:13]
	v_cndmask_b32_e64 v46, v49, v250, s[14:15]
	v_cndmask_b32_e64 v47, v51, v251, s[14:15]
	v_cndmask_b32_e64 v30, v48, v250, s[12:13]
	v_cndmask_b32_e64 v31, v50, v251, s[12:13]
	v_mov_b32_dpp v40, v248 row_ror:14 row_mask:0xf bank_mask:0xf
	v_mov_b32_dpp v41, v249 row_ror:14 row_mask:0xf bank_mask:0xf
	v_mov_b32_dpp v42, v250 row_ror:14 row_mask:0xf bank_mask:0xf
	v_mov_b32_dpp v43, v251 row_ror:14 row_mask:0xf bank_mask:0xf
	v_cndmask_b32_e64 v40, v45, v40, s[12:13]
	v_cndmask_b32_e64 v41, v44, v41, s[12:13]
	v_cndmask_b32_e64 v42, v46, v42, s[12:13]
	v_cndmask_b32_e64 v43, v47, v43, s[12:13]
	s_mul_i32 s100, s36, 88
	v_lshl_add_u64 v[240:241], v[252:253], 0, s[100:101]
	global_load_dwordx4 v[240:243], v[240:241], off offset:16
	v_lshl_add_u64 v[248:249], v[254:255], 0, s[100:101]
	global_load_dwordx4 v[248:251], v[248:249], off offset:3088
	s_branch .LBB0_715

; template <int N> __device__ __forceinline__ float dpp_ror(float v) { const int i = __builtin_bit_cast(int, v); return __builtin_bit_cast(float, __builtin_amdgcn_update_dpp(i, i, 0x120 + N, 0xF, 0xF, false)); }
;     __device__ __forceinline__ void operator()(const f32x4 (&acc)[2][2][4][2], const pg8::Unit& u, int wr, int wc, int fr, int fq, PG8_LAS unsigned char* xl) const {
;     ...
;                         } else { const int t = fr & 3, b = (row - MP) >> 2;
; #pragma unroll
;                             for (int j = 0; j < 4; ++j) { p1[j] = dpp_ror<1>(cur[j]); p2[j] = dpp_ror<2>(cur[j]); }
;                             const f32x4 c1 = *(const f32x4*)(ctx_s + (size_t)(b * 2 + 1) * FF2 + bj * FF + jc0 + 4 * n), c0 = *(const f32x4*)(ctx_s + (size_t)(b * 2) * FF2 + bj * FF + jc0 + 4 * n);
; #pragma unroll
;                             for (int j = 0; j < 4; ++j) { p2[j] = t == 0 ? c0[j] : (t == 1 ? c1[j] : p2[j]); p1[j] = t == 0 ? c1[j] : p1[j]; }
;                         }
.Lsmp_0_28:
	v_mov_b32_e32 v32, v8
	v_mov_b32_e32 v33, v8
	v_mov_b32_e32 v34, v9
	v_mov_b32_e32 v35, v9
	v_mov_b32_e32 v37, v10
	v_mov_b32_e32 v39, v11
	v_mov_b32_e32 v36, v10
	v_mov_b32_e32 v38, v11
	v_mov_b32_dpp v32, v32 row_ror:1 row_mask:0xf bank_mask:0xf
	v_mov_b32_dpp v33, v33 row_ror:2 row_mask:0xf bank_mask:0xf
	v_mov_b32_dpp v34, v34 row_ror:1 row_mask:0xf bank_mask:0xf
	v_mov_b32_dpp v35, v35 row_ror:2 row_mask:0xf bank_mask:0xf
	v_mov_b32_dpp v37, v37 row_ror:2 row_mask:0xf bank_mask:0xf
	v_mov_b32_dpp v39, v39 row_ror:2 row_mask:0xf bank_mask:0xf
	v_mov_b32_dpp v36, v36 row_ror:1 row_mask:0xf bank_mask:0xf
	v_mov_b32_dpp v38, v38 row_ror:1 row_mask:0xf bank_mask:0xf
	s_waitcnt vmcnt(4)
	v_cndmask_b32_e64 v33, v33, v240, s[14:15]
	v_cndmask_b32_e64 v24, v32, v240, s[12:13]
	v_cndmask_b32_e64 v32, v35, v241, s[14:15]
	v_cndmask_b32_e64 v25, v34, v241, s[12:13]
	v_cndmask_b32_e64 v34, v37, v242, s[14:15]
	v_cndmask_b32_e64 v35, v39, v243, s[14:15]
	v_cndmask_b32_e64 v26, v36, v242, s[12:13]
	v_cndmask_b32_e64 v27, v38, v243, s[12:13]
	v_mov_b32_dpp v28, v240 row_ror:14 row_mask:0xf bank_mask:0xf
	v_mov_b32_dpp v29, v241 row_ror:14 row_mask:0xf bank_mask:0xf
	v_mov_b32_dpp v30, v242 row_ror:14 row_mask:0xf bank_mask:0xf
	v_mov_b32_dpp v31, v243 row_ror:14 row_mask:0xf bank_mask:0xf
	v_cndmask_b32_e64 v28, v33, v28, s[12:13]
	v_cndmask_b32_e64 v29, v32, v29, s[12:13]
	v_cndmask_b32_e64 v30, v34, v30, s[12:13]
	v_cndmask_b32_e64 v31, v35, v31, s[12:13]
	s_branch .LBB0_721
.Lsmp_0_29:
	v_mov_b32_e32 v36, v0
	v_mov_b32_e32 v37, v0
	v_mov_b32_e32 v38, v1
	v_mov_b32_e32 v39, v1
	v_mov_b32_e32 v41, v2
	v_mov_b32_e32 v43, v3
	v_mov_b32_e32 v40, v2
	v_mov_b32_e32 v42, v3
	v_mov_b32_dpp v36, v36 row_ror:1 row_mask:0xf bank_mask:0xf
	v_mov_b32_dpp v37, v37 row_ror:2 row_mask:0xf bank_mask:0xf
	v_mov_b32_dpp v38, v38 row_ror:1 row_mask:0xf bank_mask:0xf
	v_mov_b32_dpp v39, v39 row_ror:2 row_mask:0xf bank_mask:0xf
	v_mov_b32_dpp v41, v41 row_ror:2 row_mask:0xf bank_mask:0xf
	v_mov_b32_dpp v43, v43 row_ror:2 row_mask:0xf bank_mask:0xf
	v_mov_b32_dpp v40, v40 row_ror:1 row_mask:0xf bank_mask:0xf
	v_mov_b32_dpp v42, v42 row_ror:1 row_mask:0xf bank_mask:0xf
	s_waitcnt vmcnt(3)
	v_cndmask_b32_e64 v37, v37, v248, s[14:15]
	v_cndmask_b32_e64 v20, v36, v248, s[12:13]
	v_cndmask_b32_e64 v36, v39, v249, s[14:15]
	v_cndmask_b32_e64 v21, v38, v249, s[12:13]
	v_cndmask_b32_e64 v38, v41, v250, s[14:15]
	v_cndmask_b32_e64 v39, v43, v251, s[14:15]
	v_cndmask_b32_e64 v22, v40, v250, s[12:13]
	v_cndmask_b32_e64 v23, v42, v251, s[12:13]
	v_mov_b32_dpp v32, v248 row_ror:14 row_mask:0xf bank_mask:0xf
	v_mov_b32_dpp v33, v249 row_ror:14 row_mask:0xf bank_mask:0xf
	v_mov_b32_dpp v34, v250 row_ror:14 row_mask:0xf bank_mask:0xf
	v_mov_b32_dpp v35, v251 row_ror:14 row_mask:0xf bank_mask:0xf
	v_cndmask_b32_e64 v32, v37, v32, s[12:13]
	v_cndmask_b32_e64 v33, v36, v33, s[12:13]
	v_cndmask_b32_e64 v34, v38, v34, s[12:13]
	v_cndmask_b32_e64 v35, v39, v35, s[12:13]
	s_branch .LBB0_725

; template <int N> __device__ __forceinline__ float dpp_ror(float v) { const int i = __builtin_bit_cast(int, v); return __builtin_bit_cast(float, __builtin_amdgcn_update_dpp(i, i, 0x120 + N, 0xF, 0xF, false)); }
;     __device__ __forceinline__ void operator()(const f32x4 (&acc)[2][2][4][2], const pg8::Unit& u, int wr, int wc, int fr, int fq, PG8_LAS unsigned char* xl) const {
;     ...
;                         } else { const int t = fr & 3, b = (row - MP) >> 2;
; #pragma unroll
;                             for (int j = 0; j < 4; ++j) { p1[j] = dpp_ror<1>(cur[j]); p2[j] = dpp_ror<2>(cur[j]); }
;                             const f32x4 c1 = *(const f32x4*)(ctx_s + (size_t)(b * 2 + 1) * FF2 + bj * FF + jc0 + 4 * n), c0 = *(const f32x4*)(ctx_s + (size_t)(b * 2) * FF2 + bj * FF + jc0 + 4 * n);
; #pragma unroll
;                             for (int j = 0; j < 4; ++j) { p2[j] = t == 0 ? c0[j] : (t == 1 ? c1[j] : p2[j]); p1[j] = t == 0 ? c1[j] : p1[j]; }
;                         }
.Lsmp1_0_0:
	v_or_b32_e32 v166, 1, v164
	v_mov_b64_e32 v[164:165], s[40:41]
	v_mad_i64_i32 v[166:167], vcc, v166, s36, v[164:165]
	v_mad_i64_i32 v[164:165], vcc, v224, s36, v[164:165]
	v_lshl_add_u64 v[202:203], v[166:167], 0, v[198:199]
	v_lshl_add_u64 v[200:201], v[164:165], 0, v[198:199]
	s_or_b64 vcc, s[12:13], s[14:15]
	s_mov_b32 s101, 0
	v_cndmask_b32_e32 v252, v200, v202, vcc
	v_cndmask_b32_e32 v253, v201, v203, vcc
	s_movk_i32 s100, 0x2000
	global_load_dwordx4 v[240:243], v[252:253], off
	v_lshl_add_u64 v[254:255], v[252:253], 0, s[100:101]
	global_load_dwordx4 v[248:251], v[254:255], off offset:3072
	v_mov_b32_e32 v176, v156
	v_mov_b32_e32 v177, v156
	v_mov_b32_e32 v178, v157
	v_mov_b32_e32 v179, v157
	v_mov_b32_e32 v227, v158
	v_mov_b32_e32 v229, v159
	v_mov_b32_e32 v226, v158
	v_mov_b32_e32 v228, v159
	v_mov_b32_dpp v176, v176 row_ror:1 row_mask:0xf bank_mask:0xf
	v_mov_b32_dpp v177, v177 row_ror:2 row_mask:0xf bank_mask:0xf
	v_mov_b32_dpp v178, v178 row_ror:1 row_mask:0xf bank_mask:0xf
	v_mov_b32_dpp v179, v179 row_ror:2 row_mask:0xf bank_mask:0xf
	v_mov_b32_dpp v227, v227 row_ror:2 row_mask:0xf bank_mask:0xf
	v_mov_b32_dpp v229, v229 row_ror:2 row_mask:0xf bank_mask:0xf
	v_mov_b32_dpp v226, v226 row_ror:1 row_mask:0xf bank_mask:0xf
	v_mov_b32_dpp v228, v228 row_ror:1 row_mask:0xf bank_mask:0xf
	s_mov_b64 s[6:7], 0
	s_waitcnt vmcnt(1)
	v_cndmask_b32_e64 v177, v177, v240, s[14:15]
	v_cndmask_b32_e64 v164, v176, v240, s[12:13]
	v_cndmask_b32_e64 v176, v179, v241, s[14:15]
	v_cndmask_b32_e64 v165, v178, v241, s[12:13]
	v_cndmask_b32_e64 v178, v227, v242, s[14:15]
	v_cndmask_b32_e64 v179, v229, v243, s[14:15]
	v_cndmask_b32_e64 v166, v226, v242, s[12:13]
	v_cndmask_b32_e64 v167, v228, v243, s[12:13]
	v_mov_b32_dpp v168, v240 row_ror:14 row_mask:0xf bank_mask:0xf
	v_mov_b32_dpp v169, v241 row_ror:14 row_mask:0xf bank_mask:0xf
	v_mov_b32_dpp v170, v242 row_ror:14 row_mask:0xf bank_mask:0xf
	v_mov_b32_dpp v171, v243 row_ror:14 row_mask:0xf bank_mask:0xf
	v_cndmask_b32_e64 v168, v177, v168, s[12:13]
	v_cndmask_b32_e64 v169, v176, v169, s[12:13]
	v_cndmask_b32_e64 v170, v178, v170, s[12:13]
	v_cndmask_b32_e64 v171, v179, v171, s[12:13]
	s_branch .LBB0_561
.Lsmp1_0_1:
	v_mov_b32_e32 v226, v152
	v_mov_b32_e32 v227, v152
	v_mov_b32_e32 v228, v153
	v_mov_b32_e32 v229, v153
	v_mov_b32_e32 v231, v154
	v_mov_b32_e32 v233, v155
	v_mov_b32_e32 v230, v154
	v_mov_b32_e32 v232, v155
	v_mov_b32_dpp v226, v226 row_ror:1 row_mask:0xf bank_mask:0xf
	v_mov_b32_dpp v227, v227 row_ror:2 row_mask:0xf bank_mask:0xf
	v_mov_b32_dpp v228, v228 row_ror:1 row_mask:0xf bank_mask:0xf
	v_mov_b32_dpp v229, v229 row_ror:2 row_mask:0xf bank_mask:0xf
	v_mov_b32_dpp v231, v231 row_ror:2 row_mask:0xf bank_mask:0xf
	v_mov_b32_dpp v233, v233 row_ror:2 row_mask:0xf bank_mask:0xf
	v_mov_b32_dpp v230, v230 row_ror:1 row_mask:0xf bank_mask:0xf
	v_mov_b32_dpp v232, v232 row_ror:1 row_mask:0xf bank_mask:0xf
	s_mov_b64 s[6:7], 0
	s_waitcnt vmcnt(0)
	v_cndmask_b32_e64 v227, v227, v248, s[14:15]
	v_cndmask_b32_e64 v172, v226, v248, s[12:13]
	v_cndmask_b32_e64 v226, v229, v249, s[14:15]
	v_cndmask_b32_e64 v173, v228, v249, s[12:13]
	v_cndmask_b32_e64 v228, v231, v250, s[14:15]
	v_cndmask_b32_e64 v229, v233, v251, s[14:15]
	v_cndmask_b32_e64 v174, v230, v250, s[12:13]
	v_cndmask_b32_e64 v175, v232, v251, s[12:13]
	v_mov_b32_dpp v176, v248 row_ror:14 row_mask:0xf bank_mask:0xf
	v_mov_b32_dpp v177, v249 row_ror:14 row_mask:0xf bank_mask:0xf
	v_mov_b32_dpp v178, v250 row_ror:14 row_mask:0xf bank_mask:0xf
	v_mov_b32_dpp v179, v251 row_ror:14 row_mask:0xf bank_mask:0xf
	v_cndmask_b32_e64 v176, v227, v176, s[12:13]
	v_cndmask_b32_e64 v177, v226, v177, s[12:13]
	v_cndmask_b32_e64 v178, v228, v178, s[12:13]
	v_cndmask_b32_e64 v179, v229, v179, s[12:13]
	s_mul_i32 s100, s36, 8
	v_lshl_add_u64 v[240:241], v[252:253], 0, s[100:101]
	global_load_dwordx4 v[240:243], v[240:241], off
	v_lshl_add_u64 v[248:249], v[254:255], 0, s[100:101]
	global_load_dwordx4 v[248:251], v[248:249], off offset:3072
	s_branch .LBB0_565

; template <int N> __device__ __forceinline__ float dpp_ror(float v) { const int i = __builtin_bit_cast(int, v); return __builtin_bit_cast(float, __builtin_amdgcn_update_dpp(i, i, 0x120 + N, 0xF, 0xF, false)); }
;     __device__ __forceinline__ void operator()(const f32x4 (&acc)[2][2][4][2], const pg8::Unit& u, int wr, int wc, int fr, int fq, PG8_LAS unsigned char* xl) const {
;     ...
;                         const f32x4 cur = acc[ai][bj][m][n]; f32x4 p1, p2;
;                         if (!sample) { const f32x4 prv = (m == 0) ? hb[bj] : acc[ai][bj][m == 0 ? 0 : m - 1][n];
; #pragma unroll
;                             for (int j = 0; j < 4; ++j) { const float s1 = fr == 15 ? prv[j] : cur[j], s2 = fr >= 14 ? prv[j] : cur[j]; p1[j] = dpp_ror<1>(s1); p2[j] = dpp_ror<2>(s2); }
;                         } else { const int t = fr & 3, b = (row - MP) >> 2;
; #pragma unroll
;                             for (int j = 0; j < 4; ++j) { p1[j] = dpp_ror<1>(cur[j]); p2[j] = dpp_ror<2>(cur[j]); }
;                             const f32x4 c1 = *(const f32x4*)(ctx_s + (size_t)(b * 2 + 1) * FF2 + bj * FF + jc0 + 4 * n), c0 = *(const f32x4*)(ctx_s + (size_t)(b * 2) * FF2 + bj * FF + jc0 + 4 * n);
; #pragma unroll
;                             for (int j = 0; j < 4; ++j) { p2[j] = t == 0 ? c0[j] : (t == 1 ? c1[j] : p2[j]); p1[j] = t == 0 ? c1[j] : p1[j]; }
;                         }
.LBB0_1675:
	s_or_b64 exec, exec, s[6:7]
	v_lshl_add_u32 v221, s36, 8, v206
	v_add_u32_e32 v164, 0xffffc000, v221
	v_ashrrev_i32_e32 v164, 1, v164
	v_and_b32_e32 v220, 0xffffffe6, v164
	s_mov_b64 s[6:7], -1
	s_and_b64 vcc, exec, s[58:59]
	s_cbranch_vccnz .Lsmp1_1_0
	s_waitcnt lgkmcnt(0)
	v_cndmask_b32_e64 v164, v156, v172, s[16:17]
	v_cndmask_b32_e64 v168, v156, v172, s[10:11]
	v_cndmask_b32_e64 v165, v157, v173, s[16:17]
	v_cndmask_b32_e64 v169, v157, v173, s[10:11]
	v_cndmask_b32_e64 v166, v158, v174, s[16:17]
	v_cndmask_b32_e64 v170, v158, v174, s[10:11]
	v_cndmask_b32_e64 v167, v159, v175, s[16:17]
	v_cndmask_b32_e64 v171, v159, v175, s[10:11]
	v_mov_b32_dpp v164, v164 row_ror:1 row_mask:0xf bank_mask:0xf
	v_mov_b32_dpp v168, v168 row_ror:2 row_mask:0xf bank_mask:0xf
	v_mov_b32_dpp v165, v165 row_ror:1 row_mask:0xf bank_mask:0xf
	v_mov_b32_dpp v169, v169 row_ror:2 row_mask:0xf bank_mask:0xf
	v_mov_b32_dpp v166, v166 row_ror:1 row_mask:0xf bank_mask:0xf
	v_mov_b32_dpp v170, v170 row_ror:2 row_mask:0xf bank_mask:0xf
	v_mov_b32_dpp v167, v167 row_ror:1 row_mask:0xf bank_mask:0xf
	v_mov_b32_dpp v171, v171 row_ror:2 row_mask:0xf bank_mask:0xf
.LBB0_1679:
	s_waitcnt lgkmcnt(0)
	v_cndmask_b32_e64 v172, 0, 1, s[58:59]
	v_cmp_ne_u32_e64 s[22:23], 1, v172
	s_andn2_b64 vcc, exec, s[58:59]
	s_mov_b64 s[6:7], -1
	s_cbranch_vccz .Lsmp1_1_1
	v_cndmask_b32_e64 v172, v152, v160, s[16:17]
	v_cndmask_b32_e64 v176, v152, v160, s[10:11]
	v_cndmask_b32_e64 v173, v153, v161, s[16:17]
	v_cndmask_b32_e64 v177, v153, v161, s[10:11]
	v_cndmask_b32_e64 v174, v154, v162, s[16:17]
	v_cndmask_b32_e64 v178, v154, v162, s[10:11]
	v_cndmask_b32_e64 v175, v155, v163, s[16:17]
	v_cndmask_b32_e64 v179, v155, v163, s[10:11]
	v_mov_b32_dpp v172, v172 row_ror:1 row_mask:0xf bank_mask:0xf
	v_mov_b32_dpp v176, v176 row_ror:2 row_mask:0xf bank_mask:0xf
	v_mov_b32_dpp v173, v173 row_ror:1 row_mask:0xf bank_mask:0xf
	v_mov_b32_dpp v177, v177 row_ror:2 row_mask:0xf bank_mask:0xf
	v_mov_b32_dpp v174, v174 row_ror:1 row_mask:0xf bank_mask:0xf
	v_mov_b32_dpp v178, v178 row_ror:2 row_mask:0xf bank_mask:0xf
	v_mov_b32_dpp v175, v175 row_ror:1 row_mask:0xf bank_mask:0xf
	v_mov_b32_dpp v179, v179 row_ror:2 row_mask:0xf bank_mask:0xf

; template <int N> __device__ __forceinline__ float dpp_ror(float v) { const int i = __builtin_bit_cast(int, v); return __builtin_bit_cast(float, __builtin_amdgcn_update_dpp(i, i, 0x120 + N, 0xF, 0xF, false)); }
;     __device__ __forceinline__ void operator()(const f32x4 (&acc)[2][2][4][2], const pg8::Unit& u, int wr, int wc, int fr, int fq, PG8_LAS unsigned char* xl) const {
;     ...
;                         } else { const int t = fr & 3, b = (row - MP) >> 2;
; #pragma unroll
;                             for (int j = 0; j < 4; ++j) { p1[j] = dpp_ror<1>(cur[j]); p2[j] = dpp_ror<2>(cur[j]); }
;                             const f32x4 c1 = *(const f32x4*)(ctx_s + (size_t)(b * 2 + 1) * FF2 + bj * FF + jc0 + 4 * n), c0 = *(const f32x4*)(ctx_s + (size_t)(b * 2) * FF2 + bj * FF + jc0 + 4 * n);
; #pragma unroll
;                             for (int j = 0; j < 4; ++j) { p2[j] = t == 0 ? c0[j] : (t == 1 ? c1[j] : p2[j]); p1[j] = t == 0 ? c1[j] : p1[j]; }
;                         }
.Lsmp_1_30:
	v_mov_b32_e32 v168, v148
	v_mov_b32_e32 v169, v148
	v_mov_b32_e32 v170, v149
	v_mov_b32_e32 v171, v149
	v_mov_b32_e32 v224, v150
	v_mov_b32_e32 v226, v151
	v_mov_b32_e32 v223, v150
	v_mov_b32_e32 v225, v151
	v_mov_b32_dpp v168, v168 row_ror:1 row_mask:0xf bank_mask:0xf
	v_mov_b32_dpp v169, v169 row_ror:2 row_mask:0xf bank_mask:0xf
	v_mov_b32_dpp v170, v170 row_ror:1 row_mask:0xf bank_mask:0xf
	v_mov_b32_dpp v171, v171 row_ror:2 row_mask:0xf bank_mask:0xf
	v_mov_b32_dpp v224, v224 row_ror:2 row_mask:0xf bank_mask:0xf
	v_mov_b32_dpp v226, v226 row_ror:2 row_mask:0xf bank_mask:0xf
	v_mov_b32_dpp v223, v223 row_ror:1 row_mask:0xf bank_mask:0xf
	v_mov_b32_dpp v225, v225 row_ror:1 row_mask:0xf bank_mask:0xf
	s_waitcnt vmcnt(4)
	v_cndmask_b32_e64 v169, v169, v240, s[14:15]
	v_cndmask_b32_e64 v160, v168, v240, s[12:13]
	v_cndmask_b32_e64 v168, v171, v241, s[14:15]
	v_cndmask_b32_e64 v161, v170, v241, s[12:13]
	v_cndmask_b32_e64 v170, v224, v242, s[14:15]
	v_cndmask_b32_e64 v171, v226, v243, s[14:15]
	v_cndmask_b32_e64 v162, v223, v242, s[12:13]
	v_cndmask_b32_e64 v163, v225, v243, s[12:13]
	v_mov_b32_dpp v164, v240 row_ror:14 row_mask:0xf bank_mask:0xf
	v_mov_b32_dpp v165, v241 row_ror:14 row_mask:0xf bank_mask:0xf
	v_mov_b32_dpp v166, v242 row_ror:14 row_mask:0xf bank_mask:0xf
	v_mov_b32_dpp v167, v243 row_ror:14 row_mask:0xf bank_mask:0xf
	v_cndmask_b32_e64 v164, v169, v164, s[12:13]
	v_cndmask_b32_e64 v165, v168, v165, s[12:13]
	v_cndmask_b32_e64 v166, v170, v166, s[12:13]
	v_cndmask_b32_e64 v167, v171, v167, s[12:13]
	s_branch .LBB0_1691
.Lsmp_1_31:
	v_mov_b32_e32 v223, v144
	v_mov_b32_e32 v224, v144
	v_mov_b32_e32 v225, v145
	v_mov_b32_e32 v226, v145
	v_mov_b32_e32 v228, v146
	v_mov_b32_e32 v230, v147
	v_mov_b32_e32 v227, v146
	v_mov_b32_e32 v229, v147
	v_mov_b32_dpp v223, v223 row_ror:1 row_mask:0xf bank_mask:0xf
	v_mov_b32_dpp v224, v224 row_ror:2 row_mask:0xf bank_mask:0xf
	v_mov_b32_dpp v225, v225 row_ror:1 row_mask:0xf bank_mask:0xf
	v_mov_b32_dpp v226, v226 row_ror:2 row_mask:0xf bank_mask:0xf
	v_mov_b32_dpp v228, v228 row_ror:2 row_mask:0xf bank_mask:0xf
	v_mov_b32_dpp v230, v230 row_ror:2 row_mask:0xf bank_mask:0xf
	v_mov_b32_dpp v227, v227 row_ror:1 row_mask:0xf bank_mask:0xf
	v_mov_b32_dpp v229, v229 row_ror:1 row_mask:0xf bank_mask:0xf
	s_waitcnt vmcnt(3)
	v_cndmask_b32_e64 v224, v224, v248, s[14:15]
	v_cndmask_b32_e64 v156, v223, v248, s[12:13]
	v_cndmask_b32_e64 v223, v226, v249, s[14:15]
	v_cndmask_b32_e64 v157, v225, v249, s[12:13]
	v_cndmask_b32_e64 v225, v228, v250, s[14:15]
	v_cndmask_b32_e64 v226, v230, v251, s[14:15]
	v_cndmask_b32_e64 v158, v227, v250, s[12:13]
	v_cndmask_b32_e64 v159, v229, v251, s[12:13]
	v_mov_b32_dpp v168, v248 row_ror:14 row_mask:0xf bank_mask:0xf
	v_mov_b32_dpp v169, v249 row_ror:14 row_mask:0xf bank_mask:0xf
	v_mov_b32_dpp v170, v250 row_ror:14 row_mask:0xf bank_mask:0xf
	v_mov_b32_dpp v171, v251 row_ror:14 row_mask:0xf bank_mask:0xf
	v_cndmask_b32_e64 v168, v224, v168, s[12:13]
	v_cndmask_b32_e64 v169, v223, v169, s[12:13]
	v_cndmask_b32_e64 v170, v225, v170, s[12:13]
	v_cndmask_b32_e64 v171, v226, v171, s[12:13]
	s_mul_i32 s100, s76, 16
	v_lshl_add_u64 v[240:241], v[252:253], 0, s[100:101]
	global_load_dwordx4 v[240:243], v[240:241], off
	v_lshl_add_u64 v[248:249], v[254:255], 0, s[100:101]
	global_load_dwordx4 v[248:251], v[248:249], off offset:3072
	s_branch .LBB0_1695

; template <int N> __device__ __forceinline__ float dpp_ror(float v) { const int i = __builtin_bit_cast(int, v); return __builtin_bit_cast(float, __builtin_amdgcn_update_dpp(i, i, 0x120 + N, 0xF, 0xF, false)); }
;     __device__ __forceinline__ void operator()(const f32x4 (&acc)[2][2][4][2], const pg8::Unit& u, int wr, int wc, int fr, int fq, PG8_LAS unsigned char* xl) const {
;     ...
;                         } else { const int t = fr & 3, b = (row - MP) >> 2;
; #pragma unroll
;                             for (int j = 0; j < 4; ++j) { p1[j] = dpp_ror<1>(cur[j]); p2[j] = dpp_ror<2>(cur[j]); }
;                             const f32x4 c1 = *(const f32x4*)(ctx_s + (size_t)(b * 2 + 1) * FF2 + bj * FF + jc0 + 4 * n), c0 = *(const f32x4*)(ctx_s + (size_t)(b * 2) * FF2 + bj * FF + jc0 + 4 * n);
; #pragma unroll
;                             for (int j = 0; j < 4; ++j) { p2[j] = t == 0 ? c0[j] : (t == 1 ? c1[j] : p2[j]); p1[j] = t == 0 ? c1[j] : p1[j]; }
;                         }
.Lsmp_1_32:
	v_mov_b32_e32 v160, v140
	v_mov_b32_e32 v161, v140
	v_mov_b32_e32 v162, v141
	v_mov_b32_e32 v163, v141
	v_mov_b32_e32 v223, v142
	v_mov_b32_e32 v225, v143
	v_mov_b32_e32 v222, v142
	v_mov_b32_e32 v224, v143
	v_mov_b32_dpp v160, v160 row_ror:1 row_mask:0xf bank_mask:0xf
	v_mov_b32_dpp v161, v161 row_ror:2 row_mask:0xf bank_mask:0xf
	v_mov_b32_dpp v162, v162 row_ror:1 row_mask:0xf bank_mask:0xf
	v_mov_b32_dpp v163, v163 row_ror:2 row_mask:0xf bank_mask:0xf
	v_mov_b32_dpp v223, v223 row_ror:2 row_mask:0xf bank_mask:0xf
	v_mov_b32_dpp v225, v225 row_ror:2 row_mask:0xf bank_mask:0xf
	v_mov_b32_dpp v222, v222 row_ror:1 row_mask:0xf bank_mask:0xf
	v_mov_b32_dpp v224, v224 row_ror:1 row_mask:0xf bank_mask:0xf
	s_waitcnt vmcnt(4)
	v_cndmask_b32_e64 v161, v161, v240, s[14:15]
	v_cndmask_b32_e64 v152, v160, v240, s[12:13]
	v_cndmask_b32_e64 v160, v163, v241, s[14:15]
	v_cndmask_b32_e64 v153, v162, v241, s[12:13]
	v_cndmask_b32_e64 v162, v223, v242, s[14:15]
	v_cndmask_b32_e64 v163, v225, v243, s[14:15]
	v_cndmask_b32_e64 v154, v222, v242, s[12:13]
	v_cndmask_b32_e64 v155, v224, v243, s[12:13]
	v_mov_b32_dpp v156, v240 row_ror:14 row_mask:0xf bank_mask:0xf
	v_mov_b32_dpp v157, v241 row_ror:14 row_mask:0xf bank_mask:0xf
	v_mov_b32_dpp v158, v242 row_ror:14 row_mask:0xf bank_mask:0xf
	v_mov_b32_dpp v159, v243 row_ror:14 row_mask:0xf bank_mask:0xf
	v_cndmask_b32_e64 v156, v161, v156, s[12:13]
	v_cndmask_b32_e64 v157, v160, v157, s[12:13]
	v_cndmask_b32_e64 v158, v162, v158, s[12:13]
	v_cndmask_b32_e64 v159, v163, v159, s[12:13]
	s_branch .LBB0_1701
.Lsmp_1_33:
	v_mov_b32_e32 v222, v136
	v_mov_b32_e32 v223, v136
	v_mov_b32_e32 v224, v137
	v_mov_b32_e32 v225, v137
	v_mov_b32_e32 v227, v138
	v_mov_b32_e32 v229, v139
	v_mov_b32_e32 v226, v138
	v_mov_b32_e32 v228, v139
	v_mov_b32_dpp v222, v222 row_ror:1 row_mask:0xf bank_mask:0xf
	v_mov_b32_dpp v223, v223 row_ror:2 row_mask:0xf bank_mask:0xf
	v_mov_b32_dpp v224, v224 row_ror:1 row_mask:0xf bank_mask:0xf
	v_mov_b32_dpp v225, v225 row_ror:2 row_mask:0xf bank_mask:0xf
	v_mov_b32_dpp v227, v227 row_ror:2 row_mask:0xf bank_mask:0xf
	v_mov_b32_dpp v229, v229 row_ror:2 row_mask:0xf bank_mask:0xf
	v_mov_b32_dpp v226, v226 row_ror:1 row_mask:0xf bank_mask:0xf
	v_mov_b32_dpp v228, v228 row_ror:1 row_mask:0xf bank_mask:0xf
	s_waitcnt vmcnt(3)
	v_cndmask_b32_e64 v223, v223, v248, s[14:15]
	v_cndmask_b32_e64 v148, v222, v248, s[12:13]
	v_cndmask_b32_e64 v222, v225, v249, s[14:15]
	v_cndmask_b32_e64 v149, v224, v249, s[12:13]
	v_cndmask_b32_e64 v224, v227, v250, s[14:15]
	v_cndmask_b32_e64 v225, v229, v251, s[14:15]
	v_cndmask_b32_e64 v150, v226, v250, s[12:13]
	v_cndmask_b32_e64 v151, v228, v251, s[12:13]
	v_mov_b32_dpp v160, v248 row_ror:14 row_mask:0xf bank_mask:0xf
	v_mov_b32_dpp v161, v249 row_ror:14 row_mask:0xf bank_mask:0xf
	v_mov_b32_dpp v162, v250 row_ror:14 row_mask:0xf bank_mask:0xf
	v_mov_b32_dpp v163, v251 row_ror:14 row_mask:0xf bank_mask:0xf
	v_cndmask_b32_e64 v160, v223, v160, s[12:13]
	v_cndmask_b32_e64 v161, v222, v161, s[12:13]
	v_cndmask_b32_e64 v162, v224, v162, s[12:13]
	v_cndmask_b32_e64 v163, v225, v163, s[12:13]
	s_mul_i32 s100, s76, 24
	v_lshl_add_u64 v[240:241], v[252:253], 0, s[100:101]
	global_load_dwordx4 v[240:243], v[240:241], off
	v_lshl_add_u64 v[248:249], v[254:255], 0, s[100:101]
	global_load_dwordx4 v[248:251], v[248:249], off offset:3072
	s_branch .LBB0_1705

; template <int N> __device__ __forceinline__ float dpp_ror(float v) { const int i = __builtin_bit_cast(int, v); return __builtin_bit_cast(float, __builtin_amdgcn_update_dpp(i, i, 0x120 + N, 0xF, 0xF, false)); }
;     __device__ __forceinline__ void operator()(const f32x4 (&acc)[2][2][4][2], const pg8::Unit& u, int wr, int wc, int fr, int fq, PG8_LAS unsigned char* xl) const {
;     ...
;                         } else { const int t = fr & 3, b = (row - MP) >> 2;
; #pragma unroll
;                             for (int j = 0; j < 4; ++j) { p1[j] = dpp_ror<1>(cur[j]); p2[j] = dpp_ror<2>(cur[j]); }
;                             const f32x4 c1 = *(const f32x4*)(ctx_s + (size_t)(b * 2 + 1) * FF2 + bj * FF + jc0 + 4 * n), c0 = *(const f32x4*)(ctx_s + (size_t)(b * 2) * FF2 + bj * FF + jc0 + 4 * n);
; #pragma unroll
;                             for (int j = 0; j < 4; ++j) { p2[j] = t == 0 ? c0[j] : (t == 1 ? c1[j] : p2[j]); p1[j] = t == 0 ? c1[j] : p1[j]; }
;                         }
.Lsmp_1_34:
	v_mov_b32_e32 v152, v132
	v_mov_b32_e32 v153, v132
	v_mov_b32_e32 v154, v133
	v_mov_b32_e32 v155, v133
	v_mov_b32_e32 v222, v134
	v_mov_b32_e32 v224, v135
	v_mov_b32_e32 v171, v134
	v_mov_b32_e32 v223, v135
	v_mov_b32_dpp v152, v152 row_ror:1 row_mask:0xf bank_mask:0xf
	v_mov_b32_dpp v153, v153 row_ror:2 row_mask:0xf bank_mask:0xf
	v_mov_b32_dpp v154, v154 row_ror:1 row_mask:0xf bank_mask:0xf
	v_mov_b32_dpp v155, v155 row_ror:2 row_mask:0xf bank_mask:0xf
	v_mov_b32_dpp v222, v222 row_ror:2 row_mask:0xf bank_mask:0xf
	v_mov_b32_dpp v224, v224 row_ror:2 row_mask:0xf bank_mask:0xf
	v_mov_b32_dpp v171, v171 row_ror:1 row_mask:0xf bank_mask:0xf
	v_mov_b32_dpp v223, v223 row_ror:1 row_mask:0xf bank_mask:0xf
	s_waitcnt vmcnt(4)
	v_cndmask_b32_e64 v153, v153, v240, s[14:15]
	v_cndmask_b32_e64 v144, v152, v240, s[12:13]
	v_cndmask_b32_e64 v152, v155, v241, s[14:15]
	v_cndmask_b32_e64 v145, v154, v241, s[12:13]
	v_cndmask_b32_e64 v154, v222, v242, s[14:15]
	v_cndmask_b32_e64 v155, v224, v243, s[14:15]
	v_cndmask_b32_e64 v146, v171, v242, s[12:13]
	v_cndmask_b32_e64 v147, v223, v243, s[12:13]
	v_mov_b32_dpp v148, v240 row_ror:14 row_mask:0xf bank_mask:0xf
	v_mov_b32_dpp v149, v241 row_ror:14 row_mask:0xf bank_mask:0xf
	v_mov_b32_dpp v150, v242 row_ror:14 row_mask:0xf bank_mask:0xf
	v_mov_b32_dpp v151, v243 row_ror:14 row_mask:0xf bank_mask:0xf
	v_cndmask_b32_e64 v148, v153, v148, s[12:13]
	v_cndmask_b32_e64 v149, v152, v149, s[12:13]
	v_cndmask_b32_e64 v150, v154, v150, s[12:13]
	v_cndmask_b32_e64 v151, v155, v151, s[12:13]
	s_branch .LBB0_1711
.Lsmp_1_35:
	v_mov_b32_e32 v171, v128
	v_mov_b32_e32 v222, v128
	v_mov_b32_e32 v223, v129
	v_mov_b32_e32 v224, v129
	v_mov_b32_e32 v226, v130
	v_mov_b32_e32 v228, v131
	v_mov_b32_e32 v225, v130
	v_mov_b32_e32 v227, v131
	v_mov_b32_dpp v171, v171 row_ror:1 row_mask:0xf bank_mask:0xf
	v_mov_b32_dpp v222, v222 row_ror:2 row_mask:0xf bank_mask:0xf
	v_mov_b32_dpp v223, v223 row_ror:1 row_mask:0xf bank_mask:0xf
	v_mov_b32_dpp v224, v224 row_ror:2 row_mask:0xf bank_mask:0xf
	v_mov_b32_dpp v226, v226 row_ror:2 row_mask:0xf bank_mask:0xf
	v_mov_b32_dpp v228, v228 row_ror:2 row_mask:0xf bank_mask:0xf
	v_mov_b32_dpp v225, v225 row_ror:1 row_mask:0xf bank_mask:0xf
	v_mov_b32_dpp v227, v227 row_ror:1 row_mask:0xf bank_mask:0xf
	s_waitcnt vmcnt(3)
	v_cndmask_b32_e64 v222, v222, v248, s[14:15]
	v_cndmask_b32_e64 v140, v171, v248, s[12:13]
	v_cndmask_b32_e64 v171, v224, v249, s[14:15]
	v_cndmask_b32_e64 v141, v223, v249, s[12:13]
	v_cndmask_b32_e64 v223, v226, v250, s[14:15]
	v_cndmask_b32_e64 v224, v228, v251, s[14:15]
	v_cndmask_b32_e64 v142, v225, v250, s[12:13]
	v_cndmask_b32_e64 v143, v227, v251, s[12:13]
	v_mov_b32_dpp v152, v248 row_ror:14 row_mask:0xf bank_mask:0xf
	v_mov_b32_dpp v153, v249 row_ror:14 row_mask:0xf bank_mask:0xf
	v_mov_b32_dpp v154, v250 row_ror:14 row_mask:0xf bank_mask:0xf
	v_mov_b32_dpp v155, v251 row_ror:14 row_mask:0xf bank_mask:0xf
	v_cndmask_b32_e64 v152, v222, v152, s[12:13]
	v_cndmask_b32_e64 v153, v171, v153, s[12:13]
	v_cndmask_b32_e64 v154, v223, v154, s[12:13]
	v_cndmask_b32_e64 v155, v224, v155, s[12:13]
	s_mul_i32 s100, s76, 64
	v_lshl_add_u64 v[240:241], v[252:253], 0, s[100:101]
	global_load_dwordx4 v[240:243], v[240:241], off
	v_lshl_add_u64 v[248:249], v[254:255], 0, s[100:101]
	global_load_dwordx4 v[248:251], v[248:249], off offset:3072
	s_branch .LBB0_1715

; template <int N> __device__ __forceinline__ float dpp_ror(float v) { const int i = __builtin_bit_cast(int, v); return __builtin_bit_cast(float, __builtin_amdgcn_update_dpp(i, i, 0x120 + N, 0xF, 0xF, false)); }
;     __device__ __forceinline__ void operator()(const f32x4 (&acc)[2][2][4][2], const pg8::Unit& u, int wr, int wc, int fr, int fq, PG8_LAS unsigned char* xl) const {
;     ...
;                         } else { const int t = fr & 3, b = (row - MP) >> 2;
; #pragma unroll
;                             for (int j = 0; j < 4; ++j) { p1[j] = dpp_ror<1>(cur[j]); p2[j] = dpp_ror<2>(cur[j]); }
;                             const f32x4 c1 = *(const f32x4*)(ctx_s + (size_t)(b * 2 + 1) * FF2 + bj * FF + jc0 + 4 * n), c0 = *(const f32x4*)(ctx_s + (size_t)(b * 2) * FF2 + bj * FF + jc0 + 4 * n);
; #pragma unroll
;                             for (int j = 0; j < 4; ++j) { p2[j] = t == 0 ? c0[j] : (t == 1 ? c1[j] : p2[j]); p1[j] = t == 0 ? c1[j] : p1[j]; }
;                         }
.Lsmp_1_36:
	v_mov_b32_e32 v144, v124
	v_mov_b32_e32 v145, v124
	v_mov_b32_e32 v146, v125
	v_mov_b32_e32 v147, v125
	v_mov_b32_e32 v171, v126
	v_mov_b32_e32 v223, v127
	v_mov_b32_e32 v163, v126
	v_mov_b32_e32 v222, v127
	v_mov_b32_dpp v144, v144 row_ror:1 row_mask:0xf bank_mask:0xf
	v_mov_b32_dpp v145, v145 row_ror:2 row_mask:0xf bank_mask:0xf
	v_mov_b32_dpp v146, v146 row_ror:1 row_mask:0xf bank_mask:0xf
	v_mov_b32_dpp v147, v147 row_ror:2 row_mask:0xf bank_mask:0xf
	v_mov_b32_dpp v171, v171 row_ror:2 row_mask:0xf bank_mask:0xf
	v_mov_b32_dpp v223, v223 row_ror:2 row_mask:0xf bank_mask:0xf
	v_mov_b32_dpp v163, v163 row_ror:1 row_mask:0xf bank_mask:0xf
	v_mov_b32_dpp v222, v222 row_ror:1 row_mask:0xf bank_mask:0xf
	s_waitcnt vmcnt(4)
	v_cndmask_b32_e64 v145, v145, v240, s[14:15]
	v_cndmask_b32_e64 v132, v144, v240, s[12:13]
	v_cndmask_b32_e64 v144, v147, v241, s[14:15]
	v_cndmask_b32_e64 v133, v146, v241, s[12:13]
	v_cndmask_b32_e64 v146, v171, v242, s[14:15]
	v_cndmask_b32_e64 v147, v223, v243, s[14:15]
	v_cndmask_b32_e64 v134, v163, v242, s[12:13]
	v_cndmask_b32_e64 v135, v222, v243, s[12:13]
	v_mov_b32_dpp v136, v240 row_ror:14 row_mask:0xf bank_mask:0xf
	v_mov_b32_dpp v137, v241 row_ror:14 row_mask:0xf bank_mask:0xf
	v_mov_b32_dpp v138, v242 row_ror:14 row_mask:0xf bank_mask:0xf
	v_mov_b32_dpp v139, v243 row_ror:14 row_mask:0xf bank_mask:0xf
	v_cndmask_b32_e64 v136, v145, v136, s[12:13]
	v_cndmask_b32_e64 v137, v144, v137, s[12:13]
	v_cndmask_b32_e64 v138, v146, v138, s[12:13]
	v_cndmask_b32_e64 v139, v147, v139, s[12:13]
	s_branch .LBB0_1723
.Lsmp_1_37:
	s_waitcnt lgkmcnt(1)
	v_mov_b32_e32 v163, v88
	v_mov_b32_e32 v171, v88
	v_mov_b32_e32 v222, v89
	v_mov_b32_e32 v223, v89
	v_mov_b32_e32 v225, v90
	v_mov_b32_e32 v227, v91
	v_mov_b32_e32 v224, v90
	v_mov_b32_e32 v226, v91
	v_mov_b32_dpp v163, v163 row_ror:1 row_mask:0xf bank_mask:0xf
	v_mov_b32_dpp v171, v171 row_ror:2 row_mask:0xf bank_mask:0xf
	v_mov_b32_dpp v222, v222 row_ror:1 row_mask:0xf bank_mask:0xf
	v_mov_b32_dpp v223, v223 row_ror:2 row_mask:0xf bank_mask:0xf
	v_mov_b32_dpp v225, v225 row_ror:2 row_mask:0xf bank_mask:0xf
	v_mov_b32_dpp v227, v227 row_ror:2 row_mask:0xf bank_mask:0xf
	v_mov_b32_dpp v224, v224 row_ror:1 row_mask:0xf bank_mask:0xf
	v_mov_b32_dpp v226, v226 row_ror:1 row_mask:0xf bank_mask:0xf
	s_waitcnt vmcnt(3)
	v_cndmask_b32_e64 v171, v171, v248, s[14:15]
	v_cndmask_b32_e64 v140, v163, v248, s[12:13]
	v_cndmask_b32_e64 v163, v223, v249, s[14:15]
	v_cndmask_b32_e64 v141, v222, v249, s[12:13]
	v_cndmask_b32_e64 v222, v225, v250, s[14:15]
	v_cndmask_b32_e64 v223, v227, v251, s[14:15]
	v_cndmask_b32_e64 v142, v224, v250, s[12:13]
	v_cndmask_b32_e64 v143, v226, v251, s[12:13]
	v_mov_b32_dpp v144, v248 row_ror:14 row_mask:0xf bank_mask:0xf
	v_mov_b32_dpp v145, v249 row_ror:14 row_mask:0xf bank_mask:0xf
	v_mov_b32_dpp v146, v250 row_ror:14 row_mask:0xf bank_mask:0xf
	v_mov_b32_dpp v147, v251 row_ror:14 row_mask:0xf bank_mask:0xf
	v_cndmask_b32_e64 v144, v171, v144, s[12:13]
	v_cndmask_b32_e64 v145, v163, v145, s[12:13]
	v_cndmask_b32_e64 v146, v222, v146, s[12:13]
	v_cndmask_b32_e64 v147, v223, v147, s[12:13]
	s_mul_i32 s100, s76, 72
	v_lshl_add_u64 v[240:241], v[252:253], 0, s[100:101]
	global_load_dwordx4 v[240:243], v[240:241], off
	v_lshl_add_u64 v[248:249], v[254:255], 0, s[100:101]
	global_load_dwordx4 v[248:251], v[248:249], off offset:3072
	s_branch .LBB0_1727

; template <int N> __device__ __forceinline__ float dpp_ror(float v) { const int i = __builtin_bit_cast(int, v); return __builtin_bit_cast(float, __builtin_amdgcn_update_dpp(i, i, 0x120 + N, 0xF, 0xF, false)); }
;     __device__ __forceinline__ void operator()(const f32x4 (&acc)[2][2][4][2], const pg8::Unit& u, int wr, int wc, int fr, int fq, PG8_LAS unsigned char* xl) const {
;     ...
;                         const f32x4 cur = acc[ai][bj][m][n]; f32x4 p1, p2;
;                         if (!sample) { const f32x4 prv = (m == 0) ? hb[bj] : acc[ai][bj][m == 0 ? 0 : m - 1][n];
; #pragma unroll
;                             for (int j = 0; j < 4; ++j) { const float s1 = fr == 15 ? prv[j] : cur[j], s2 = fr >= 14 ? prv[j] : cur[j]; p1[j] = dpp_ror<1>(s1); p2[j] = dpp_ror<2>(s2); }
;                         } else { const int t = fr & 3, b = (row - MP) >> 2;
; #pragma unroll
;                             for (int j = 0; j < 4; ++j) { p1[j] = dpp_ror<1>(cur[j]); p2[j] = dpp_ror<2>(cur[j]); }
;                             const f32x4 c1 = *(const f32x4*)(ctx_s + (size_t)(b * 2 + 1) * FF2 + bj * FF + jc0 + 4 * n), c0 = *(const f32x4*)(ctx_s + (size_t)(b * 2) * FF2 + bj * FF + jc0 + 4 * n);
; #pragma unroll
;                             for (int j = 0; j < 4; ++j) { p2[j] = t == 0 ? c0[j] : (t == 1 ? c1[j] : p2[j]); p1[j] = t == 0 ? c1[j] : p1[j]; }
;                         }
;                         cc[bj] = bb[bj] + w0[bj] * p2 + w1[bj] * p1 + w2[bj] * cur;
.Lsmp_1_38:
	v_mov_b32_e32 v136, v84
	v_mov_b32_e32 v137, v84
	v_mov_b32_e32 v138, v85
	v_mov_b32_e32 v139, v85
	v_mov_b32_e32 v163, v86
	v_mov_b32_e32 v222, v87
	v_mov_b32_e32 v155, v86
	v_mov_b32_e32 v171, v87
	v_mov_b32_dpp v136, v136 row_ror:1 row_mask:0xf bank_mask:0xf
	v_mov_b32_dpp v137, v137 row_ror:2 row_mask:0xf bank_mask:0xf
	v_mov_b32_dpp v138, v138 row_ror:1 row_mask:0xf bank_mask:0xf
	v_mov_b32_dpp v139, v139 row_ror:2 row_mask:0xf bank_mask:0xf
	v_mov_b32_dpp v163, v163 row_ror:2 row_mask:0xf bank_mask:0xf
	v_mov_b32_dpp v222, v222 row_ror:2 row_mask:0xf bank_mask:0xf
	v_mov_b32_dpp v155, v155 row_ror:1 row_mask:0xf bank_mask:0xf
	v_mov_b32_dpp v171, v171 row_ror:1 row_mask:0xf bank_mask:0xf
	s_waitcnt vmcnt(4)
	v_cndmask_b32_e64 v137, v137, v240, s[14:15]
	v_cndmask_b32_e64 v128, v136, v240, s[12:13]
	v_cndmask_b32_e64 v136, v139, v241, s[14:15]
	v_cndmask_b32_e64 v129, v138, v241, s[12:13]
	v_cndmask_b32_e64 v138, v163, v242, s[14:15]
	v_cndmask_b32_e64 v139, v222, v243, s[14:15]
	v_cndmask_b32_e64 v130, v155, v242, s[12:13]
	v_cndmask_b32_e64 v131, v171, v243, s[12:13]
	v_mov_b32_dpp v132, v240 row_ror:14 row_mask:0xf bank_mask:0xf
	v_mov_b32_dpp v133, v241 row_ror:14 row_mask:0xf bank_mask:0xf
	v_mov_b32_dpp v134, v242 row_ror:14 row_mask:0xf bank_mask:0xf
	v_mov_b32_dpp v135, v243 row_ror:14 row_mask:0xf bank_mask:0xf
	v_cndmask_b32_e64 v132, v137, v132, s[12:13]
	v_cndmask_b32_e64 v133, v136, v133, s[12:13]
	v_cndmask_b32_e64 v134, v138, v134, s[12:13]
	v_cndmask_b32_e64 v135, v139, v135, s[12:13]
	s_branch .LBB0_1733
.Lsmp_1_39:
	v_mov_b32_e32 v155, v80
	v_mov_b32_e32 v163, v80
	v_mov_b32_e32 v171, v81
	v_mov_b32_e32 v222, v81
	v_mov_b32_e32 v224, v82
	v_mov_b32_e32 v226, v83
	v_mov_b32_e32 v223, v82
	v_mov_b32_e32 v225, v83
	v_mov_b32_dpp v155, v155 row_ror:1 row_mask:0xf bank_mask:0xf
	v_mov_b32_dpp v163, v163 row_ror:2 row_mask:0xf bank_mask:0xf
	v_mov_b32_dpp v171, v171 row_ror:1 row_mask:0xf bank_mask:0xf
	v_mov_b32_dpp v222, v222 row_ror:2 row_mask:0xf bank_mask:0xf
	v_mov_b32_dpp v224, v224 row_ror:2 row_mask:0xf bank_mask:0xf
	v_mov_b32_dpp v226, v226 row_ror:2 row_mask:0xf bank_mask:0xf
	v_mov_b32_dpp v223, v223 row_ror:1 row_mask:0xf bank_mask:0xf
	v_mov_b32_dpp v225, v225 row_ror:1 row_mask:0xf bank_mask:0xf
	s_waitcnt vmcnt(3)
	v_cndmask_b32_e64 v163, v163, v248, s[14:15]
	v_cndmask_b32_e64 v124, v155, v248, s[12:13]
	v_cndmask_b32_e64 v155, v222, v249, s[14:15]
	v_cndmask_b32_e64 v125, v171, v249, s[12:13]
	v_cndmask_b32_e64 v171, v224, v250, s[14:15]
	v_cndmask_b32_e64 v222, v226, v251, s[14:15]
	v_cndmask_b32_e64 v126, v223, v250, s[12:13]
	v_cndmask_b32_e64 v127, v225, v251, s[12:13]
	v_mov_b32_dpp v136, v248 row_ror:14 row_mask:0xf bank_mask:0xf
	v_mov_b32_dpp v137, v249 row_ror:14 row_mask:0xf bank_mask:0xf
	v_mov_b32_dpp v138, v250 row_ror:14 row_mask:0xf bank_mask:0xf
	v_mov_b32_dpp v139, v251 row_ror:14 row_mask:0xf bank_mask:0xf
	v_cndmask_b32_e64 v136, v163, v136, s[12:13]
	v_cndmask_b32_e64 v137, v155, v137, s[12:13]
	v_cndmask_b32_e64 v138, v171, v138, s[12:13]
	v_cndmask_b32_e64 v139, v222, v139, s[12:13]
	s_mul_i32 s100, s76, 80
	v_lshl_add_u64 v[240:241], v[252:253], 0, s[100:101]
	global_load_dwordx4 v[240:243], v[240:241], off
	v_lshl_add_u64 v[248:249], v[254:255], 0, s[100:101]
	global_load_dwordx4 v[248:251], v[248:249], off offset:3072
	s_branch .LBB0_1737

; template <int N> __device__ __forceinline__ float dpp_ror(float v) { const int i = __builtin_bit_cast(int, v); return __builtin_bit_cast(float, __builtin_amdgcn_update_dpp(i, i, 0x120 + N, 0xF, 0xF, false)); }
;     __device__ __forceinline__ void operator()(const f32x4 (&acc)[2][2][4][2], const pg8::Unit& u, int wr, int wc, int fr, int fq, PG8_LAS unsigned char* xl) const {
;     ...
;                         const f32x4 cur = acc[ai][bj][m][n]; f32x4 p1, p2;
;                         if (!sample) { const f32x4 prv = (m == 0) ? hb[bj] : acc[ai][bj][m == 0 ? 0 : m - 1][n];
; #pragma unroll
;                             for (int j = 0; j < 4; ++j) { const float s1 = fr == 15 ? prv[j] : cur[j], s2 = fr >= 14 ? prv[j] : cur[j]; p1[j] = dpp_ror<1>(s1); p2[j] = dpp_ror<2>(s2); }
;                         } else { const int t = fr & 3, b = (row - MP) >> 2;
; #pragma unroll
;                             for (int j = 0; j < 4; ++j) { p1[j] = dpp_ror<1>(cur[j]); p2[j] = dpp_ror<2>(cur[j]); }
;                             const f32x4 c1 = *(const f32x4*)(ctx_s + (size_t)(b * 2 + 1) * FF2 + bj * FF + jc0 + 4 * n), c0 = *(const f32x4*)(ctx_s + (size_t)(b * 2) * FF2 + bj * FF + jc0 + 4 * n);
; #pragma unroll
;                             for (int j = 0; j < 4; ++j) { p2[j] = t == 0 ? c0[j] : (t == 1 ? c1[j] : p2[j]); p1[j] = t == 0 ? c1[j] : p1[j]; }
;                         }
;                         cc[bj] = bb[bj] + w0[bj] * p2 + w1[bj] * p1 + w2[bj] * cur;
.Lsmp_1_41:
	v_mov_b32_e32 v147, v72
	v_mov_b32_e32 v155, v72
	v_mov_b32_e32 v163, v73
	v_mov_b32_e32 v171, v73
	v_mov_b32_e32 v223, v74
	v_mov_b32_e32 v225, v75
	v_mov_b32_e32 v222, v74
	v_mov_b32_e32 v224, v75
	v_mov_b32_dpp v147, v147 row_ror:1 row_mask:0xf bank_mask:0xf
	v_mov_b32_dpp v155, v155 row_ror:2 row_mask:0xf bank_mask:0xf
	v_mov_b32_dpp v163, v163 row_ror:1 row_mask:0xf bank_mask:0xf
	v_mov_b32_dpp v171, v171 row_ror:2 row_mask:0xf bank_mask:0xf
	v_mov_b32_dpp v223, v223 row_ror:2 row_mask:0xf bank_mask:0xf
	v_mov_b32_dpp v225, v225 row_ror:2 row_mask:0xf bank_mask:0xf
	v_mov_b32_dpp v222, v222 row_ror:1 row_mask:0xf bank_mask:0xf
	v_mov_b32_dpp v224, v224 row_ror:1 row_mask:0xf bank_mask:0xf
	s_waitcnt vmcnt(3)
	v_cndmask_b32_e64 v155, v155, v248, s[14:15]
	v_cndmask_b32_e64 v84, v147, v248, s[12:13]
	v_cndmask_b32_e64 v147, v171, v249, s[14:15]
	v_cndmask_b32_e64 v85, v163, v249, s[12:13]
	v_cndmask_b32_e64 v163, v223, v250, s[14:15]
	v_cndmask_b32_e64 v171, v225, v251, s[14:15]
	v_cndmask_b32_e64 v86, v222, v250, s[12:13]
	v_cndmask_b32_e64 v87, v224, v251, s[12:13]
	v_mov_b32_dpp v128, v248 row_ror:14 row_mask:0xf bank_mask:0xf
	v_mov_b32_dpp v129, v249 row_ror:14 row_mask:0xf bank_mask:0xf
	v_mov_b32_dpp v130, v250 row_ror:14 row_mask:0xf bank_mask:0xf
	v_mov_b32_dpp v131, v251 row_ror:14 row_mask:0xf bank_mask:0xf
	v_cndmask_b32_e64 v128, v155, v128, s[12:13]
	v_cndmask_b32_e64 v129, v147, v129, s[12:13]
	v_cndmask_b32_e64 v130, v163, v130, s[12:13]
	v_cndmask_b32_e64 v131, v171, v131, s[12:13]
	s_mul_i32 s100, s76, 88
	v_lshl_add_u64 v[240:241], v[252:253], 0, s[100:101]
	global_load_dwordx4 v[240:243], v[240:241], off
	v_lshl_add_u64 v[248:249], v[254:255], 0, s[100:101]
	global_load_dwordx4 v[248:251], v[248:249], off offset:3072
	s_branch .LBB0_1747

; template <int N> __device__ __forceinline__ float dpp_ror(float v) { const int i = __builtin_bit_cast(int, v); return __builtin_bit_cast(float, __builtin_amdgcn_update_dpp(i, i, 0x120 + N, 0xF, 0xF, false)); }
;     __device__ __forceinline__ void operator()(const f32x4 (&acc)[2][2][4][2], const pg8::Unit& u, int wr, int wc, int fr, int fq, PG8_LAS unsigned char* xl) const {
;     ...
;                         const f32x4 cur = acc[ai][bj][m][n]; f32x4 p1, p2;
;                         if (!sample) { const f32x4 prv = (m == 0) ? hb[bj] : acc[ai][bj][m == 0 ? 0 : m - 1][n];
; #pragma unroll
;                             for (int j = 0; j < 4; ++j) { const float s1 = fr == 15 ? prv[j] : cur[j], s2 = fr >= 14 ? prv[j] : cur[j]; p1[j] = dpp_ror<1>(s1); p2[j] = dpp_ror<2>(s2); }
;                         } else { const int t = fr & 3, b = (row - MP) >> 2;
; #pragma unroll
;                             for (int j = 0; j < 4; ++j) { p1[j] = dpp_ror<1>(cur[j]); p2[j] = dpp_ror<2>(cur[j]); }
;                             const f32x4 c1 = *(const f32x4*)(ctx_s + (size_t)(b * 2 + 1) * FF2 + bj * FF + jc0 + 4 * n), c0 = *(const f32x4*)(ctx_s + (size_t)(b * 2) * FF2 + bj * FF + jc0 + 4 * n);
; #pragma unroll
;                             for (int j = 0; j < 4; ++j) { p2[j] = t == 0 ? c0[j] : (t == 1 ? c1[j] : p2[j]); p1[j] = t == 0 ? c1[j] : p1[j]; }
;                         }
;                         cc[bj] = bb[bj] + w0[bj] * p2 + w1[bj] * p1 + w2[bj] * cur;
.Lsmp_1_43:
	v_mov_b32_e32 v130, v4
	v_mov_b32_e32 v131, v4
	v_mov_b32_e32 v155, v5
	v_mov_b32_e32 v163, v5
	v_mov_b32_e32 v222, v6
	v_mov_b32_e32 v224, v7
	v_mov_b32_e32 v171, v6
	v_mov_b32_e32 v223, v7
	v_mov_b32_dpp v130, v130 row_ror:1 row_mask:0xf bank_mask:0xf
	v_mov_b32_dpp v131, v131 row_ror:2 row_mask:0xf bank_mask:0xf
	v_mov_b32_dpp v155, v155 row_ror:1 row_mask:0xf bank_mask:0xf
	v_mov_b32_dpp v163, v163 row_ror:2 row_mask:0xf bank_mask:0xf
	v_mov_b32_dpp v222, v222 row_ror:2 row_mask:0xf bank_mask:0xf
	v_mov_b32_dpp v224, v224 row_ror:2 row_mask:0xf bank_mask:0xf
	v_mov_b32_dpp v171, v171 row_ror:1 row_mask:0xf bank_mask:0xf
	v_mov_b32_dpp v223, v223 row_ror:1 row_mask:0xf bank_mask:0xf
	s_waitcnt vmcnt(3)
	v_cndmask_b32_e64 v131, v131, v248, s[14:15]
	v_cndmask_b32_e64 v76, v130, v248, s[12:13]
	v_cndmask_b32_e64 v130, v163, v249, s[14:15]
	v_cndmask_b32_e64 v77, v155, v249, s[12:13]
	v_cndmask_b32_e64 v155, v222, v250, s[14:15]
	v_cndmask_b32_e64 v163, v224, v251, s[14:15]
	v_cndmask_b32_e64 v78, v171, v250, s[12:13]
	v_cndmask_b32_e64 v79, v223, v251, s[12:13]
	v_mov_b32_dpp v88, v248 row_ror:14 row_mask:0xf bank_mask:0xf
	v_mov_b32_dpp v89, v249 row_ror:14 row_mask:0xf bank_mask:0xf
	v_mov_b32_dpp v90, v250 row_ror:14 row_mask:0xf bank_mask:0xf
	v_mov_b32_dpp v91, v251 row_ror:14 row_mask:0xf bank_mask:0xf
	v_cndmask_b32_e64 v88, v131, v88, s[12:13]
	v_cndmask_b32_e64 v89, v130, v89, s[12:13]
	v_cndmask_b32_e64 v90, v155, v90, s[12:13]
	v_cndmask_b32_e64 v91, v163, v91, s[12:13]
	s_mov_b32 s100, 0
	v_lshl_add_u64 v[240:241], v[252:253], 0, s[100:101]
	global_load_dwordx4 v[240:243], v[240:241], off offset:16
	v_lshl_add_u64 v[248:249], v[254:255], 0, s[100:101]
	global_load_dwordx4 v[248:251], v[248:249], off offset:3088
	s_branch .LBB0_1757

; template <int N> __device__ __forceinline__ float dpp_ror(float v) { const int i = __builtin_bit_cast(int, v); return __builtin_bit_cast(float, __builtin_amdgcn_update_dpp(i, i, 0x120 + N, 0xF, 0xF, false)); }
;     __device__ __forceinline__ void operator()(const f32x4 (&acc)[2][2][4][2], const pg8::Unit& u, int wr, int wc, int fr, int fq, PG8_LAS unsigned char* xl) const {
;     ...
;                         const f32x4 cur = acc[ai][bj][m][n]; f32x4 p1, p2;
;                         if (!sample) { const f32x4 prv = (m == 0) ? hb[bj] : acc[ai][bj][m == 0 ? 0 : m - 1][n];
; #pragma unroll
;                             for (int j = 0; j < 4; ++j) { const float s1 = fr == 15 ? prv[j] : cur[j], s2 = fr >= 14 ? prv[j] : cur[j]; p1[j] = dpp_ror<1>(s1); p2[j] = dpp_ror<2>(s2); }
;                         } else { const int t = fr & 3, b = (row - MP) >> 2;
; #pragma unroll
;                             for (int j = 0; j < 4; ++j) { p1[j] = dpp_ror<1>(cur[j]); p2[j] = dpp_ror<2>(cur[j]); }
;                             const f32x4 c1 = *(const f32x4*)(ctx_s + (size_t)(b * 2 + 1) * FF2 + bj * FF + jc0 + 4 * n), c0 = *(const f32x4*)(ctx_s + (size_t)(b * 2) * FF2 + bj * FF + jc0 + 4 * n);
; #pragma unroll
;                             for (int j = 0; j < 4; ++j) { p2[j] = t == 0 ? c0[j] : (t == 1 ? c1[j] : p2[j]); p1[j] = t == 0 ? c1[j] : p1[j]; }
;                         }
;                         cc[bj] = bb[bj] + w0[bj] * p2 + w1[bj] * p1 + w2[bj] * cur;
.Lsmp_1_44:
	v_mov_b32_e32 v120, v68
	v_mov_b32_e32 v121, v68
	v_mov_b32_e32 v122, v69
	v_mov_b32_e32 v123, v69
	v_mov_b32_e32 v163, v70
	v_mov_b32_e32 v221, v71
	v_mov_b32_e32 v155, v70
	v_mov_b32_e32 v171, v71
	v_mov_b32_dpp v120, v120 row_ror:1 row_mask:0xf bank_mask:0xf
	v_mov_b32_dpp v121, v121 row_ror:2 row_mask:0xf bank_mask:0xf
	v_mov_b32_dpp v122, v122 row_ror:1 row_mask:0xf bank_mask:0xf
	v_mov_b32_dpp v123, v123 row_ror:2 row_mask:0xf bank_mask:0xf
	v_mov_b32_dpp v163, v163 row_ror:2 row_mask:0xf bank_mask:0xf
	v_mov_b32_dpp v221, v221 row_ror:2 row_mask:0xf bank_mask:0xf
	v_mov_b32_dpp v155, v155 row_ror:1 row_mask:0xf bank_mask:0xf
	v_mov_b32_dpp v171, v171 row_ror:1 row_mask:0xf bank_mask:0xf
	s_waitcnt vmcnt(12)
	v_cndmask_b32_e64 v121, v121, v240, s[14:15]
	v_cndmask_b32_e64 v108, v120, v240, s[12:13]
	v_cndmask_b32_e64 v120, v123, v241, s[14:15]
	v_cndmask_b32_e64 v109, v122, v241, s[12:13]
	v_cndmask_b32_e64 v122, v163, v242, s[14:15]
	v_cndmask_b32_e64 v123, v221, v243, s[14:15]
	v_cndmask_b32_e64 v110, v155, v242, s[12:13]
	v_cndmask_b32_e64 v111, v171, v243, s[12:13]
	v_mov_b32_dpp v112, v240 row_ror:14 row_mask:0xf bank_mask:0xf
	v_mov_b32_dpp v113, v241 row_ror:14 row_mask:0xf bank_mask:0xf
	v_mov_b32_dpp v114, v242 row_ror:14 row_mask:0xf bank_mask:0xf
	v_mov_b32_dpp v115, v243 row_ror:14 row_mask:0xf bank_mask:0xf
	v_cndmask_b32_e64 v112, v121, v112, s[12:13]
	v_cndmask_b32_e64 v113, v120, v113, s[12:13]
	v_cndmask_b32_e64 v114, v122, v114, s[12:13]
	v_cndmask_b32_e64 v115, v123, v115, s[12:13]
	s_branch .LBB0_1765
.Lsmp_1_45:
	s_waitcnt lgkmcnt(1)
	v_mov_b32_e32 v155, v64
	v_mov_b32_e32 v163, v64
	v_mov_b32_e32 v171, v65
	v_mov_b32_e32 v200, v65
	v_mov_b32_e32 v202, v66
	v_mov_b32_e32 v221, v67
	v_mov_b32_e32 v201, v66
	v_mov_b32_e32 v203, v67
	v_mov_b32_dpp v155, v155 row_ror:1 row_mask:0xf bank_mask:0xf
	v_mov_b32_dpp v163, v163 row_ror:2 row_mask:0xf bank_mask:0xf
	v_mov_b32_dpp v171, v171 row_ror:1 row_mask:0xf bank_mask:0xf
	v_mov_b32_dpp v200, v200 row_ror:2 row_mask:0xf bank_mask:0xf
	v_mov_b32_dpp v202, v202 row_ror:2 row_mask:0xf bank_mask:0xf
	v_mov_b32_dpp v221, v221 row_ror:2 row_mask:0xf bank_mask:0xf
	v_mov_b32_dpp v201, v201 row_ror:1 row_mask:0xf bank_mask:0xf
	v_mov_b32_dpp v203, v203 row_ror:1 row_mask:0xf bank_mask:0xf
	s_waitcnt vmcnt(11)
	v_cndmask_b32_e64 v163, v163, v248, s[14:15]
	v_cndmask_b32_e64 v116, v155, v248, s[12:13]
	v_cndmask_b32_e64 v155, v200, v249, s[14:15]
	v_cndmask_b32_e64 v117, v171, v249, s[12:13]
	v_cndmask_b32_e64 v171, v202, v250, s[14:15]
	v_cndmask_b32_e64 v200, v221, v251, s[14:15]
	v_cndmask_b32_e64 v118, v201, v250, s[12:13]
	v_cndmask_b32_e64 v119, v203, v251, s[12:13]
	v_mov_b32_dpp v120, v248 row_ror:14 row_mask:0xf bank_mask:0xf
	v_mov_b32_dpp v121, v249 row_ror:14 row_mask:0xf bank_mask:0xf
	v_mov_b32_dpp v122, v250 row_ror:14 row_mask:0xf bank_mask:0xf
	v_mov_b32_dpp v123, v251 row_ror:14 row_mask:0xf bank_mask:0xf
	v_cndmask_b32_e64 v120, v163, v120, s[12:13]
	v_cndmask_b32_e64 v121, v155, v121, s[12:13]
	v_cndmask_b32_e64 v122, v171, v122, s[12:13]
	v_cndmask_b32_e64 v123, v200, v123, s[12:13]
	s_mul_i32 s100, s76, 8
	v_lshl_add_u64 v[240:241], v[252:253], 0, s[100:101]
	global_load_dwordx4 v[240:243], v[240:241], off offset:16
	v_lshl_add_u64 v[248:249], v[254:255], 0, s[100:101]
	global_load_dwordx4 v[248:251], v[248:249], off offset:3088
	s_branch .LBB0_1769

; template <int N> __device__ __forceinline__ float dpp_ror(float v) { const int i = __builtin_bit_cast(int, v); return __builtin_bit_cast(float, __builtin_amdgcn_update_dpp(i, i, 0x120 + N, 0xF, 0xF, false)); }
;     __device__ __forceinline__ void operator()(const f32x4 (&acc)[2][2][4][2], const pg8::Unit& u, int wr, int wc, int fr, int fq, PG8_LAS unsigned char* xl) const {
;     ...
;                         const f32x4 cur = acc[ai][bj][m][n]; f32x4 p1, p2;
;                         if (!sample) { const f32x4 prv = (m == 0) ? hb[bj] : acc[ai][bj][m == 0 ? 0 : m - 1][n];
; #pragma unroll
;                             for (int j = 0; j < 4; ++j) { const float s1 = fr == 15 ? prv[j] : cur[j], s2 = fr >= 14 ? prv[j] : cur[j]; p1[j] = dpp_ror<1>(s1); p2[j] = dpp_ror<2>(s2); }
;                         } else { const int t = fr & 3, b = (row - MP) >> 2;
; #pragma unroll
;                             for (int j = 0; j < 4; ++j) { p1[j] = dpp_ror<1>(cur[j]); p2[j] = dpp_ror<2>(cur[j]); }
;                             const f32x4 c1 = *(const f32x4*)(ctx_s + (size_t)(b * 2 + 1) * FF2 + bj * FF + jc0 + 4 * n), c0 = *(const f32x4*)(ctx_s + (size_t)(b * 2) * FF2 + bj * FF + jc0 + 4 * n);
; #pragma unroll
;                             for (int j = 0; j < 4; ++j) { p2[j] = t == 0 ? c0[j] : (t == 1 ? c1[j] : p2[j]); p1[j] = t == 0 ? c1[j] : p1[j]; }
;                         }
;                         cc[bj] = bb[bj] + w0[bj] * p2 + w1[bj] * p1 + w2[bj] * cur;
.Lsmp_1_47:
	v_mov_b32_e32 v116, v56
	v_mov_b32_e32 v117, v56
	v_mov_b32_e32 v118, v57
	v_mov_b32_e32 v119, v57
	v_mov_b32_e32 v121, v58
	v_mov_b32_e32 v123, v59
	v_mov_b32_e32 v120, v58
	v_mov_b32_e32 v122, v59
	v_mov_b32_dpp v116, v116 row_ror:1 row_mask:0xf bank_mask:0xf
	v_mov_b32_dpp v117, v117 row_ror:2 row_mask:0xf bank_mask:0xf
	v_mov_b32_dpp v118, v118 row_ror:1 row_mask:0xf bank_mask:0xf
	v_mov_b32_dpp v119, v119 row_ror:2 row_mask:0xf bank_mask:0xf
	v_mov_b32_dpp v121, v121 row_ror:2 row_mask:0xf bank_mask:0xf
	v_mov_b32_dpp v123, v123 row_ror:2 row_mask:0xf bank_mask:0xf
	v_mov_b32_dpp v120, v120 row_ror:1 row_mask:0xf bank_mask:0xf
	v_mov_b32_dpp v122, v122 row_ror:1 row_mask:0xf bank_mask:0xf
	s_waitcnt vmcnt(3)
	v_cndmask_b32_e64 v117, v117, v248, s[14:15]
	v_cndmask_b32_e64 v68, v116, v248, s[12:13]
	v_cndmask_b32_e64 v116, v119, v249, s[14:15]
	v_cndmask_b32_e64 v69, v118, v249, s[12:13]
	v_cndmask_b32_e64 v118, v121, v250, s[14:15]
	v_cndmask_b32_e64 v119, v123, v251, s[14:15]
	v_cndmask_b32_e64 v70, v120, v250, s[12:13]
	v_cndmask_b32_e64 v71, v122, v251, s[12:13]
	v_mov_b32_dpp v112, v248 row_ror:14 row_mask:0xf bank_mask:0xf
	v_mov_b32_dpp v113, v249 row_ror:14 row_mask:0xf bank_mask:0xf
	v_mov_b32_dpp v114, v250 row_ror:14 row_mask:0xf bank_mask:0xf
	v_mov_b32_dpp v115, v251 row_ror:14 row_mask:0xf bank_mask:0xf
	v_cndmask_b32_e64 v112, v117, v112, s[12:13]
	v_cndmask_b32_e64 v113, v116, v113, s[12:13]
	v_cndmask_b32_e64 v114, v118, v114, s[12:13]
	v_cndmask_b32_e64 v115, v119, v115, s[12:13]
	s_mul_i32 s100, s76, 16
	v_lshl_add_u64 v[240:241], v[252:253], 0, s[100:101]
	global_load_dwordx4 v[240:243], v[240:241], off offset:16
	v_lshl_add_u64 v[248:249], v[254:255], 0, s[100:101]
	global_load_dwordx4 v[248:251], v[248:249], off offset:3088
	s_branch .LBB0_1781

; template <int N> __device__ __forceinline__ float dpp_ror(float v) { const int i = __builtin_bit_cast(int, v); return __builtin_bit_cast(float, __builtin_amdgcn_update_dpp(i, i, 0x120 + N, 0xF, 0xF, false)); }
;     __device__ __forceinline__ void operator()(const f32x4 (&acc)[2][2][4][2], const pg8::Unit& u, int wr, int wc, int fr, int fq, PG8_LAS unsigned char* xl) const {
;     ...
;                         const f32x4 cur = acc[ai][bj][m][n]; f32x4 p1, p2;
;                         if (!sample) { const f32x4 prv = (m == 0) ? hb[bj] : acc[ai][bj][m == 0 ? 0 : m - 1][n];
; #pragma unroll
;                             for (int j = 0; j < 4; ++j) { const float s1 = fr == 15 ? prv[j] : cur[j], s2 = fr >= 14 ? prv[j] : cur[j]; p1[j] = dpp_ror<1>(s1); p2[j] = dpp_ror<2>(s2); }
;                         } else { const int t = fr & 3, b = (row - MP) >> 2;
; #pragma unroll
;                             for (int j = 0; j < 4; ++j) { p1[j] = dpp_ror<1>(cur[j]); p2[j] = dpp_ror<2>(cur[j]); }
;                             const f32x4 c1 = *(const f32x4*)(ctx_s + (size_t)(b * 2 + 1) * FF2 + bj * FF + jc0 + 4 * n), c0 = *(const f32x4*)(ctx_s + (size_t)(b * 2) * FF2 + bj * FF + jc0 + 4 * n);
; #pragma unroll
;                             for (int j = 0; j < 4; ++j) { p2[j] = t == 0 ? c0[j] : (t == 1 ? c1[j] : p2[j]); p1[j] = t == 0 ? c1[j] : p1[j]; }
;                         }
;                         cc[bj] = bb[bj] + w0[bj] * p2 + w1[bj] * p1 + w2[bj] * cur;
.Lsmp_1_49:
	v_mov_b32_e32 v108, v48
	v_mov_b32_e32 v109, v48
	v_mov_b32_e32 v110, v49
	v_mov_b32_e32 v111, v49
	v_mov_b32_e32 v113, v50
	v_mov_b32_e32 v115, v51
	v_mov_b32_e32 v112, v50
	v_mov_b32_e32 v114, v51
	v_mov_b32_dpp v108, v108 row_ror:1 row_mask:0xf bank_mask:0xf
	v_mov_b32_dpp v109, v109 row_ror:2 row_mask:0xf bank_mask:0xf
	v_mov_b32_dpp v110, v110 row_ror:1 row_mask:0xf bank_mask:0xf
	v_mov_b32_dpp v111, v111 row_ror:2 row_mask:0xf bank_mask:0xf
	v_mov_b32_dpp v113, v113 row_ror:2 row_mask:0xf bank_mask:0xf
	v_mov_b32_dpp v115, v115 row_ror:2 row_mask:0xf bank_mask:0xf
	v_mov_b32_dpp v112, v112 row_ror:1 row_mask:0xf bank_mask:0xf
	v_mov_b32_dpp v114, v114 row_ror:1 row_mask:0xf bank_mask:0xf
	s_waitcnt vmcnt(3)
	v_cndmask_b32_e64 v109, v109, v248, s[14:15]
	v_cndmask_b32_e64 v60, v108, v248, s[12:13]
	v_cndmask_b32_e64 v108, v111, v249, s[14:15]
	v_cndmask_b32_e64 v61, v110, v249, s[12:13]
	v_cndmask_b32_e64 v110, v113, v250, s[14:15]
	v_cndmask_b32_e64 v111, v115, v251, s[14:15]
	v_cndmask_b32_e64 v62, v112, v250, s[12:13]
	v_cndmask_b32_e64 v63, v114, v251, s[12:13]
	v_mov_b32_dpp v104, v248 row_ror:14 row_mask:0xf bank_mask:0xf
	v_mov_b32_dpp v105, v249 row_ror:14 row_mask:0xf bank_mask:0xf
	v_mov_b32_dpp v106, v250 row_ror:14 row_mask:0xf bank_mask:0xf
	v_mov_b32_dpp v107, v251 row_ror:14 row_mask:0xf bank_mask:0xf
	v_cndmask_b32_e64 v104, v109, v104, s[12:13]
	v_cndmask_b32_e64 v105, v108, v105, s[12:13]
	v_cndmask_b32_e64 v106, v110, v106, s[12:13]
	v_cndmask_b32_e64 v107, v111, v107, s[12:13]
	s_mul_i32 s100, s76, 24
	v_lshl_add_u64 v[240:241], v[252:253], 0, s[100:101]
	global_load_dwordx4 v[240:243], v[240:241], off offset:16
	v_lshl_add_u64 v[248:249], v[254:255], 0, s[100:101]
	global_load_dwordx4 v[248:251], v[248:249], off offset:3088
	s_branch .LBB0_1791

; template <int N> __device__ __forceinline__ float dpp_ror(float v) { const int i = __builtin_bit_cast(int, v); return __builtin_bit_cast(float, __builtin_amdgcn_update_dpp(i, i, 0x120 + N, 0xF, 0xF, false)); }
;     __device__ __forceinline__ void operator()(const f32x4 (&acc)[2][2][4][2], const pg8::Unit& u, int wr, int wc, int fr, int fq, PG8_LAS unsigned char* xl) const {
;     ...
;                         const f32x4 cur = acc[ai][bj][m][n]; f32x4 p1, p2;
;                         if (!sample) { const f32x4 prv = (m == 0) ? hb[bj] : acc[ai][bj][m == 0 ? 0 : m - 1][n];
; #pragma unroll
;                             for (int j = 0; j < 4; ++j) { const float s1 = fr == 15 ? prv[j] : cur[j], s2 = fr >= 14 ? prv[j] : cur[j]; p1[j] = dpp_ror<1>(s1); p2[j] = dpp_ror<2>(s2); }
;                         } else { const int t = fr & 3, b = (row - MP) >> 2;
; #pragma unroll
;                             for (int j = 0; j < 4; ++j) { p1[j] = dpp_ror<1>(cur[j]); p2[j] = dpp_ror<2>(cur[j]); }
;                             const f32x4 c1 = *(const f32x4*)(ctx_s + (size_t)(b * 2 + 1) * FF2 + bj * FF + jc0 + 4 * n), c0 = *(const f32x4*)(ctx_s + (size_t)(b * 2) * FF2 + bj * FF + jc0 + 4 * n);
; #pragma unroll
;                             for (int j = 0; j < 4; ++j) { p2[j] = t == 0 ? c0[j] : (t == 1 ? c1[j] : p2[j]); p1[j] = t == 0 ? c1[j] : p1[j]; }
;                         }
;                         cc[bj] = bb[bj] + w0[bj] * p2 + w1[bj] * p1 + w2[bj] * cur;
.Lsmp_1_51:
	v_mov_b32_e32 v68, v40
	v_mov_b32_e32 v69, v40
	v_mov_b32_e32 v70, v41
	v_mov_b32_e32 v71, v41
	v_mov_b32_e32 v105, v42
	v_mov_b32_e32 v107, v43
	v_mov_b32_e32 v104, v42
	v_mov_b32_e32 v106, v43
	v_mov_b32_dpp v68, v68 row_ror:1 row_mask:0xf bank_mask:0xf
	v_mov_b32_dpp v69, v69 row_ror:2 row_mask:0xf bank_mask:0xf
	v_mov_b32_dpp v70, v70 row_ror:1 row_mask:0xf bank_mask:0xf
	v_mov_b32_dpp v71, v71 row_ror:2 row_mask:0xf bank_mask:0xf
	v_mov_b32_dpp v105, v105 row_ror:2 row_mask:0xf bank_mask:0xf
	v_mov_b32_dpp v107, v107 row_ror:2 row_mask:0xf bank_mask:0xf
	v_mov_b32_dpp v104, v104 row_ror:1 row_mask:0xf bank_mask:0xf
	v_mov_b32_dpp v106, v106 row_ror:1 row_mask:0xf bank_mask:0xf
	s_waitcnt vmcnt(3)
	v_cndmask_b32_e64 v69, v69, v248, s[14:15]
	v_cndmask_b32_e64 v52, v68, v248, s[12:13]
	v_cndmask_b32_e64 v68, v71, v249, s[14:15]
	v_cndmask_b32_e64 v53, v70, v249, s[12:13]
	v_cndmask_b32_e64 v70, v105, v250, s[14:15]
	v_cndmask_b32_e64 v71, v107, v251, s[14:15]
	v_cndmask_b32_e64 v54, v104, v250, s[12:13]
	v_cndmask_b32_e64 v55, v106, v251, s[12:13]
	v_mov_b32_dpp v64, v248 row_ror:14 row_mask:0xf bank_mask:0xf
	v_mov_b32_dpp v65, v249 row_ror:14 row_mask:0xf bank_mask:0xf
	v_mov_b32_dpp v66, v250 row_ror:14 row_mask:0xf bank_mask:0xf
	v_mov_b32_dpp v67, v251 row_ror:14 row_mask:0xf bank_mask:0xf
	v_cndmask_b32_e64 v64, v69, v64, s[12:13]
	v_cndmask_b32_e64 v65, v68, v65, s[12:13]
	v_cndmask_b32_e64 v66, v70, v66, s[12:13]
	v_cndmask_b32_e64 v67, v71, v67, s[12:13]
	s_mul_i32 s100, s76, 64
	v_lshl_add_u64 v[240:241], v[252:253], 0, s[100:101]
	global_load_dwordx4 v[240:243], v[240:241], off offset:16
	v_lshl_add_u64 v[248:249], v[254:255], 0, s[100:101]
	global_load_dwordx4 v[248:251], v[248:249], off offset:3088
	s_branch .LBB0_1801

; template <int N> __device__ __forceinline__ float dpp_ror(float v) { const int i = __builtin_bit_cast(int, v); return __builtin_bit_cast(float, __builtin_amdgcn_update_dpp(i, i, 0x120 + N, 0xF, 0xF, false)); }
;     __device__ __forceinline__ void operator()(const f32x4 (&acc)[2][2][4][2], const pg8::Unit& u, int wr, int wc, int fr, int fq, PG8_LAS unsigned char* xl) const {
;     ...
;                         const f32x4 cur = acc[ai][bj][m][n]; f32x4 p1, p2;
;                         if (!sample) { const f32x4 prv = (m == 0) ? hb[bj] : acc[ai][bj][m == 0 ? 0 : m - 1][n];
; #pragma unroll
;                             for (int j = 0; j < 4; ++j) { const float s1 = fr == 15 ? prv[j] : cur[j], s2 = fr >= 14 ? prv[j] : cur[j]; p1[j] = dpp_ror<1>(s1); p2[j] = dpp_ror<2>(s2); }
;                         } else { const int t = fr & 3, b = (row - MP) >> 2;
; #pragma unroll
;                             for (int j = 0; j < 4; ++j) { p1[j] = dpp_ror<1>(cur[j]); p2[j] = dpp_ror<2>(cur[j]); }
;                             const f32x4 c1 = *(const f32x4*)(ctx_s + (size_t)(b * 2 + 1) * FF2 + bj * FF + jc0 + 4 * n), c0 = *(const f32x4*)(ctx_s + (size_t)(b * 2) * FF2 + bj * FF + jc0 + 4 * n);
; #pragma unroll
;                             for (int j = 0; j < 4; ++j) { p2[j] = t == 0 ? c0[j] : (t == 1 ? c1[j] : p2[j]); p1[j] = t == 0 ? c1[j] : p1[j]; }
;                         }
;                         cc[bj] = bb[bj] + w0[bj] * p2 + w1[bj] * p1 + w2[bj] * cur;
.Lsmp_1_53:
	s_waitcnt lgkmcnt(1)
	v_mov_b32_e32 v60, v32
	v_mov_b32_e32 v61, v32
	v_mov_b32_e32 v62, v33
	v_mov_b32_e32 v63, v33
	v_mov_b32_e32 v65, v34
	v_mov_b32_e32 v67, v35
	v_mov_b32_e32 v64, v34
	v_mov_b32_e32 v66, v35
	v_mov_b32_dpp v60, v60 row_ror:1 row_mask:0xf bank_mask:0xf
	v_mov_b32_dpp v61, v61 row_ror:2 row_mask:0xf bank_mask:0xf
	v_mov_b32_dpp v62, v62 row_ror:1 row_mask:0xf bank_mask:0xf
	v_mov_b32_dpp v63, v63 row_ror:2 row_mask:0xf bank_mask:0xf
	v_mov_b32_dpp v65, v65 row_ror:2 row_mask:0xf bank_mask:0xf
	v_mov_b32_dpp v67, v67 row_ror:2 row_mask:0xf bank_mask:0xf
	v_mov_b32_dpp v64, v64 row_ror:1 row_mask:0xf bank_mask:0xf
	v_mov_b32_dpp v66, v66 row_ror:1 row_mask:0xf bank_mask:0xf
	s_waitcnt vmcnt(3)
	v_cndmask_b32_e64 v61, v61, v248, s[14:15]
	v_cndmask_b32_e64 v52, v60, v248, s[12:13]
	v_cndmask_b32_e64 v60, v63, v249, s[14:15]
	v_cndmask_b32_e64 v53, v62, v249, s[12:13]
	v_cndmask_b32_e64 v62, v65, v250, s[14:15]
	v_cndmask_b32_e64 v63, v67, v251, s[14:15]
	v_cndmask_b32_e64 v54, v64, v250, s[12:13]
	v_cndmask_b32_e64 v55, v66, v251, s[12:13]
	v_mov_b32_dpp v56, v248 row_ror:14 row_mask:0xf bank_mask:0xf
	v_mov_b32_dpp v57, v249 row_ror:14 row_mask:0xf bank_mask:0xf
	v_mov_b32_dpp v58, v250 row_ror:14 row_mask:0xf bank_mask:0xf
	v_mov_b32_dpp v59, v251 row_ror:14 row_mask:0xf bank_mask:0xf
	v_cndmask_b32_e64 v56, v61, v56, s[12:13]
	v_cndmask_b32_e64 v57, v60, v57, s[12:13]
	v_cndmask_b32_e64 v58, v62, v58, s[12:13]
	v_cndmask_b32_e64 v59, v63, v59, s[12:13]
	s_mul_i32 s100, s76, 72
	v_lshl_add_u64 v[240:241], v[252:253], 0, s[100:101]
	global_load_dwordx4 v[240:243], v[240:241], off offset:16
	v_lshl_add_u64 v[248:249], v[254:255], 0, s[100:101]
	global_load_dwordx4 v[248:251], v[248:249], off offset:3088
	s_branch .LBB0_1813

; template <int N> __device__ __forceinline__ float dpp_ror(float v) { const int i = __builtin_bit_cast(int, v); return __builtin_bit_cast(float, __builtin_amdgcn_update_dpp(i, i, 0x120 + N, 0xF, 0xF, false)); }
;     __device__ __forceinline__ void operator()(const f32x4 (&acc)[2][2][4][2], const pg8::Unit& u, int wr, int wc, int fr, int fq, PG8_LAS unsigned char* xl) const {
;     ...
;                         const f32x4 cur = acc[ai][bj][m][n]; f32x4 p1, p2;
;                         if (!sample) { const f32x4 prv = (m == 0) ? hb[bj] : acc[ai][bj][m == 0 ? 0 : m - 1][n];
; #pragma unroll
;                             for (int j = 0; j < 4; ++j) { const float s1 = fr == 15 ? prv[j] : cur[j], s2 = fr >= 14 ? prv[j] : cur[j]; p1[j] = dpp_ror<1>(s1); p2[j] = dpp_ror<2>(s2); }
;                         } else { const int t = fr & 3, b = (row - MP) >> 2;
; #pragma unroll
;                             for (int j = 0; j < 4; ++j) { p1[j] = dpp_ror<1>(cur[j]); p2[j] = dpp_ror<2>(cur[j]); }
;                             const f32x4 c1 = *(const f32x4*)(ctx_s + (size_t)(b * 2 + 1) * FF2 + bj * FF + jc0 + 4 * n), c0 = *(const f32x4*)(ctx_s + (size_t)(b * 2) * FF2 + bj * FF + jc0 + 4 * n);
; #pragma unroll
;                             for (int j = 0; j < 4; ++j) { p2[j] = t == 0 ? c0[j] : (t == 1 ? c1[j] : p2[j]); p1[j] = t == 0 ? c1[j] : p1[j]; }
;                         }
;                         cc[bj] = bb[bj] + w0[bj] * p2 + w1[bj] * p1 + w2[bj] * cur;
.Lsmp_1_55:
	v_mov_b32_e32 v52, v24
	v_mov_b32_e32 v53, v24
	v_mov_b32_e32 v54, v25
	v_mov_b32_e32 v55, v25
	v_mov_b32_e32 v57, v26
	v_mov_b32_e32 v59, v27
	v_mov_b32_e32 v56, v26
	v_mov_b32_e32 v58, v27
	v_mov_b32_dpp v52, v52 row_ror:1 row_mask:0xf bank_mask:0xf
	v_mov_b32_dpp v53, v53 row_ror:2 row_mask:0xf bank_mask:0xf
	v_mov_b32_dpp v54, v54 row_ror:1 row_mask:0xf bank_mask:0xf
	v_mov_b32_dpp v55, v55 row_ror:2 row_mask:0xf bank_mask:0xf
	v_mov_b32_dpp v57, v57 row_ror:2 row_mask:0xf bank_mask:0xf
	v_mov_b32_dpp v59, v59 row_ror:2 row_mask:0xf bank_mask:0xf
	v_mov_b32_dpp v56, v56 row_ror:1 row_mask:0xf bank_mask:0xf
	v_mov_b32_dpp v58, v58 row_ror:1 row_mask:0xf bank_mask:0xf
	s_waitcnt vmcnt(3)
	v_cndmask_b32_e64 v53, v53, v248, s[14:15]
	v_cndmask_b32_e64 v36, v52, v248, s[12:13]
	v_cndmask_b32_e64 v52, v55, v249, s[14:15]
	v_cndmask_b32_e64 v37, v54, v249, s[12:13]
	v_cndmask_b32_e64 v54, v57, v250, s[14:15]
	v_cndmask_b32_e64 v55, v59, v251, s[14:15]
	v_cndmask_b32_e64 v38, v56, v250, s[12:13]
	v_cndmask_b32_e64 v39, v58, v251, s[12:13]
	v_mov_b32_dpp v48, v248 row_ror:14 row_mask:0xf bank_mask:0xf
	v_mov_b32_dpp v49, v249 row_ror:14 row_mask:0xf bank_mask:0xf
	v_mov_b32_dpp v50, v250 row_ror:14 row_mask:0xf bank_mask:0xf
	v_mov_b32_dpp v51, v251 row_ror:14 row_mask:0xf bank_mask:0xf
	v_cndmask_b32_e64 v48, v53, v48, s[12:13]
	v_cndmask_b32_e64 v49, v52, v49, s[12:13]
	v_cndmask_b32_e64 v50, v54, v50, s[12:13]
	v_cndmask_b32_e64 v51, v55, v51, s[12:13]
	s_mul_i32 s100, s76, 80
	v_lshl_add_u64 v[240:241], v[252:253], 0, s[100:101]
	global_load_dwordx4 v[240:243], v[240:241], off offset:16
	v_lshl_add_u64 v[248:249], v[254:255], 0, s[100:101]
	global_load_dwordx4 v[248:251], v[248:249], off offset:3088
	s_branch .LBB0_1823

; template <int N> __device__ __forceinline__ float dpp_ror(float v) { const int i = __builtin_bit_cast(int, v); return __builtin_bit_cast(float, __builtin_amdgcn_update_dpp(i, i, 0x120 + N, 0xF, 0xF, false)); }
;     __device__ __forceinline__ void operator()(const f32x4 (&acc)[2][2][4][2], const pg8::Unit& u, int wr, int wc, int fr, int fq, PG8_LAS unsigned char* xl) const {
;     ...
;                         const f32x4 cur = acc[ai][bj][m][n]; f32x4 p1, p2;
;                         if (!sample) { const f32x4 prv = (m == 0) ? hb[bj] : acc[ai][bj][m == 0 ? 0 : m - 1][n];
; #pragma unroll
;                             for (int j = 0; j < 4; ++j) { const float s1 = fr == 15 ? prv[j] : cur[j], s2 = fr >= 14 ? prv[j] : cur[j]; p1[j] = dpp_ror<1>(s1); p2[j] = dpp_ror<2>(s2); }
;                         } else { const int t = fr & 3, b = (row - MP) >> 2;
; #pragma unroll
;                             for (int j = 0; j < 4; ++j) { p1[j] = dpp_ror<1>(cur[j]); p2[j] = dpp_ror<2>(cur[j]); }
;                             const f32x4 c1 = *(const f32x4*)(ctx_s + (size_t)(b * 2 + 1) * FF2 + bj * FF + jc0 + 4 * n), c0 = *(const f32x4*)(ctx_s + (size_t)(b * 2) * FF2 + bj * FF + jc0 + 4 * n);
; #pragma unroll
;                             for (int j = 0; j < 4; ++j) { p2[j] = t == 0 ? c0[j] : (t == 1 ? c1[j] : p2[j]); p1[j] = t == 0 ? c1[j] : p1[j]; }
;                         }
;                         cc[bj] = bb[bj] + w0[bj] * p2 + w1[bj] * p1 + w2[bj] * cur;
.Lsmp_1_57:
	v_mov_b32_e32 v44, v16
	v_mov_b32_e32 v45, v16
	v_mov_b32_e32 v46, v17
	v_mov_b32_e32 v47, v17
	v_mov_b32_e32 v49, v18
	v_mov_b32_e32 v51, v19
	v_mov_b32_e32 v48, v18
	v_mov_b32_e32 v50, v19
	v_mov_b32_dpp v44, v44 row_ror:1 row_mask:0xf bank_mask:0xf
	v_mov_b32_dpp v45, v45 row_ror:2 row_mask:0xf bank_mask:0xf
	v_mov_b32_dpp v46, v46 row_ror:1 row_mask:0xf bank_mask:0xf
	v_mov_b32_dpp v47, v47 row_ror:2 row_mask:0xf bank_mask:0xf
	v_mov_b32_dpp v49, v49 row_ror:2 row_mask:0xf bank_mask:0xf
	v_mov_b32_dpp v51, v51 row_ror:2 row_mask:0xf bank_mask:0xf
	v_mov_b32_dpp v48, v48 row_ror:1 row_mask:0xf bank_mask:0xf
	v_mov_b32_dpp v50, v50 row_ror:1 row_mask:0xf bank_mask:0xf
	s_waitcnt vmcnt(3)
	v_cndmask_b32_e64 v45, v45, v248, s[14:15]
	v_cndmask_b32_e64 v28, v44, v248, s[12:13]
	v_cndmask_b32_e64 v44, v47, v249, s[14:15]
	v_cndmask_b32_e64 v29, v46, v249, s[12:13]
	v_cndmask_b32_e64 v46, v49, v250, s[14:15]
	v_cndmask_b32_e64 v47, v51, v251, s[14:15]
	v_cndmask_b32_e64 v30, v48, v250, s[12:13]
	v_cndmask_b32_e64 v31, v50, v251, s[12:13]
	v_mov_b32_dpp v40, v248 row_ror:14 row_mask:0xf bank_mask:0xf
	v_mov_b32_dpp v41, v249 row_ror:14 row_mask:0xf bank_mask:0xf
	v_mov_b32_dpp v42, v250 row_ror:14 row_mask:0xf bank_mask:0xf
	v_mov_b32_dpp v43, v251 row_ror:14 row_mask:0xf bank_mask:0xf
	v_cndmask_b32_e64 v40, v45, v40, s[12:13]
	v_cndmask_b32_e64 v41, v44, v41, s[12:13]
	v_cndmask_b32_e64 v42, v46, v42, s[12:13]
	v_cndmask_b32_e64 v43, v47, v43, s[12:13]
	s_mul_i32 s100, s76, 88
	v_lshl_add_u64 v[240:241], v[252:253], 0, s[100:101]
	global_load_dwordx4 v[240:243], v[240:241], off offset:16
	v_lshl_add_u64 v[248:249], v[254:255], 0, s[100:101]
	global_load_dwordx4 v[248:251], v[248:249], off offset:3088
	s_branch .LBB0_1833

; template <int N> __device__ __forceinline__ float dpp_ror(float v) { const int i = __builtin_bit_cast(int, v); return __builtin_bit_cast(float, __builtin_amdgcn_update_dpp(i, i, 0x120 + N, 0xF, 0xF, false)); }
;     __device__ __forceinline__ void operator()(const f32x4 (&acc)[2][2][4][2], const pg8::Unit& u, int wr, int wc, int fr, int fq, PG8_LAS unsigned char* xl) const {
;     ...
;                         const f32x4 cur = acc[ai][bj][m][n]; f32x4 p1, p2;
;                         if (!sample) { const f32x4 prv = (m == 0) ? hb[bj] : acc[ai][bj][m == 0 ? 0 : m - 1][n];
; #pragma unroll
;                             for (int j = 0; j < 4; ++j) { const float s1 = fr == 15 ? prv[j] : cur[j], s2 = fr >= 14 ? prv[j] : cur[j]; p1[j] = dpp_ror<1>(s1); p2[j] = dpp_ror<2>(s2); }
;                         } else { const int t = fr & 3, b = (row - MP) >> 2;
; #pragma unroll
;                             for (int j = 0; j < 4; ++j) { p1[j] = dpp_ror<1>(cur[j]); p2[j] = dpp_ror<2>(cur[j]); }
;                             const f32x4 c1 = *(const f32x4*)(ctx_s + (size_t)(b * 2 + 1) * FF2 + bj * FF + jc0 + 4 * n), c0 = *(const f32x4*)(ctx_s + (size_t)(b * 2) * FF2 + bj * FF + jc0 + 4 * n);
; #pragma unroll
;                             for (int j = 0; j < 4; ++j) { p2[j] = t == 0 ? c0[j] : (t == 1 ? c1[j] : p2[j]); p1[j] = t == 0 ? c1[j] : p1[j]; }
;                         }
;                         cc[bj] = bb[bj] + w0[bj] * p2 + w1[bj] * p1 + w2[bj] * cur;
.Lsmp1_1_0:
	v_or_b32_e32 v166, 1, v164
	v_mov_b64_e32 v[164:165], s[48:49]
	v_mad_i64_i32 v[166:167], vcc, v166, s76, v[164:165]
	v_mad_i64_i32 v[164:165], vcc, v220, s76, v[164:165]
	v_lshl_add_u64 v[202:203], v[166:167], 0, v[198:199]
	v_lshl_add_u64 v[200:201], v[164:165], 0, v[198:199]
	s_or_b64 vcc, s[12:13], s[14:15]
	s_mov_b32 s101, 0
	v_cndmask_b32_e32 v252, v200, v202, vcc
	v_cndmask_b32_e32 v253, v201, v203, vcc
	s_movk_i32 s100, 0x2000
	global_load_dwordx4 v[240:243], v[252:253], off
	v_lshl_add_u64 v[254:255], v[252:253], 0, s[100:101]
	global_load_dwordx4 v[248:251], v[254:255], off offset:3072
	v_mov_b32_e32 v176, v156
	v_mov_b32_e32 v177, v156
	v_mov_b32_e32 v178, v157
	v_mov_b32_e32 v179, v157
	v_mov_b32_e32 v223, v158
	v_mov_b32_e32 v225, v159
	v_mov_b32_e32 v222, v158
	v_mov_b32_e32 v224, v159
	v_mov_b32_dpp v176, v176 row_ror:1 row_mask:0xf bank_mask:0xf
	v_mov_b32_dpp v177, v177 row_ror:2 row_mask:0xf bank_mask:0xf
	v_mov_b32_dpp v178, v178 row_ror:1 row_mask:0xf bank_mask:0xf
	v_mov_b32_dpp v179, v179 row_ror:2 row_mask:0xf bank_mask:0xf
	v_mov_b32_dpp v223, v223 row_ror:2 row_mask:0xf bank_mask:0xf
	v_mov_b32_dpp v225, v225 row_ror:2 row_mask:0xf bank_mask:0xf
	v_mov_b32_dpp v222, v222 row_ror:1 row_mask:0xf bank_mask:0xf
	v_mov_b32_dpp v224, v224 row_ror:1 row_mask:0xf bank_mask:0xf
	s_mov_b64 s[6:7], 0
	s_waitcnt vmcnt(1)
	v_cndmask_b32_e64 v177, v177, v240, s[14:15]
	v_cndmask_b32_e64 v164, v176, v240, s[12:13]
	v_cndmask_b32_e64 v176, v179, v241, s[14:15]
	v_cndmask_b32_e64 v165, v178, v241, s[12:13]
	v_cndmask_b32_e64 v178, v223, v242, s[14:15]
	v_cndmask_b32_e64 v179, v225, v243, s[14:15]
	v_cndmask_b32_e64 v166, v222, v242, s[12:13]
	v_cndmask_b32_e64 v167, v224, v243, s[12:13]
	v_mov_b32_dpp v168, v240 row_ror:14 row_mask:0xf bank_mask:0xf
	v_mov_b32_dpp v169, v241 row_ror:14 row_mask:0xf bank_mask:0xf
	v_mov_b32_dpp v170, v242 row_ror:14 row_mask:0xf bank_mask:0xf
	v_mov_b32_dpp v171, v243 row_ror:14 row_mask:0xf bank_mask:0xf
	v_cndmask_b32_e64 v168, v177, v168, s[12:13]
	v_cndmask_b32_e64 v169, v176, v169, s[12:13]
	v_cndmask_b32_e64 v170, v178, v170, s[12:13]
	v_cndmask_b32_e64 v171, v179, v171, s[12:13]
	s_branch .LBB0_1679
.Lsmp1_1_1:
	v_mov_b32_e32 v222, v152
	v_mov_b32_e32 v223, v152
	v_mov_b32_e32 v224, v153
	v_mov_b32_e32 v225, v153
	v_mov_b32_e32 v227, v154
	v_mov_b32_e32 v229, v155
	v_mov_b32_e32 v226, v154
	v_mov_b32_e32 v228, v155
	v_mov_b32_dpp v222, v222 row_ror:1 row_mask:0xf bank_mask:0xf
	v_mov_b32_dpp v223, v223 row_ror:2 row_mask:0xf bank_mask:0xf
	v_mov_b32_dpp v224, v224 row_ror:1 row_mask:0xf bank_mask:0xf
	v_mov_b32_dpp v225, v225 row_ror:2 row_mask:0xf bank_mask:0xf
	v_mov_b32_dpp v227, v227 row_ror:2 row_mask:0xf bank_mask:0xf
	v_mov_b32_dpp v229, v229 row_ror:2 row_mask:0xf bank_mask:0xf
	v_mov_b32_dpp v226, v226 row_ror:1 row_mask:0xf bank_mask:0xf
	v_mov_b32_dpp v228, v228 row_ror:1 row_mask:0xf bank_mask:0xf
	s_mov_b64 s[6:7], 0
	s_waitcnt vmcnt(0)
	v_cndmask_b32_e64 v223, v223, v248, s[14:15]
	v_cndmask_b32_e64 v172, v222, v248, s[12:13]
	v_cndmask_b32_e64 v222, v225, v249, s[14:15]
	v_cndmask_b32_e64 v173, v224, v249, s[12:13]
	v_cndmask_b32_e64 v224, v227, v250, s[14:15]
	v_cndmask_b32_e64 v225, v229, v251, s[14:15]
	v_cndmask_b32_e64 v174, v226, v250, s[12:13]
	v_cndmask_b32_e64 v175, v228, v251, s[12:13]
	v_mov_b32_dpp v176, v248 row_ror:14 row_mask:0xf bank_mask:0xf
	v_mov_b32_dpp v177, v249 row_ror:14 row_mask:0xf bank_mask:0xf
	v_mov_b32_dpp v178, v250 row_ror:14 row_mask:0xf bank_mask:0xf
	v_mov_b32_dpp v179, v251 row_ror:14 row_mask:0xf bank_mask:0xf
	v_cndmask_b32_e64 v176, v223, v176, s[12:13]
	v_cndmask_b32_e64 v177, v222, v177, s[12:13]
	v_cndmask_b32_e64 v178, v224, v178, s[12:13]
	v_cndmask_b32_e64 v179, v225, v179, s[12:13]
	s_mul_i32 s100, s76, 8
	v_lshl_add_u64 v[240:241], v[252:253], 0, s[100:101]
	global_load_dwordx4 v[240:243], v[240:241], off
	v_lshl_add_u64 v[248:249], v[254:255], 0, s[100:101]
	global_load_dwordx4 v[248:251], v[248:249], off offset:3072
	s_branch .LBB0_1683

; __global__ void __launch_bounds__(512, 2) fwd_megakernel(Args a_unused) {
	.amdhsa_kernel _Z14fwd_megakernel4Args
		.amdhsa_group_segment_fixed_size 0
		.amdhsa_private_segment_fixed_size 0
		.amdhsa_kernarg_size 432
		.amdhsa_user_sgpr_count 2
		.amdhsa_user_sgpr_dispatch_ptr 0
		.amdhsa_user_sgpr_queue_ptr 0
		.amdhsa_user_sgpr_kernarg_segment_ptr 1
		.amdhsa_user_sgpr_dispatch_id 0
		.amdhsa_user_sgpr_kernarg_preload_length 0
		.amdhsa_user_sgpr_kernarg_preload_offset 0
		.amdhsa_user_sgpr_private_segment_size 0
		.amdhsa_uses_dynamic_stack 0
		.amdhsa_enable_private_segment 0
		.amdhsa_system_sgpr_workgroup_id_x 1
		.amdhsa_system_sgpr_workgroup_id_y 0
		.amdhsa_system_sgpr_workgroup_id_z 0
		.amdhsa_system_sgpr_workgroup_info 0
		.amdhsa_system_vgpr_workitem_id 2
		.amdhsa_next_free_vgpr 256
		.amdhsa_next_free_sgpr 102
		.amdhsa_accum_offset 256
		.amdhsa_reserve_vcc 1
		.amdhsa_float_round_mode_32 0
		.amdhsa_float_round_mode_16_64 0
		.amdhsa_float_denorm_mode_32 3
		.amdhsa_float_denorm_mode_16_64 3
		.amdhsa_dx10_clamp 1
		.amdhsa_ieee_mode 1
		.amdhsa_fp16_overflow 0
		.amdhsa_tg_split 0
		.amdhsa_exception_fp_ieee_invalid_op 0
		.amdhsa_exception_fp_denorm_src 0
		.amdhsa_exception_fp_ieee_div_zero 0
		.amdhsa_exception_fp_ieee_overflow 0
		.amdhsa_exception_fp_ieee_underflow 0
		.amdhsa_exception_fp_ieee_inexact 0
		.amdhsa_exception_int_div_zero 0
	.end_amdhsa_kernel

; __global__ void __launch_bounds__(512, 2) fwd_megakernel(Args a_unused) {
amdhsa.kernels:
  - .agpr_count:     0
    .args:
      - .offset:         0
        .size:           176
        .value_kind:     by_value
      - .offset:         176
        .size:           4
        .value_kind:     hidden_block_count_x
      - .offset:         180
        .size:           4
        .value_kind:     hidden_block_count_y
      - .offset:         184
        .size:           4
        .value_kind:     hidden_block_count_z
      - .offset:         188
        .size:           2
        .value_kind:     hidden_group_size_x
      - .offset:         190
        .size:           2
        .value_kind:     hidden_group_size_y
      - .offset:         192
        .size:           2
        .value_kind:     hidden_group_size_z
      - .offset:         194
        .size:           2
        .value_kind:     hidden_remainder_x
      - .offset:         196
        .size:           2
        .value_kind:     hidden_remainder_y
      - .offset:         198
        .size:           2
        .value_kind:     hidden_remainder_z
      - .offset:         216
        .size:           8
        .value_kind:     hidden_global_offset_x
      - .offset:         224
        .size:           8
        .value_kind:     hidden_global_offset_y
      - .offset:         232
        .size:           8
        .value_kind:     hidden_global_offset_z
      - .offset:         240
        .size:           2
        .value_kind:     hidden_grid_dims
      - .offset:         264
        .size:           8
        .value_kind:     hidden_multigrid_sync_arg
      - .offset:         296
        .size:           4
        .value_kind:     hidden_dynamic_lds_size
    .group_segment_fixed_size: 0
    .kernarg_segment_align: 8
    .kernarg_segment_size: 432
    .language:       OpenCL C
    .language_version:
      - 2
      - 0
    .max_flat_workgroup_size: 512
    .name:           _Z14fwd_megakernel4Args
    .private_segment_fixed_size: 0
    .sgpr_count:     108
    .sgpr_spill_count: 80
    .symbol:         _Z14fwd_megakernel4Args.kd
    .uniform_work_group_size: 1
    .uses_dynamic_stack: false
    .vgpr_count:     256
    .vgpr_spill_count: 0
    .wavefront_size: 64
